# loop-edge: K-loop tail SALU issued in last MFMA run; attention -mrun broadcast via v_mov_b64; static s_setprio 1 for waves 4-7 in attention+SGU
# speedup vs baseline: 1.0036x; 1.0002x over previous
; #define PG8_STAGE(bufoff, gbase, voff) do { _Pragma("unroll") for (int _i = 0; _i < 2; ++_i) \
;         __builtin_amdgcn_global_load_lds((const unsigned*)((const char*)(gbase) + (voff)[_i]), (PG8_LAS unsigned*)(lds + (bufoff) + ldsw + _i * 8192), 16, 0, 0); } while (0)
; #define PG8_LDA(dst, b, h) do { _Pragma("unroll") for (int m = 0; m < 4; ++m) _Pragma("unroll") for (int k = 0; k < 2; ++k) dst[m][k] = *(const PG8_LAS bf16x8*)(lds + PG8_SA(b, h) + aoff + m * 2048 + k * 1024); } while (0)
; #define PG8_LDB(dst, b, h) do { _Pragma("unroll") for (int n = 0; n < 2; ++n) _Pragma("unroll") for (int k = 0; k < 2; ++k) dst[n][k] = *(const PG8_LAS bf16x8*)(lds + PG8_SB(b, h) + boff + n * 2048 + k * 1024); } while (0)
; #define PG8_MMA(ai, bj, At, Bt) do { __builtin_amdgcn_s_setprio(1); _Pragma("unroll") for (int m = 0; m < 4; ++m) _Pragma("unroll") for (int n = 0; n < 2; ++n) _Pragma("unroll") for (int k = 0; k < 2; ++k) \
;         acc[ai][bj][m][n] = __builtin_amdgcn_mfma_f32_16x16x32_bf16(Bt[n][k], At[m][k], acc[ai][bj][m][n], 0, 0, 0); __builtin_amdgcn_s_setprio(0); } while (0)
; #define PG8_WAIT_V(n) asm volatile("s_waitcnt vmcnt(" #n ")" ::: "memory")
; #define PG8_BAR __builtin_amdgcn_s_barrier()
; template <class Epi, class Sched, bool ALIGN_EPI = false, bool SP2 = false>
; __device__ __forceinline__ void gemm_phase(PG8_LAS unsigned char* lds, const Gemm g, const Sched& S, const Epi& E) {
;     ...
;         for (int t = 0; t < nt; t += 2) {
;             const bool last = (t == nt - 2);
;             const char* a1 = cA + (size_t)(t + 1) * kstep;
;             const char* a2 = last ? nA : cA + (size_t)(t + 2) * kstep; const char* b2 = last ? nB : cB + (size_t)(t + 2) * kstep;
;             const char* a3 = a2 + kstep; const char* b3 = b2 + kstep;
;             if (last && has_next) S.a_ready(nxt);
;             if constexpr (SP2) {
;             PG8_LDB(B0, 0, 0); PG8_LDB(B1, 0, 1); PG8_SCHED; PG8_LDA(At, 0, 0); PG8_STAGE(PG8_SA(1, 1), a1 + hstep, voffA);
;             PG8_WAIT_V(8); PG8_WAIT_L(0); PG8_BAR; PG8_MMA(0, 0, At, B0); PG8_MMA(0, 1, At, B1); PG8_BAR; PG8_SCHED;
;             PG8_LDA(At, 0, 1); PG8_STAGE(PG8_SB(0, 0), b2, voffB); PG8_STAGE(PG8_SB(0, 1), b2 + hstep, voffB); PG8_STAGE(PG8_SA(0, 0), a2, voffA);
;             PG8_WAIT_V(8); PG8_WAIT_L(0); PG8_BAR; PG8_MMA(1, 0, At, B0); PG8_MMA(1, 1, At, B1); PG8_BAR; PG8_SCHED;
.LBB0_168:
	s_add_i32 s18, s6, 2
	s_add_u32 s19, s0, 0x80
	s_addc_u32 s7, s1, 0
	s_add_i32 s28, 0, 0x10000
	s_cmp_eq_u32 s79, s6
	s_cselect_b32 s7, s67, s7
	s_cselect_b32 s6, s66, s19
	s_cselect_b32 s25, s27, s9
	s_cselect_b32 s24, s26, s8
	s_add_i32 s19, 0, 0x14000
	v_add_u32_e32 v154, s28, v197
	v_add_u32_e32 v170, s19, v197
	ds_read_b128 v[142:145], v154
	ds_read_b128 v[146:149], v154 offset:1024
	ds_read_b128 v[150:153], v154 offset:2048
	ds_read_b128 v[154:157], v154 offset:3072
	ds_read_b128 v[158:161], v170
	ds_read_b128 v[162:165], v170 offset:1024
	ds_read_b128 v[166:169], v170 offset:2048
	ds_read_b128 v[170:173], v170 offset:3072
	v_lshl_add_u64 v[174:175], s[0:1], 0, v[136:137]
	s_add_i32 m0, s42, 0xc000
	ds_read_b128 v[186:189], v198
	ds_read_b128 v[190:193], v198 offset:1024
	ds_read_b128 v[200:203], v198 offset:2048
	ds_read_b128 v[204:207], v198 offset:3072
	ds_read_b128 v[208:211], v198 offset:4096
	ds_read_b128 v[212:215], v198 offset:5120
	ds_read_b128 v[216:219], v198 offset:6144
	ds_read_b128 v[220:223], v198 offset:7168
	global_load_lds_dwordx4 v[174:175], off
	v_lshl_add_u64 v[174:175], s[0:1], 0, v[138:139]
	s_add_i32 m0, s42, 0xe000
	s_nop 0
	global_load_lds_dwordx4 v[174:175], off
	s_waitcnt vmcnt(8)
	s_waitcnt lgkmcnt(0)
	s_barrier
	s_setprio 1
	s_waitcnt lgkmcnt(0)
	v_mfma_f32_16x16x32_bf16 v[120:123], v[142:145], v[186:189], v[120:123]
	v_mfma_f32_16x16x32_bf16 v[124:127], v[150:153], v[186:189], v[124:127]
	v_mfma_f32_16x16x32_bf16 v[112:115], v[142:145], v[200:203], v[112:115]
	v_mfma_f32_16x16x32_bf16 v[116:119], v[150:153], v[200:203], v[116:119]
	v_mfma_f32_16x16x32_bf16 v[104:107], v[142:145], v[208:211], v[104:107]
	v_mfma_f32_16x16x32_bf16 v[108:111], v[150:153], v[208:211], v[108:111]
	v_mfma_f32_16x16x32_bf16 v[96:99], v[142:145], v[216:219], v[96:99]
	v_mfma_f32_16x16x32_bf16 v[100:103], v[150:153], v[216:219], v[100:103]
	v_mfma_f32_16x16x32_bf16 v[120:123], v[146:149], v[190:193], v[120:123]
	v_mfma_f32_16x16x32_bf16 v[124:127], v[154:157], v[190:193], v[124:127]
	v_mfma_f32_16x16x32_bf16 v[112:115], v[146:149], v[204:207], v[112:115]
	v_mfma_f32_16x16x32_bf16 v[116:119], v[154:157], v[204:207], v[116:119]
	v_mfma_f32_16x16x32_bf16 v[104:107], v[146:149], v[212:215], v[104:107]
	v_mfma_f32_16x16x32_bf16 v[108:111], v[154:157], v[212:215], v[108:111]
	v_mfma_f32_16x16x32_bf16 v[96:99], v[146:149], v[220:223], v[96:99]
	v_mfma_f32_16x16x32_bf16 v[100:103], v[154:157], v[220:223], v[100:103]
	s_setprio 0
	s_setprio 1
	v_mfma_f32_16x16x32_bf16 v[60:63], v[158:161], v[186:189], v[60:63]
	v_mfma_f32_16x16x32_bf16 v[56:59], v[166:169], v[186:189], v[56:59]
	v_mfma_f32_16x16x32_bf16 v[52:55], v[158:161], v[200:203], v[52:55]
	v_mfma_f32_16x16x32_bf16 v[48:51], v[166:169], v[200:203], v[48:51]
	v_mfma_f32_16x16x32_bf16 v[44:47], v[158:161], v[208:211], v[44:47]
	v_mfma_f32_16x16x32_bf16 v[40:43], v[166:169], v[208:211], v[40:43]
	v_mfma_f32_16x16x32_bf16 v[36:39], v[158:161], v[216:219], v[36:39]
	v_mfma_f32_16x16x32_bf16 v[32:35], v[166:169], v[216:219], v[32:35]
	v_mfma_f32_16x16x32_bf16 v[60:63], v[162:165], v[190:193], v[60:63]
	v_mfma_f32_16x16x32_bf16 v[56:59], v[170:173], v[190:193], v[56:59]
	v_mfma_f32_16x16x32_bf16 v[52:55], v[162:165], v[204:207], v[52:55]
	v_mfma_f32_16x16x32_bf16 v[48:51], v[170:173], v[204:207], v[48:51]
	v_mfma_f32_16x16x32_bf16 v[44:47], v[162:165], v[212:215], v[44:47]
	v_mfma_f32_16x16x32_bf16 v[40:43], v[170:173], v[212:215], v[40:43]
	v_mfma_f32_16x16x32_bf16 v[36:39], v[162:165], v[220:223], v[36:39]
	v_mfma_f32_16x16x32_bf16 v[32:35], v[170:173], v[220:223], v[32:35]
	s_setprio 0
	s_barrier
	s_add_i32 s28, s28, s31
	v_lshl_add_u64 v[174:175], s[24:25], 0, v[130:131]
	s_mov_b32 m0, s28
	ds_read_b128 v[186:189], v198 offset:16384
	ds_read_b128 v[190:193], v198 offset:17408
	ds_read_b128 v[200:203], v198 offset:18432
	ds_read_b128 v[204:207], v198 offset:19456
	ds_read_b128 v[208:211], v198 offset:20480
	ds_read_b128 v[212:215], v198 offset:21504
	ds_read_b128 v[216:219], v198 offset:22528
	ds_read_b128 v[220:223], v198 offset:23552
	global_load_lds_dwordx4 v[174:175], off
	s_add_i32 m0, s28, 0x2000
	v_lshl_add_u64 v[182:183], s[24:25], 0, v[134:135]
	s_add_u32 s24, s24, s14
	s_addc_u32 s25, s25, s15
	s_add_i32 s19, s19, s31
	global_load_lds_dwordx4 v[182:183], off
	v_lshl_add_u64 v[184:185], s[24:25], 0, v[130:131]
	s_mov_b32 m0, s19
	v_lshl_add_u64 v[194:195], s[24:25], 0, v[134:135]
	global_load_lds_dwordx4 v[184:185], off
	s_add_i32 m0, s19, 0x2000
	v_lshl_add_u64 v[224:225], s[6:7], 0, v[128:129]
	global_load_lds_dwordx4 v[194:195], off
	s_mov_b32 m0, s42
	v_lshl_add_u64 v[226:227], s[6:7], 0, v[132:133]
	global_load_lds_dwordx4 v[224:225], off
	s_mov_b32 m0, s43
	s_nop 0
	global_load_lds_dwordx4 v[226:227], off
	s_waitcnt vmcnt(8)
	s_waitcnt lgkmcnt(0)
	s_barrier
; #define PG8_STAGE(bufoff, gbase, voff) do { _Pragma("unroll") for (int _i = 0; _i < 2; ++_i) \
;         __builtin_amdgcn_global_load_lds((const unsigned*)((const char*)(gbase) + (voff)[_i]), (PG8_LAS unsigned*)(lds + (bufoff) + ldsw + _i * 8192), 16, 0, 0); } while (0)
; #define PG8_LDA(dst, b, h) do { _Pragma("unroll") for (int m = 0; m < 4; ++m) _Pragma("unroll") for (int k = 0; k < 2; ++k) dst[m][k] = *(const PG8_LAS bf16x8*)(lds + PG8_SA(b, h) + aoff + m * 2048 + k * 1024); } while (0)
; #define PG8_LDB(dst, b, h) do { _Pragma("unroll") for (int n = 0; n < 2; ++n) _Pragma("unroll") for (int k = 0; k < 2; ++k) dst[n][k] = *(const PG8_LAS bf16x8*)(lds + PG8_SB(b, h) + boff + n * 2048 + k * 1024); } while (0)
; #define PG8_MMA(ai, bj, At, Bt) do { __builtin_amdgcn_s_setprio(1); _Pragma("unroll") for (int m = 0; m < 4; ++m) _Pragma("unroll") for (int n = 0; n < 2; ++n) _Pragma("unroll") for (int k = 0; k < 2; ++k) \
;         acc[ai][bj][m][n] = __builtin_amdgcn_mfma_f32_16x16x32_bf16(Bt[n][k], At[m][k], acc[ai][bj][m][n], 0, 0, 0); __builtin_amdgcn_s_setprio(0); } while (0)
; #define PG8_WAIT_V(n) asm volatile("s_waitcnt vmcnt(" #n ")" ::: "memory")
; #define PG8_WAIT_L(n) asm volatile("s_waitcnt lgkmcnt(" #n ")" ::: "memory")
; #define PG8_BAR __builtin_amdgcn_s_barrier()
; #define PG8_SCHED __builtin_amdgcn_sched_barrier(0)
; template <class Epi, class Sched, bool ALIGN_EPI = false, bool SP2 = false>
; __device__ __forceinline__ void gemm_phase(PG8_LAS unsigned char* lds, const Gemm g, const Sched& S, const Epi& E) {
;     ...
;             PG8_WAIT_V(8); PG8_WAIT_L(0); PG8_BAR; PG8_MMA(1, 0, At, B0); PG8_MMA(1, 1, At, B1); PG8_BAR; PG8_SCHED;
;             PG8_LDB(B0, 1, 0); PG8_LDB(B1, 1, 1); PG8_SCHED; PG8_LDA(At, 1, 0); PG8_STAGE(PG8_SA(0, 1), a2 + hstep, voffA);
;             PG8_WAIT_V(8); PG8_WAIT_L(0); PG8_BAR; PG8_MMA(0, 0, At, B0); PG8_MMA(0, 1, At, B1); PG8_BAR; PG8_SCHED;
;             PG8_LDA(At, 1, 1); PG8_STAGE(PG8_SB(1, 0), b3, voffB); PG8_STAGE(PG8_SB(1, 1), b3 + hstep, voffB); PG8_STAGE(PG8_SA(1, 0), a3, voffA);
;             PG8_WAIT_V(8); PG8_WAIT_L(0); PG8_BAR; PG8_MMA(1, 0, At, B0); PG8_MMA(1, 1, At, B1); PG8_BAR; PG8_SCHED;
	s_setprio 1
	s_waitcnt lgkmcnt(0)
	v_mfma_f32_16x16x32_bf16 v[88:91], v[142:145], v[186:189], v[88:91]
	v_mfma_f32_16x16x32_bf16 v[92:95], v[150:153], v[186:189], v[92:95]
	v_mfma_f32_16x16x32_bf16 v[80:83], v[142:145], v[200:203], v[80:83]
	v_mfma_f32_16x16x32_bf16 v[84:87], v[150:153], v[200:203], v[84:87]
	v_mfma_f32_16x16x32_bf16 v[72:75], v[142:145], v[208:211], v[72:75]
	v_mfma_f32_16x16x32_bf16 v[76:79], v[150:153], v[208:211], v[76:79]
	v_mfma_f32_16x16x32_bf16 v[64:67], v[142:145], v[216:219], v[64:67]
	v_mfma_f32_16x16x32_bf16 v[68:71], v[150:153], v[216:219], v[68:71]
	v_mfma_f32_16x16x32_bf16 v[88:91], v[146:149], v[190:193], v[88:91]
	v_mfma_f32_16x16x32_bf16 v[92:95], v[154:157], v[190:193], v[92:95]
	v_mfma_f32_16x16x32_bf16 v[80:83], v[146:149], v[204:207], v[80:83]
	v_mfma_f32_16x16x32_bf16 v[84:87], v[154:157], v[204:207], v[84:87]
	v_mfma_f32_16x16x32_bf16 v[72:75], v[146:149], v[212:215], v[72:75]
	v_mfma_f32_16x16x32_bf16 v[76:79], v[154:157], v[212:215], v[76:79]
	v_mfma_f32_16x16x32_bf16 v[64:67], v[146:149], v[220:223], v[64:67]
	v_mfma_f32_16x16x32_bf16 v[68:71], v[154:157], v[220:223], v[68:71]
	s_setprio 0
	s_setprio 1
	v_mfma_f32_16x16x32_bf16 v[28:31], v[158:161], v[186:189], v[28:31]
	v_mfma_f32_16x16x32_bf16 v[24:27], v[166:169], v[186:189], v[24:27]
	v_mfma_f32_16x16x32_bf16 v[20:23], v[158:161], v[200:203], v[20:23]
	v_mfma_f32_16x16x32_bf16 v[16:19], v[166:169], v[200:203], v[16:19]
	v_mfma_f32_16x16x32_bf16 v[12:15], v[158:161], v[208:211], v[12:15]
	v_mfma_f32_16x16x32_bf16 v[8:11], v[166:169], v[208:211], v[8:11]
	v_mfma_f32_16x16x32_bf16 v[4:7], v[158:161], v[216:219], v[4:7]
	v_mfma_f32_16x16x32_bf16 v[0:3], v[166:169], v[216:219], v[0:3]
	v_mfma_f32_16x16x32_bf16 v[28:31], v[162:165], v[190:193], v[28:31]
	v_mfma_f32_16x16x32_bf16 v[24:27], v[170:173], v[190:193], v[24:27]
	v_mfma_f32_16x16x32_bf16 v[20:23], v[162:165], v[204:207], v[20:23]
	v_mfma_f32_16x16x32_bf16 v[16:19], v[170:173], v[204:207], v[16:19]
	v_mfma_f32_16x16x32_bf16 v[12:15], v[162:165], v[212:215], v[12:15]
	v_mfma_f32_16x16x32_bf16 v[8:11], v[170:173], v[212:215], v[8:11]
	v_mfma_f32_16x16x32_bf16 v[4:7], v[162:165], v[220:223], v[4:7]
	v_mfma_f32_16x16x32_bf16 v[0:3], v[170:173], v[220:223], v[0:3]
	s_setprio 0
	s_barrier
	s_add_i32 s19, 0, 0x18000
	s_add_i32 s24, 0, 0x1c000
	v_add_u32_e32 v154, s19, v197
	v_add_u32_e32 v170, s24, v197
	ds_read_b128 v[142:145], v154
	ds_read_b128 v[146:149], v154 offset:1024
	ds_read_b128 v[150:153], v154 offset:2048
	ds_read_b128 v[154:157], v154 offset:3072
	ds_read_b128 v[158:161], v170
	ds_read_b128 v[162:165], v170 offset:1024
	ds_read_b128 v[166:169], v170 offset:2048
	ds_read_b128 v[170:173], v170 offset:3072
	s_add_u32 s6, s6, s14
	s_addc_u32 s7, s7, s15
	s_mov_b32 m0, s72
	v_lshl_add_u64 v[236:237], s[6:7], 0, v[128:129]
	ds_read_b128 v[186:189], v198 offset:32768
	ds_read_b128 v[190:193], v198 offset:33792
	ds_read_b128 v[200:203], v198 offset:34816
	ds_read_b128 v[204:207], v198 offset:35840
	ds_read_b128 v[208:211], v198 offset:36864
	ds_read_b128 v[212:215], v198 offset:37888
	ds_read_b128 v[216:219], v198 offset:38912
	ds_read_b128 v[220:223], v198 offset:39936
	global_load_lds_dwordx4 v[236:237], off
	v_lshl_add_u64 v[236:237], s[6:7], 0, v[132:133]
	s_mov_b32 m0, s73
	s_nop 0
	global_load_lds_dwordx4 v[236:237], off
	s_waitcnt vmcnt(8)
	s_waitcnt lgkmcnt(0)
	s_barrier
	s_setprio 1
	s_waitcnt lgkmcnt(0)
	v_mfma_f32_16x16x32_bf16 v[120:123], v[142:145], v[186:189], v[120:123]
	v_mfma_f32_16x16x32_bf16 v[124:127], v[150:153], v[186:189], v[124:127]
	v_mfma_f32_16x16x32_bf16 v[112:115], v[142:145], v[200:203], v[112:115]
	v_mfma_f32_16x16x32_bf16 v[116:119], v[150:153], v[200:203], v[116:119]
	v_mfma_f32_16x16x32_bf16 v[104:107], v[142:145], v[208:211], v[104:107]
	v_mfma_f32_16x16x32_bf16 v[108:111], v[150:153], v[208:211], v[108:111]
	v_mfma_f32_16x16x32_bf16 v[96:99], v[142:145], v[216:219], v[96:99]
	v_mfma_f32_16x16x32_bf16 v[100:103], v[150:153], v[216:219], v[100:103]
	v_mfma_f32_16x16x32_bf16 v[120:123], v[146:149], v[190:193], v[120:123]
	v_mfma_f32_16x16x32_bf16 v[124:127], v[154:157], v[190:193], v[124:127]
	v_mfma_f32_16x16x32_bf16 v[112:115], v[146:149], v[204:207], v[112:115]
	v_mfma_f32_16x16x32_bf16 v[116:119], v[154:157], v[204:207], v[116:119]
	v_mfma_f32_16x16x32_bf16 v[104:107], v[146:149], v[212:215], v[104:107]
	v_mfma_f32_16x16x32_bf16 v[108:111], v[154:157], v[212:215], v[108:111]
	v_mfma_f32_16x16x32_bf16 v[96:99], v[146:149], v[220:223], v[96:99]
	v_mfma_f32_16x16x32_bf16 v[100:103], v[154:157], v[220:223], v[100:103]
	s_setprio 0
	s_setprio 1
	v_mfma_f32_16x16x32_bf16 v[60:63], v[158:161], v[186:189], v[60:63]
	v_mfma_f32_16x16x32_bf16 v[56:59], v[166:169], v[186:189], v[56:59]
	v_mfma_f32_16x16x32_bf16 v[52:55], v[158:161], v[200:203], v[52:55]
	v_mfma_f32_16x16x32_bf16 v[48:51], v[166:169], v[200:203], v[48:51]
	v_mfma_f32_16x16x32_bf16 v[44:47], v[158:161], v[208:211], v[44:47]
	v_mfma_f32_16x16x32_bf16 v[40:43], v[166:169], v[208:211], v[40:43]
	v_mfma_f32_16x16x32_bf16 v[36:39], v[158:161], v[216:219], v[36:39]
	v_mfma_f32_16x16x32_bf16 v[32:35], v[166:169], v[216:219], v[32:35]
	v_mfma_f32_16x16x32_bf16 v[60:63], v[162:165], v[190:193], v[60:63]
	v_mfma_f32_16x16x32_bf16 v[56:59], v[170:173], v[190:193], v[56:59]
	v_mfma_f32_16x16x32_bf16 v[52:55], v[162:165], v[204:207], v[52:55]
	v_mfma_f32_16x16x32_bf16 v[48:51], v[170:173], v[204:207], v[48:51]
	v_mfma_f32_16x16x32_bf16 v[44:47], v[162:165], v[212:215], v[44:47]
	v_mfma_f32_16x16x32_bf16 v[40:43], v[170:173], v[212:215], v[40:43]
	v_mfma_f32_16x16x32_bf16 v[36:39], v[162:165], v[220:223], v[36:39]
	v_mfma_f32_16x16x32_bf16 v[32:35], v[170:173], v[220:223], v[32:35]
	s_setprio 0
	s_barrier
; #define PG8_STAGE(bufoff, gbase, voff) do { _Pragma("unroll") for (int _i = 0; _i < 2; ++_i) \
;         __builtin_amdgcn_global_load_lds((const unsigned*)((const char*)(gbase) + (voff)[_i]), (PG8_LAS unsigned*)(lds + (bufoff) + ldsw + _i * 8192), 16, 0, 0); } while (0)
; #define PG8_LDA(dst, b, h) do { _Pragma("unroll") for (int m = 0; m < 4; ++m) _Pragma("unroll") for (int k = 0; k < 2; ++k) dst[m][k] = *(const PG8_LAS bf16x8*)(lds + PG8_SA(b, h) + aoff + m * 2048 + k * 1024); } while (0)
; #define PG8_MMA(ai, bj, At, Bt) do { __builtin_amdgcn_s_setprio(1); _Pragma("unroll") for (int m = 0; m < 4; ++m) _Pragma("unroll") for (int n = 0; n < 2; ++n) _Pragma("unroll") for (int k = 0; k < 2; ++k) \
;         acc[ai][bj][m][n] = __builtin_amdgcn_mfma_f32_16x16x32_bf16(Bt[n][k], At[m][k], acc[ai][bj][m][n], 0, 0, 0); __builtin_amdgcn_s_setprio(0); } while (0)
; #define PG8_WAIT_V(n) asm volatile("s_waitcnt vmcnt(" #n ")" ::: "memory")
; #define PG8_WAIT_L(n) asm volatile("s_waitcnt lgkmcnt(" #n ")" ::: "memory")
; #define PG8_BAR __builtin_amdgcn_s_barrier()
; #define PG8_SCHED __builtin_amdgcn_sched_barrier(0)
; template <class Epi, class Sched, bool ALIGN_EPI = false, bool SP2 = false>
; __device__ __forceinline__ void gemm_phase(PG8_LAS unsigned char* lds, const Gemm g, const Sched& S, const Epi& E) {
;     ...
;         for (int t = 0; t < nt; t += 2) {
;             const bool last = (t == nt - 2);
;             const char* a1 = cA + (size_t)(t + 1) * kstep;
;             const char* a2 = last ? nA : cA + (size_t)(t + 2) * kstep; const char* b2 = last ? nB : cB + (size_t)(t + 2) * kstep;
;     ...
;             PG8_LDA(At, 1, 1); PG8_STAGE(PG8_SB(1, 0), b3, voffB); PG8_STAGE(PG8_SB(1, 1), b3 + hstep, voffB); PG8_STAGE(PG8_SA(1, 0), a3, voffA);
;             PG8_WAIT_V(8); PG8_WAIT_L(0); PG8_BAR; PG8_MMA(1, 0, At, B0); PG8_MMA(1, 1, At, B1); PG8_BAR; PG8_SCHED;
	s_add_i32 s6, s19, s31
	v_lshl_add_u64 v[174:175], v[174:175], 0, s[44:45]
	s_mov_b32 m0, s6
	ds_read_b128 v[186:189], v198 offset:49152
	ds_read_b128 v[190:193], v198 offset:50176
	ds_read_b128 v[200:203], v198 offset:51200
	ds_read_b128 v[204:207], v198 offset:52224
	ds_read_b128 v[208:211], v198 offset:53248
	ds_read_b128 v[212:215], v198 offset:54272
	ds_read_b128 v[216:219], v198 offset:55296
	ds_read_b128 v[220:223], v198 offset:56320
	global_load_lds_dwordx4 v[174:175], off
	v_lshl_add_u64 v[174:175], v[182:183], 0, s[44:45]
	s_add_i32 m0, s6, 0x2000
	s_add_i32 s6, s24, s31
	global_load_lds_dwordx4 v[174:175], off
	v_lshl_add_u64 v[174:175], v[184:185], 0, s[44:45]
	s_mov_b32 m0, s6
	s_nop 0
	global_load_lds_dwordx4 v[174:175], off
	v_lshl_add_u64 v[174:175], v[194:195], 0, s[44:45]
	s_add_i32 m0, s6, 0x2000
	s_nop 0
	global_load_lds_dwordx4 v[174:175], off
	v_lshl_add_u64 v[174:175], v[224:225], 0, s[44:45]
	s_mov_b32 m0, s74
	s_nop 0
	global_load_lds_dwordx4 v[174:175], off
	v_lshl_add_u64 v[174:175], v[226:227], 0, s[44:45]
	s_mov_b32 m0, s75
	s_nop 0
	global_load_lds_dwordx4 v[174:175], off
	s_waitcnt vmcnt(8)
	s_waitcnt lgkmcnt(0)
	s_barrier
	s_setprio 1
	s_waitcnt lgkmcnt(0)
	v_mfma_f32_16x16x32_bf16 v[88:91], v[142:145], v[186:189], v[88:91]
	v_mfma_f32_16x16x32_bf16 v[92:95], v[150:153], v[186:189], v[92:95]
	v_mfma_f32_16x16x32_bf16 v[80:83], v[142:145], v[200:203], v[80:83]
	v_mfma_f32_16x16x32_bf16 v[84:87], v[150:153], v[200:203], v[84:87]
	v_mfma_f32_16x16x32_bf16 v[72:75], v[142:145], v[208:211], v[72:75]
	v_mfma_f32_16x16x32_bf16 v[76:79], v[150:153], v[208:211], v[76:79]
	v_mfma_f32_16x16x32_bf16 v[64:67], v[142:145], v[216:219], v[64:67]
	v_mfma_f32_16x16x32_bf16 v[68:71], v[150:153], v[216:219], v[68:71]
	v_mfma_f32_16x16x32_bf16 v[88:91], v[146:149], v[190:193], v[88:91]
	v_mfma_f32_16x16x32_bf16 v[92:95], v[154:157], v[190:193], v[92:95]
	v_mfma_f32_16x16x32_bf16 v[80:83], v[146:149], v[204:207], v[80:83]
	v_mfma_f32_16x16x32_bf16 v[84:87], v[154:157], v[204:207], v[84:87]
	v_mfma_f32_16x16x32_bf16 v[72:75], v[146:149], v[212:215], v[72:75]
	v_mfma_f32_16x16x32_bf16 v[76:79], v[154:157], v[212:215], v[76:79]
	v_mfma_f32_16x16x32_bf16 v[64:67], v[146:149], v[220:223], v[64:67]
	v_mfma_f32_16x16x32_bf16 v[68:71], v[154:157], v[220:223], v[68:71]
	s_setprio 0
	s_setprio 1
	v_mfma_f32_16x16x32_bf16 v[28:31], v[158:161], v[186:189], v[28:31]
	v_mfma_f32_16x16x32_bf16 v[24:27], v[166:169], v[186:189], v[24:27]
	v_mfma_f32_16x16x32_bf16 v[20:23], v[158:161], v[200:203], v[20:23]
	v_mfma_f32_16x16x32_bf16 v[16:19], v[166:169], v[200:203], v[16:19]
	v_mfma_f32_16x16x32_bf16 v[12:15], v[158:161], v[208:211], v[12:15]
	v_mfma_f32_16x16x32_bf16 v[8:11], v[166:169], v[208:211], v[8:11]
	v_mfma_f32_16x16x32_bf16 v[4:7], v[158:161], v[216:219], v[4:7]
	v_mfma_f32_16x16x32_bf16 v[0:3], v[166:169], v[216:219], v[0:3]
	v_mfma_f32_16x16x32_bf16 v[28:31], v[162:165], v[190:193], v[28:31]
	v_mfma_f32_16x16x32_bf16 v[24:27], v[170:173], v[190:193], v[24:27]
	s_add_u32 s0, s0, 0x100
	v_mfma_f32_16x16x32_bf16 v[20:23], v[162:165], v[204:207], v[20:23]
	s_addc_u32 s1, s1, 0
	v_mfma_f32_16x16x32_bf16 v[16:19], v[170:173], v[204:207], v[16:19]
	s_add_u32 s8, s8, 0x100
	v_mfma_f32_16x16x32_bf16 v[12:15], v[162:165], v[212:215], v[12:15]
	s_addc_u32 s9, s9, 0
	v_mfma_f32_16x16x32_bf16 v[8:11], v[170:173], v[212:215], v[8:11]
	s_cmp_ge_i32 s18, s76
	v_mfma_f32_16x16x32_bf16 v[4:7], v[162:165], v[220:223], v[4:7]
	s_mov_b32 s6, s18
	v_mfma_f32_16x16x32_bf16 v[0:3], v[170:173], v[220:223], v[0:3]
	s_setprio 0
	s_barrier
	s_cbranch_scc0 .LBB0_168

; #define LAS __attribute__((address_space(3)))
; __device__ __forceinline__ void attn_units(LAS unsigned char* lds, const bf16* QB, const bf16* KB, const bf16* VT, const bf16* VTc, bf16* MIX, const float* sink, const float* gmix,
;                                            int nunits, int G, int vb, int tid) {
;     asm volatile("" : "+v"(tid));
;     const int wave = __builtin_amdgcn_readfirstlane(tid >> 6), lane = tid & 63, h = wave >> 2, c = lane & 31, hh = lane >> 5;
;     LAS float* red = (LAS float*)(lds + AT_RED);
;     for (int L = vb; L < nunits; L += G) {
;         const int uidx = (L < 1024 && (G & 7) == 0) ? (L & 7) * 128 + (L >> 3) : L;
;         const bool isctx = uidx >= 1024; int b, nb, q0;
;         if (!isctx) { b = uidx >> 7; nb = (uidx >> 1) & 63; q0 = nb * 128 + (uidx & 1) * 64; } else { const int v = uidx - 1024; b = v >> 2; nb = 0; q0 = (v & 3) * 64; }
;         const size_t qrow0 = (size_t)(isctx ? ML + b * CTXL : b * SEQ) + q0;
;         bf16x8 qf[2][4];
; #pragma unroll
;         for (int qs = 0; qs < 2; ++qs)
; #pragma unroll
;             for (int ks = 0; ks < 4; ++ks) qf[qs][ks] = *(const bf16x8*)(QB + (qrow0 + qs * 32 + c) * 512 + wave * 64 + ks * 16 + hh * 8);
.LBB0_291:
	s_or_b64 exec, exec, s[0:1]
	s_lshl_b32 s46, s40, 10
	s_lshl_b64 s[0:1], s[46:47], 2
	s_add_u32 s4, s88, s0
	v_writelane_b32 v255, s0, 1
	s_addc_u32 s5, s89, s1
	s_mov_b32 s41, s47
	v_writelane_b32 v255, s1, 2
	v_readlane_b32 s0, v254, 20
	v_readlane_b32 s1, v254, 21
	v_writelane_b32 v255, s4, 3
	s_and_b64 s[0:1], s[0:1], exec
	s_movk_i32 s0, 0x420
	v_writelane_b32 v255, s5, 4
	s_cselect_b32 s24, 0x400, s0
	s_waitcnt lgkmcnt(0)
	v_mov_b32_e32 v0, v179
	v_writelane_b32 v255, s40, 5
	s_barrier
	s_cmp_ge_i32 s2, s24
	v_readfirstlane_b32 s0, v0
	v_writelane_b32 v255, s41, 6
	s_cbranch_scc1 .LBB0_339
	s_lshl_b32 s46, s40, 3
	s_lshl_b64 s[4:5], s[46:47], 2
	s_add_u32 s6, s80, s4
	s_addc_u32 s7, s81, s5
	s_and_b32 s8, s0, 0xffffffc0
	v_and_b32_e32 v186, 31, v0
	v_readlane_b32 s1, v254, 18
	s_ashr_i32 s9, s8, 31
	s_ashr_i32 s12, s0, 8
	v_lshl_add_u32 v235, v186, 2, s1
	s_ashr_i32 s4, s0, 6
	s_lshl_b64 s[10:11], s[8:9], 1
	v_readlane_b32 s0, v253, 63
	v_bfe_u32 v4, v0, 5, 1
	v_readlane_b32 s1, v254, 0
	s_add_u32 s0, s0, s10
	s_addc_u32 s1, s1, s11
	v_lshlrev_b32_e32 v176, 4, v4
	s_ashr_i32 s5, s4, 31
	v_lshl_add_u64 v[188:189], s[0:1], 0, v[176:177]
	s_lshl_b64 s[0:1], s[4:5], 2
	s_add_u32 s0, s6, s0
	s_mulk_i32 s4, 0x2400
	s_addc_u32 s1, s7, s1
	v_lshlrev_b32_e32 v2, 3, v0
	s_lshl_b32 s13, s12, 7
	v_lshl_add_u32 v236, s8, 2, v235
	s_add_i32 s14, s4, 0
	s_lshl_b64 s[4:5], s[8:9], 2
	v_readlane_b32 s8, v255, 3
	v_and_b32_e32 v180, 0x78, v2
	v_readlane_b32 s6, v253, 1
	v_readlane_b32 s9, v255, 4
	s_add_u32 s4, s8, s4
	v_and_b32_e32 v1, 63, v0
	v_lshlrev_b32_e32 v2, 1, v180
	v_mov_b32_e32 v3, v177
	v_readlane_b32 s7, v253, 2
	s_addc_u32 s5, s9, s5
	v_lshl_add_u64 v[192:193], s[4:5], 0, v[176:177]
	v_lshl_add_u64 v[190:191], s[6:7], 0, v[2:3]
	v_cmp_gt_u32_e64 s[6:7], 32, v1
	v_lshlrev_b32_e32 v1, 4, v0
	v_readlane_b32 s4, v253, 53
	v_and_b32_e32 v2, 0x70, v1
	v_readlane_b32 s5, v253, 54
	s_add_u32 s4, s4, s10
	v_add_u32_e32 v1, 0x200, v0
	v_bfe_u32 v194, v0, 3, 3
	s_addc_u32 s5, s5, s11
	v_ashrrev_i32_e32 v198, 4, v0
	v_ashrrev_i32_e32 v202, 4, v1
	v_add_u32_e32 v1, 0x400, v0
	v_add_u32_e32 v0, 0x600, v0
	s_movk_i32 s8, 0x88
	v_lshl_add_u64 v[196:197], s[4:5], 0, v[2:3]
	v_ashrrev_i32_e32 v206, 4, v1
	v_ashrrev_i32_e32 v210, 4, v0
	v_mad_u64_u32 v[0:1], s[4:5], v198, s8, v[180:181]
	v_ashrrev_i32_e32 v199, 31, v198
	v_ashrrev_i32_e32 v203, 31, v202
	v_lshlrev_b32_e32 v1, 2, v198
	v_lshlrev_b64 v[200:201], 8, v[198:199]
	v_lshlrev_b64 v[204:205], 8, v[202:203]
	v_lshlrev_b32_e32 v199, 1, v0
	v_add_lshl_u32 v203, v0, v1, 1
	v_mad_u64_u32 v[0:1], s[4:5], v202, s8, v[180:181]
	v_ashrrev_i32_e32 v207, 31, v206
	v_ashrrev_i32_e32 v211, 31, v210
	v_lshlrev_b32_e32 v1, 2, v202
	v_lshlrev_b64 v[208:209], 8, v[206:207]
	v_lshlrev_b64 v[212:213], 8, v[210:211]
	v_lshlrev_b32_e32 v207, 1, v0
	v_add_lshl_u32 v211, v0, v1, 1
	v_mad_u64_u32 v[0:1], s[4:5], v206, s8, v[180:181]
	v_lshlrev_b32_e32 v1, 2, v206
	v_lshlrev_b32_e32 v237, 1, v0
	v_add_lshl_u32 v238, v0, v1, 1
	v_mad_u64_u32 v[0:1], s[4:5], v210, s8, v[180:181]
	s_mul_i32 s4, s12, 0x4600
	s_nop 0
	v_mov_b32_e32 v3, s4
	s_movk_i32 s4, 0x118
	v_lshlrev_b32_e32 v5, 3, v4
	v_mad_u32_u24 v3, v186, s4, v3
	v_readlane_b32 s4, v254, 19
	v_lshlrev_b32_e32 v1, 2, v210
	v_or_b32_e32 v214, 8, v194
	v_add3_u32 v241, v3, v5, s4
	v_mov_b32_e32 v3, s13
	s_movk_i32 s4, 0x110
	v_lshlrev_b32_e32 v4, 2, v4
	v_add_u32_e32 v6, s14, v5
	v_add_u32_e32 v7, s14, v2
	v_mul_u32_u24_e32 v2, 0x90, v194
	v_lshlrev_b32_e32 v239, 1, v0
	v_add_lshl_u32 v240, v0, v1, 1
	v_mul_u32_u24_e32 v0, 0x90, v186
	v_mul_u32_u24_e32 v1, 0x90, v214
	v_mad_u32_u24 v3, v186, s4, v3
	v_mov_b32_e32 v187, v177
	v_mov_b32_e32 v195, v177
	v_mov_b32_e32 v215, v177
	v_or_b32_e32 v216, 16, v194
	v_mov_b32_e32 v217, v177
	v_or_b32_e32 v218, 24, v194
	v_mov_b32_e32 v219, v177
	v_or_b32_e32 v220, 32, v194
	v_mov_b32_e32 v221, v177
	v_or_b32_e32 v222, 40, v194
	v_mov_b32_e32 v223, v177
	v_or_b32_e32 v224, 48, v194
	v_mov_b32_e32 v225, v177
	v_or_b32_e32 v226, 56, v194
	v_mov_b32_e32 v227, v177
	v_add3_u32 v242, v3, v176, 0
	v_sub_u32_e32 v243, v4, v186
	v_add_u32_e32 v244, v6, v0
	v_add_u32_e32 v245, v7, v2
	v_add_u32_e32 v246, v7, v1
	v_readfirstlane_b32 s100, v179
	s_lshr_b32 s100, s100, 6
	s_cmp_ge_u32 s100, 4
	s_cbranch_scc0 .Lattn_noprio
	s_setprio 1
.Lattn_noprio:
	s_mov_b32 s25, s2
	s_branch .LBB0_294

; #define LAS __attribute__((address_space(3)))
; #define MFMA32(a, b, c) __builtin_amdgcn_mfma_f32_32x32x16_bf16(a, b, c, 0, 0, 0)
; __device__ __forceinline__ void attn_units(LAS unsigned char* lds, const bf16* QB, const bf16* KB, const bf16* VT, const bf16* VTc, bf16* MIX, const float* sink, const float* gmix,
;                                            int nunits, int G, int vb, int tid) {
;     ...
;                 bf16x8 kf[4];
; #pragma unroll
;                 for (int ks = 0; ks < 4; ++ks) kf[ks] = *(const LAS bf16x8*)(Ks + (kt * 32 + c) * AT_ST + h * 64 + ks * 16 + hh * 8);
;                 bf16x8 vf[2][2];
; #pragma unroll
;                 for (int dt = 0; dt < 2; ++dt)
; #pragma unroll
;                     for (int s2 = 0; s2 < 2; ++s2) { const LAS bf16* p = Vs + (h * 64 + dt * 32 + c) * AT_STV + kt * 32 + s2 * 16 + hh * 4;
;                         const v2u lo = *(const LAS v2u*)p, hi = *(const LAS v2u*)(p + 8); v4u t; t.x = lo.x; t.y = lo.y; t.z = hi.x; t.w = hi.y; vf[dt][s2] = __builtin_bit_cast(bf16x8, t); }
;                 f32x16 st[2];
; #pragma unroll
;                 for (int qs = 0; qs < 2; ++qs) {
;                     const float nm = -mrun[qs];
; #pragma unroll
;                     for (int r = 0; r < 16; ++r) st[qs][r] = nm;
; #pragma unroll
;                     for (int ks = 0; ks < 4; ++ks) st[qs] = MFMA32(kf[ks], qf[qs][ks], st[qs]);
;                 }
;                 bf16x8 pb[2][2];
; #pragma unroll
;                 for (int qs = 0; qs < 2; ++qs) {
;                     const int kmin = kb0 + kt * 32, qmin = q0 + qs * 32;
;                     if (s < 3 && (kmin - (qmin + 31) > 128 || qmin - (kmin + 31) > 128)) continue;
;                     float t[16];
; #pragma unroll
;                     for (int r = 0; r < 16; ++r) t[r] = st[qs][r];
;                     if (s < 3 && (kmin - (qmin + 31) < -128 || kmin + 31 - qmin > 128)) {
;                         const int base = kmin + 4 * hh - (qmin + c) + 128;
; #pragma unroll
;                         for (int r = 0; r < 16; ++r) { if ((unsigned)(base + (r & 3) + 8 * (r >> 2)) > 256u) t[r] = -1e30f; } }
.LBB0_315:
	s_waitcnt lgkmcnt(0)
	ds_read_b128 v[160:163], v229
	ds_read_b128 v[164:167], v229 offset:32
	v_xor_b32_e32 v80, 0x80000000, v248
	v_xor_b32_e32 v64, 0x80000000, v250
	v_mov_b32_e32 v81, v80
	v_mov_b64_e32 v[82:83], v[80:81]
	v_mov_b64_e32 v[84:85], v[80:81]
	v_mov_b64_e32 v[86:87], v[80:81]
	v_mov_b64_e32 v[88:89], v[80:81]
	v_mov_b64_e32 v[90:91], v[80:81]
	v_mov_b64_e32 v[92:93], v[80:81]
	v_mov_b64_e32 v[94:95], v[80:81]
	v_mov_b32_e32 v65, v64
	v_mov_b64_e32 v[66:67], v[64:65]
	v_mov_b64_e32 v[68:69], v[64:65]
	v_mov_b64_e32 v[70:71], v[64:65]
	v_mov_b64_e32 v[72:73], v[64:65]
	v_mov_b64_e32 v[74:75], v[64:65]
	v_mov_b64_e32 v[76:77], v[64:65]
	v_mov_b64_e32 v[78:79], v[64:65]
	s_waitcnt lgkmcnt(1)
	v_mfma_f32_32x32x16_bf16 v[80:95], v[160:163], v[96:99], v[80:95]
	ds_read_b128 v[168:171], v229 offset:64
	ds_read_b128 v[182:185], v229 offset:96
	v_cndmask_b32_e64 v233, 0, 1, s[40:41]
	s_mov_b64 s[8:9], -1
	v_cmp_ne_u32_e64 s[4:5], 1, v233
	s_andn2_b64 vcc, exec, s[40:41]
	v_mfma_f32_32x32x16_bf16 v[64:79], v[160:163], v[112:115], v[64:79]
	v_add_u32_e32 v160, 0x2000, v251
	s_waitcnt lgkmcnt(2)
	v_mfma_f32_32x32x16_bf16 v[80:95], v[164:167], v[100:103], v[80:95]
	v_mfma_f32_32x32x16_bf16 v[64:79], v[164:167], v[116:119], v[64:79]
	ds_read2_b64 v[172:175], v251 offset1:2
	ds_read2_b64 v[164:167], v251 offset0:4 offset1:6
	s_waitcnt lgkmcnt(3)
	v_mfma_f32_32x32x16_bf16 v[80:95], v[168:171], v[104:107], v[80:95]
	v_mfma_f32_32x32x16_bf16 v[64:79], v[168:171], v[120:123], v[64:79]
	ds_read2_b64 v[168:171], v160 offset0:96 offset1:98
	ds_read2_b64 v[160:163], v160 offset0:100 offset1:102
	s_waitcnt lgkmcnt(4)
	v_mfma_f32_32x32x16_bf16 v[80:95], v[182:185], v[108:111], v[80:95]
	v_mfma_f32_32x32x16_bf16 v[64:79], v[182:185], v[124:127], v[64:79]
	s_cbranch_vccnz .LBB0_320
	s_sub_i32 s69, s68, 30
	s_sub_i32 s8, s46, 32
	s_max_i32 s8, s69, s8
	s_cmpk_lt_i32 s8, 0x81
	s_mov_b64 s[8:9], 0
	s_cbranch_scc0 .LBB0_320
	s_cmpk_lt_i32 s69, 0xff80
	s_cselect_b64 s[8:9], -1, 0
	s_add_i32 s28, s68, 32
	s_cmpk_gt_i32 s28, 0x80
	s_cselect_b64 s[70:71], -1, 0
	s_or_b64 s[8:9], s[8:9], s[70:71]
	s_andn2_b64 vcc, exec, s[8:9]
	s_cbranch_vccnz .LBB0_319
	v_add_u32_e32 v182, s68, v243
	v_add_u32_e32 v183, 0x81, v182
	v_cmp_gt_u32_e32 vcc, s33, v183
	v_add_u32_e32 v183, 0xffffff81, v182
	s_nop 0
	v_cndmask_b32_e32 v80, v234, v80, vcc
	v_cmp_lt_u32_e32 vcc, s55, v183
	v_add_u32_e32 v183, 0xffffff82, v182
	s_nop 0
	v_cndmask_b32_e32 v81, v234, v81, vcc
	v_cmp_lt_u32_e32 vcc, s55, v183
	v_add_u32_e32 v183, 0xffffff83, v182
	s_nop 0
	v_cndmask_b32_e32 v82, v234, v82, vcc
	v_cmp_lt_u32_e32 vcc, s55, v183
	v_add_u32_e32 v183, 0xffffff88, v182
	s_nop 0
	v_cndmask_b32_e32 v83, v234, v83, vcc
	v_cmp_lt_u32_e32 vcc, s55, v183
	v_add_u32_e32 v183, 0xffffff89, v182
	s_nop 0
	v_cndmask_b32_e32 v84, v234, v84, vcc
	v_cmp_lt_u32_e32 vcc, s55, v183
	v_add_u32_e32 v183, 0xffffff8a, v182
	s_nop 0
	v_cndmask_b32_e32 v85, v234, v85, vcc
	v_cmp_lt_u32_e32 vcc, s55, v183
	v_add_u32_e32 v183, 0xffffff8b, v182
	s_nop 0
	v_cndmask_b32_e32 v86, v234, v86, vcc
	v_cmp_lt_u32_e32 vcc, s55, v183
	v_add_u32_e32 v183, 0xffffff90, v182
	s_nop 0
	v_cndmask_b32_e32 v87, v234, v87, vcc
	v_cmp_lt_u32_e32 vcc, s55, v183
	v_add_u32_e32 v183, 0xffffff91, v182
	s_nop 0
	v_cndmask_b32_e32 v88, v234, v88, vcc
	v_cmp_lt_u32_e32 vcc, s55, v183
	v_add_u32_e32 v183, 0xffffff92, v182
	s_nop 0
	v_cndmask_b32_e32 v89, v234, v89, vcc
	v_cmp_lt_u32_e32 vcc, s55, v183
	v_add_u32_e32 v183, 0xffffff93, v182
	s_nop 0
	v_cndmask_b32_e32 v90, v234, v90, vcc
	v_cmp_lt_u32_e32 vcc, s55, v183
	v_add_u32_e32 v183, 0xffffff98, v182
	s_nop 0
	v_cndmask_b32_e32 v91, v234, v91, vcc
	v_cmp_lt_u32_e32 vcc, s55, v183
	v_add_u32_e32 v183, 0xffffff99, v182
	s_nop 0
	v_cndmask_b32_e32 v92, v234, v92, vcc
	v_cmp_lt_u32_e32 vcc, s55, v183
	v_add_u32_e32 v183, 0xffffff9a, v182
	v_add_u32_e32 v182, 0xffffff9b, v182
	v_cndmask_b32_e32 v93, v234, v93, vcc
	v_cmp_lt_u32_e32 vcc, s55, v183
	s_nop 1
	v_cndmask_b32_e32 v94, v234, v94, vcc
	v_cmp_lt_u32_e32 vcc, s55, v182
	s_nop 1
	v_cndmask_b32_e32 v95, v234, v95, vcc

; __global__ void __launch_bounds__(512, 2) fwd_megakernel(Args a) {
;     ...
;         __syncthreads();
;     ...
;         {
;             int fM = 512, fN = 32768, fK = 512; asm volatile("" : "+s"(fM), "+s"(fN), "+s"(fK));
;             pg8::Gemm g{(const bf16*)(ws + WS_DFT512), (const bf16*)(ws + WS_GT), fM, fN, fK}; pg8::StaticOrder S; S.init(fM, fN, G, bid);
;             pg8::EpiPlain<0, false> E{(bf16*)(ws + WS_TP), fN, 1.f};
;             pg8::gemm_phase<pg8::EpiPlain<0, false>, pg8::StaticOrder, true, true>(lds, g, S, E);
.LBB0_353:
	s_setprio 0
	s_movk_i32 s0, 0x200
	s_movk_i32 s4, 0x200
	s_mov_b32 s8, 0x8000
	s_barrier
	s_ashr_i32 s1, s0, 31
	s_lshr_b32 s1, s1, 24
	s_add_i32 s0, s0, s1
	s_ashr_i32 s9, s0, 8
	s_ashr_i32 s0, s8, 31
	s_lshr_b32 s0, s0, 24
	s_add_i32 s0, s8, s0
	s_ashr_i32 s14, s0, 8
	s_mul_i32 s0, s14, s9
	v_mov_b32_e32 v18, v179
	s_cmp_ge_i32 s2, s0
	v_readfirstlane_b32 s34, v18
	s_cbranch_scc1 .LBB0_383
	s_ashr_i32 s1, s0, 31
	s_lshr_b32 s5, s1, 29
	s_add_i32 s5, s0, s5
	s_ashr_i32 s18, s5, 3
	s_and_b32 s5, s5, -8
	s_sub_i32 s19, s0, s5
	s_add_i32 s22, s18, 1
	v_readlane_b32 s5, v253, 48
	s_cmp_ge_i32 s5, s19
	s_mov_b64 s[6:7], -1
	s_mul_i32 s23, s22, s19
	s_cbranch_scc0 .LBB0_356
	v_readlane_b32 s5, v253, 48
	s_sub_i32 s5, s5, s19
	s_mul_i32 s5, s5, s18
	s_add_i32 s15, s5, s23
	s_mov_b64 s[6:7], 0

; #define PG8_STAGE(bufoff, gbase, voff) do { _Pragma("unroll") for (int _i = 0; _i < 2; ++_i) \
;         __builtin_amdgcn_global_load_lds((const unsigned*)((const char*)(gbase) + (voff)[_i]), (PG8_LAS unsigned*)(lds + (bufoff) + ldsw + _i * 8192), 16, 0, 0); } while (0)
; #define PG8_LDA(dst, b, h) do { _Pragma("unroll") for (int m = 0; m < 4; ++m) _Pragma("unroll") for (int k = 0; k < 2; ++k) dst[m][k] = *(const PG8_LAS bf16x8*)(lds + PG8_SA(b, h) + aoff + m * 2048 + k * 1024); } while (0)
; #define PG8_LDB(dst, b, h) do { _Pragma("unroll") for (int n = 0; n < 2; ++n) _Pragma("unroll") for (int k = 0; k < 2; ++k) dst[n][k] = *(const PG8_LAS bf16x8*)(lds + PG8_SB(b, h) + boff + n * 2048 + k * 1024); } while (0)
; #define PG8_MMA(ai, bj, At, Bt) do { __builtin_amdgcn_s_setprio(1); _Pragma("unroll") for (int m = 0; m < 4; ++m) _Pragma("unroll") for (int n = 0; n < 2; ++n) _Pragma("unroll") for (int k = 0; k < 2; ++k) \
;         acc[ai][bj][m][n] = __builtin_amdgcn_mfma_f32_16x16x32_bf16(Bt[n][k], At[m][k], acc[ai][bj][m][n], 0, 0, 0); __builtin_amdgcn_s_setprio(0); } while (0)
; #define PG8_WAIT_V(n) asm volatile("s_waitcnt vmcnt(" #n ")" ::: "memory")
; #define PG8_BAR __builtin_amdgcn_s_barrier()
; template <class Epi, class Sched, bool ALIGN_EPI = false, bool SP2 = false>
; __device__ __forceinline__ void gemm_phase(PG8_LAS unsigned char* lds, const Gemm g, const Sched& S, const Epi& E) {
;     ...
;         for (int t = 0; t < nt; t += 2) {
;             const bool last = (t == nt - 2);
;             const char* a1 = cA + (size_t)(t + 1) * kstep;
;             const char* a2 = last ? nA : cA + (size_t)(t + 2) * kstep; const char* b2 = last ? nB : cB + (size_t)(t + 2) * kstep;
;             const char* a3 = a2 + kstep; const char* b3 = b2 + kstep;
;             if (last && has_next) S.a_ready(nxt);
;             if constexpr (SP2) {
;             PG8_LDB(B0, 0, 0); PG8_LDB(B1, 0, 1); PG8_SCHED; PG8_LDA(At, 0, 0); PG8_STAGE(PG8_SA(1, 1), a1 + hstep, voffA);
;             PG8_WAIT_V(8); PG8_WAIT_L(0); PG8_BAR; PG8_MMA(0, 0, At, B0); PG8_MMA(0, 1, At, B1); PG8_BAR; PG8_SCHED;
;             PG8_LDA(At, 0, 1); PG8_STAGE(PG8_SB(0, 0), b2, voffB); PG8_STAGE(PG8_SB(0, 1), b2 + hstep, voffB); PG8_STAGE(PG8_SA(0, 0), a2, voffA);
;             PG8_WAIT_V(8); PG8_WAIT_L(0); PG8_BAR; PG8_MMA(1, 0, At, B0); PG8_MMA(1, 1, At, B1); PG8_BAR; PG8_SCHED;
.LBB0_375:
	s_add_i32 s80, s64, 2
	s_add_u32 s28, s40, 0x80
	s_addc_u32 s38, s41, 0
	s_add_i32 s48, 0, 0x10000
	s_cmp_eq_u32 s74, s64
	s_cselect_b32 s65, s5, s38
	s_cselect_b32 s64, s4, s28
	s_cselect_b32 s39, s37, s79
	s_cselect_b32 s38, s36, s78
	s_add_i32 s28, 0, 0x14000
	v_add_u32_e32 v154, s48, v140
	v_add_u32_e32 v170, s28, v140
	ds_read_b128 v[142:145], v154
	ds_read_b128 v[146:149], v154 offset:1024
	ds_read_b128 v[150:153], v154 offset:2048
	ds_read_b128 v[154:157], v154 offset:3072
	ds_read_b128 v[158:161], v170
	ds_read_b128 v[162:165], v170 offset:1024
	ds_read_b128 v[166:169], v170 offset:2048
	ds_read_b128 v[170:173], v170 offset:3072
	v_lshl_add_u64 v[174:175], s[40:41], 0, v[134:135]
	s_add_i32 m0, s43, 0xc000
	ds_read_b128 v[182:185], v141
	ds_read_b128 v[186:189], v141 offset:1024
	ds_read_b128 v[190:193], v141 offset:2048
	ds_read_b128 v[194:197], v141 offset:3072
	ds_read_b128 v[198:201], v141 offset:4096
	ds_read_b128 v[202:205], v141 offset:5120
	ds_read_b128 v[206:209], v141 offset:6144
	ds_read_b128 v[210:213], v141 offset:7168
	global_load_lds_dwordx4 v[174:175], off
	v_lshl_add_u64 v[174:175], s[40:41], 0, v[136:137]
	s_add_i32 m0, s43, 0xe000
	s_nop 0
	global_load_lds_dwordx4 v[174:175], off
	s_waitcnt vmcnt(8)
	s_waitcnt lgkmcnt(0)
	s_barrier
	s_setprio 1
	s_waitcnt lgkmcnt(0)
	v_mfma_f32_16x16x32_bf16 v[120:123], v[142:145], v[182:185], v[120:123]
	v_mfma_f32_16x16x32_bf16 v[124:127], v[150:153], v[182:185], v[124:127]
	v_mfma_f32_16x16x32_bf16 v[108:111], v[142:145], v[190:193], v[108:111]
	v_mfma_f32_16x16x32_bf16 v[104:107], v[150:153], v[190:193], v[104:107]
	v_mfma_f32_16x16x32_bf16 v[92:95], v[142:145], v[198:201], v[92:95]
	v_mfma_f32_16x16x32_bf16 v[88:91], v[150:153], v[198:201], v[88:91]
	v_mfma_f32_16x16x32_bf16 v[76:79], v[142:145], v[206:209], v[76:79]
	v_mfma_f32_16x16x32_bf16 v[72:75], v[150:153], v[206:209], v[72:75]
	v_mfma_f32_16x16x32_bf16 v[120:123], v[146:149], v[186:189], v[120:123]
	v_mfma_f32_16x16x32_bf16 v[124:127], v[154:157], v[186:189], v[124:127]
	v_mfma_f32_16x16x32_bf16 v[108:111], v[146:149], v[194:197], v[108:111]
	v_mfma_f32_16x16x32_bf16 v[104:107], v[154:157], v[194:197], v[104:107]
	v_mfma_f32_16x16x32_bf16 v[92:95], v[146:149], v[202:205], v[92:95]
	v_mfma_f32_16x16x32_bf16 v[88:91], v[154:157], v[202:205], v[88:91]
	v_mfma_f32_16x16x32_bf16 v[76:79], v[146:149], v[210:213], v[76:79]
	v_mfma_f32_16x16x32_bf16 v[72:75], v[154:157], v[210:213], v[72:75]
	s_setprio 0
	s_setprio 1
	v_mfma_f32_16x16x32_bf16 v[116:119], v[158:161], v[182:185], v[116:119]
	v_mfma_f32_16x16x32_bf16 v[112:115], v[166:169], v[182:185], v[112:115]
	v_mfma_f32_16x16x32_bf16 v[100:103], v[158:161], v[190:193], v[100:103]
	v_mfma_f32_16x16x32_bf16 v[96:99], v[166:169], v[190:193], v[96:99]
	v_mfma_f32_16x16x32_bf16 v[84:87], v[158:161], v[198:201], v[84:87]
	v_mfma_f32_16x16x32_bf16 v[80:83], v[166:169], v[198:201], v[80:83]
	v_mfma_f32_16x16x32_bf16 v[68:71], v[158:161], v[206:209], v[68:71]
	v_mfma_f32_16x16x32_bf16 v[64:67], v[166:169], v[206:209], v[64:67]
	v_mfma_f32_16x16x32_bf16 v[116:119], v[162:165], v[186:189], v[116:119]
	v_mfma_f32_16x16x32_bf16 v[112:115], v[170:173], v[186:189], v[112:115]
	v_mfma_f32_16x16x32_bf16 v[100:103], v[162:165], v[194:197], v[100:103]
	v_mfma_f32_16x16x32_bf16 v[96:99], v[170:173], v[194:197], v[96:99]
	v_mfma_f32_16x16x32_bf16 v[84:87], v[162:165], v[202:205], v[84:87]
	v_mfma_f32_16x16x32_bf16 v[80:83], v[170:173], v[202:205], v[80:83]
	v_mfma_f32_16x16x32_bf16 v[68:71], v[162:165], v[210:213], v[68:71]
	v_mfma_f32_16x16x32_bf16 v[64:67], v[170:173], v[210:213], v[64:67]
	s_setprio 0
	s_barrier
	s_add_i32 s48, s48, s24
	v_lshl_add_u64 v[174:175], s[38:39], 0, v[176:177]
	s_mov_b32 m0, s48
	ds_read_b128 v[182:185], v141 offset:16384
	ds_read_b128 v[186:189], v141 offset:17408
	ds_read_b128 v[190:193], v141 offset:18432
	ds_read_b128 v[194:197], v141 offset:19456
	ds_read_b128 v[198:201], v141 offset:20480
	ds_read_b128 v[202:205], v141 offset:21504
	ds_read_b128 v[206:209], v141 offset:22528
	ds_read_b128 v[210:213], v141 offset:23552
	global_load_lds_dwordx4 v[174:175], off
	s_add_i32 m0, s48, 0x2000
	v_lshl_add_u64 v[214:215], s[38:39], 0, v[132:133]
	s_add_u32 s38, s38, s10
	s_addc_u32 s39, s39, s11
	s_add_i32 s28, s28, s24
	global_load_lds_dwordx4 v[214:215], off
	v_lshl_add_u64 v[216:217], s[38:39], 0, v[176:177]
	s_mov_b32 m0, s28
	v_lshl_add_u64 v[218:219], s[38:39], 0, v[132:133]
	global_load_lds_dwordx4 v[216:217], off
	s_add_i32 m0, s28, 0x2000
	v_lshl_add_u64 v[220:221], s[64:65], 0, v[128:129]
	global_load_lds_dwordx4 v[218:219], off
	s_mov_b32 m0, s43
	v_lshl_add_u64 v[222:223], s[64:65], 0, v[130:131]
	global_load_lds_dwordx4 v[220:221], off
	s_mov_b32 m0, s46
	s_nop 0
	global_load_lds_dwordx4 v[222:223], off
	s_waitcnt vmcnt(8)
	s_waitcnt lgkmcnt(0)
	s_barrier
; #define PG8_STAGE(bufoff, gbase, voff) do { _Pragma("unroll") for (int _i = 0; _i < 2; ++_i) \
;         __builtin_amdgcn_global_load_lds((const unsigned*)((const char*)(gbase) + (voff)[_i]), (PG8_LAS unsigned*)(lds + (bufoff) + ldsw + _i * 8192), 16, 0, 0); } while (0)
; #define PG8_LDA(dst, b, h) do { _Pragma("unroll") for (int m = 0; m < 4; ++m) _Pragma("unroll") for (int k = 0; k < 2; ++k) dst[m][k] = *(const PG8_LAS bf16x8*)(lds + PG8_SA(b, h) + aoff + m * 2048 + k * 1024); } while (0)
; #define PG8_LDB(dst, b, h) do { _Pragma("unroll") for (int n = 0; n < 2; ++n) _Pragma("unroll") for (int k = 0; k < 2; ++k) dst[n][k] = *(const PG8_LAS bf16x8*)(lds + PG8_SB(b, h) + boff + n * 2048 + k * 1024); } while (0)
; #define PG8_MMA(ai, bj, At, Bt) do { __builtin_amdgcn_s_setprio(1); _Pragma("unroll") for (int m = 0; m < 4; ++m) _Pragma("unroll") for (int n = 0; n < 2; ++n) _Pragma("unroll") for (int k = 0; k < 2; ++k) \
;         acc[ai][bj][m][n] = __builtin_amdgcn_mfma_f32_16x16x32_bf16(Bt[n][k], At[m][k], acc[ai][bj][m][n], 0, 0, 0); __builtin_amdgcn_s_setprio(0); } while (0)
; #define PG8_WAIT_V(n) asm volatile("s_waitcnt vmcnt(" #n ")" ::: "memory")
; #define PG8_WAIT_L(n) asm volatile("s_waitcnt lgkmcnt(" #n ")" ::: "memory")
; #define PG8_BAR __builtin_amdgcn_s_barrier()
; #define PG8_SCHED __builtin_amdgcn_sched_barrier(0)
; template <class Epi, class Sched, bool ALIGN_EPI = false, bool SP2 = false>
; __device__ __forceinline__ void gemm_phase(PG8_LAS unsigned char* lds, const Gemm g, const Sched& S, const Epi& E) {
;     ...
;             PG8_WAIT_V(8); PG8_WAIT_L(0); PG8_BAR; PG8_MMA(1, 0, At, B0); PG8_MMA(1, 1, At, B1); PG8_BAR; PG8_SCHED;
;             PG8_LDB(B0, 1, 0); PG8_LDB(B1, 1, 1); PG8_SCHED; PG8_LDA(At, 1, 0); PG8_STAGE(PG8_SA(0, 1), a2 + hstep, voffA);
;             PG8_WAIT_V(8); PG8_WAIT_L(0); PG8_BAR; PG8_MMA(0, 0, At, B0); PG8_MMA(0, 1, At, B1); PG8_BAR; PG8_SCHED;
;             PG8_LDA(At, 1, 1); PG8_STAGE(PG8_SB(1, 0), b3, voffB); PG8_STAGE(PG8_SB(1, 1), b3 + hstep, voffB); PG8_STAGE(PG8_SA(1, 0), a3, voffA);
;             PG8_WAIT_V(8); PG8_WAIT_L(0); PG8_BAR; PG8_MMA(1, 0, At, B0); PG8_MMA(1, 1, At, B1); PG8_BAR; PG8_SCHED;
	s_setprio 1
	s_waitcnt lgkmcnt(0)
	v_mfma_f32_16x16x32_bf16 v[60:63], v[142:145], v[182:185], v[60:63]
	v_mfma_f32_16x16x32_bf16 v[56:59], v[150:153], v[182:185], v[56:59]
	v_mfma_f32_16x16x32_bf16 v[44:47], v[142:145], v[190:193], v[44:47]
	v_mfma_f32_16x16x32_bf16 v[40:43], v[150:153], v[190:193], v[40:43]
	v_mfma_f32_16x16x32_bf16 v[28:31], v[142:145], v[198:201], v[28:31]
	v_mfma_f32_16x16x32_bf16 v[24:27], v[150:153], v[198:201], v[24:27]
	v_mfma_f32_16x16x32_bf16 v[12:15], v[142:145], v[206:209], v[12:15]
	v_mfma_f32_16x16x32_bf16 v[8:11], v[150:153], v[206:209], v[8:11]
	v_mfma_f32_16x16x32_bf16 v[60:63], v[146:149], v[186:189], v[60:63]
	v_mfma_f32_16x16x32_bf16 v[56:59], v[154:157], v[186:189], v[56:59]
	v_mfma_f32_16x16x32_bf16 v[44:47], v[146:149], v[194:197], v[44:47]
	v_mfma_f32_16x16x32_bf16 v[40:43], v[154:157], v[194:197], v[40:43]
	v_mfma_f32_16x16x32_bf16 v[28:31], v[146:149], v[202:205], v[28:31]
	v_mfma_f32_16x16x32_bf16 v[24:27], v[154:157], v[202:205], v[24:27]
	v_mfma_f32_16x16x32_bf16 v[12:15], v[146:149], v[210:213], v[12:15]
	v_mfma_f32_16x16x32_bf16 v[8:11], v[154:157], v[210:213], v[8:11]
	s_setprio 0
	s_setprio 1
	v_mfma_f32_16x16x32_bf16 v[52:55], v[158:161], v[182:185], v[52:55]
	v_mfma_f32_16x16x32_bf16 v[48:51], v[166:169], v[182:185], v[48:51]
	v_mfma_f32_16x16x32_bf16 v[36:39], v[158:161], v[190:193], v[36:39]
	v_mfma_f32_16x16x32_bf16 v[32:35], v[166:169], v[190:193], v[32:35]
	v_mfma_f32_16x16x32_bf16 v[20:23], v[158:161], v[198:201], v[20:23]
	v_mfma_f32_16x16x32_bf16 v[16:19], v[166:169], v[198:201], v[16:19]
	v_mfma_f32_16x16x32_bf16 v[4:7], v[158:161], v[206:209], v[4:7]
	v_mfma_f32_16x16x32_bf16 v[0:3], v[166:169], v[206:209], v[0:3]
	v_mfma_f32_16x16x32_bf16 v[52:55], v[162:165], v[186:189], v[52:55]
	v_mfma_f32_16x16x32_bf16 v[48:51], v[170:173], v[186:189], v[48:51]
	v_mfma_f32_16x16x32_bf16 v[36:39], v[162:165], v[194:197], v[36:39]
	v_mfma_f32_16x16x32_bf16 v[32:35], v[170:173], v[194:197], v[32:35]
	v_mfma_f32_16x16x32_bf16 v[20:23], v[162:165], v[202:205], v[20:23]
	v_mfma_f32_16x16x32_bf16 v[16:19], v[170:173], v[202:205], v[16:19]
	v_mfma_f32_16x16x32_bf16 v[4:7], v[162:165], v[210:213], v[4:7]
	v_mfma_f32_16x16x32_bf16 v[0:3], v[170:173], v[210:213], v[0:3]
	s_setprio 0
	s_barrier
	s_add_i32 s28, 0, 0x18000
	s_add_i32 s48, 0, 0x1c000
	v_add_u32_e32 v154, s28, v140
	v_add_u32_e32 v170, s48, v140
	ds_read_b128 v[142:145], v154
	ds_read_b128 v[146:149], v154 offset:1024
	ds_read_b128 v[150:153], v154 offset:2048
	ds_read_b128 v[154:157], v154 offset:3072
	ds_read_b128 v[158:161], v170
	ds_read_b128 v[162:165], v170 offset:1024
	ds_read_b128 v[166:169], v170 offset:2048
	ds_read_b128 v[170:173], v170 offset:3072
	s_add_u32 s38, s64, s10
	s_addc_u32 s39, s65, s11
	s_mov_b32 m0, s63
	v_lshl_add_u64 v[224:225], s[38:39], 0, v[128:129]
	ds_read_b128 v[182:185], v141 offset:32768
	ds_read_b128 v[186:189], v141 offset:33792
	ds_read_b128 v[190:193], v141 offset:34816
	ds_read_b128 v[194:197], v141 offset:35840
	ds_read_b128 v[198:201], v141 offset:36864
	ds_read_b128 v[202:205], v141 offset:37888
	ds_read_b128 v[206:209], v141 offset:38912
	ds_read_b128 v[210:213], v141 offset:39936
	global_load_lds_dwordx4 v[224:225], off
	v_lshl_add_u64 v[224:225], s[38:39], 0, v[130:131]
	s_mov_b32 m0, s66
	s_nop 0
	global_load_lds_dwordx4 v[224:225], off
	s_waitcnt vmcnt(8)
	s_waitcnt lgkmcnt(0)
	s_barrier
	s_setprio 1
	s_waitcnt lgkmcnt(0)
	v_mfma_f32_16x16x32_bf16 v[120:123], v[142:145], v[182:185], v[120:123]
	v_mfma_f32_16x16x32_bf16 v[124:127], v[150:153], v[182:185], v[124:127]
	v_mfma_f32_16x16x32_bf16 v[108:111], v[142:145], v[190:193], v[108:111]
	v_mfma_f32_16x16x32_bf16 v[104:107], v[150:153], v[190:193], v[104:107]
	v_mfma_f32_16x16x32_bf16 v[92:95], v[142:145], v[198:201], v[92:95]
	v_mfma_f32_16x16x32_bf16 v[88:91], v[150:153], v[198:201], v[88:91]
	v_mfma_f32_16x16x32_bf16 v[76:79], v[142:145], v[206:209], v[76:79]
	v_mfma_f32_16x16x32_bf16 v[72:75], v[150:153], v[206:209], v[72:75]
	v_mfma_f32_16x16x32_bf16 v[120:123], v[146:149], v[186:189], v[120:123]
	v_mfma_f32_16x16x32_bf16 v[124:127], v[154:157], v[186:189], v[124:127]
	v_mfma_f32_16x16x32_bf16 v[108:111], v[146:149], v[194:197], v[108:111]
	v_mfma_f32_16x16x32_bf16 v[104:107], v[154:157], v[194:197], v[104:107]
	v_mfma_f32_16x16x32_bf16 v[92:95], v[146:149], v[202:205], v[92:95]
	v_mfma_f32_16x16x32_bf16 v[88:91], v[154:157], v[202:205], v[88:91]
	v_mfma_f32_16x16x32_bf16 v[76:79], v[146:149], v[210:213], v[76:79]
	v_mfma_f32_16x16x32_bf16 v[72:75], v[154:157], v[210:213], v[72:75]
	s_setprio 0
	s_setprio 1
	v_mfma_f32_16x16x32_bf16 v[116:119], v[158:161], v[182:185], v[116:119]
	v_mfma_f32_16x16x32_bf16 v[112:115], v[166:169], v[182:185], v[112:115]
	v_mfma_f32_16x16x32_bf16 v[100:103], v[158:161], v[190:193], v[100:103]
	v_mfma_f32_16x16x32_bf16 v[96:99], v[166:169], v[190:193], v[96:99]
	v_mfma_f32_16x16x32_bf16 v[84:87], v[158:161], v[198:201], v[84:87]
	v_mfma_f32_16x16x32_bf16 v[80:83], v[166:169], v[198:201], v[80:83]
	v_mfma_f32_16x16x32_bf16 v[68:71], v[158:161], v[206:209], v[68:71]
	v_mfma_f32_16x16x32_bf16 v[64:67], v[166:169], v[206:209], v[64:67]
	v_mfma_f32_16x16x32_bf16 v[116:119], v[162:165], v[186:189], v[116:119]
	v_mfma_f32_16x16x32_bf16 v[112:115], v[170:173], v[186:189], v[112:115]
	v_mfma_f32_16x16x32_bf16 v[100:103], v[162:165], v[194:197], v[100:103]
	v_mfma_f32_16x16x32_bf16 v[96:99], v[170:173], v[194:197], v[96:99]
	v_mfma_f32_16x16x32_bf16 v[84:87], v[162:165], v[202:205], v[84:87]
	v_mfma_f32_16x16x32_bf16 v[80:83], v[170:173], v[202:205], v[80:83]
	v_mfma_f32_16x16x32_bf16 v[68:71], v[162:165], v[210:213], v[68:71]
	v_mfma_f32_16x16x32_bf16 v[64:67], v[170:173], v[210:213], v[64:67]
	s_setprio 0
	s_barrier
; #define PG8_STAGE(bufoff, gbase, voff) do { _Pragma("unroll") for (int _i = 0; _i < 2; ++_i) \
;         __builtin_amdgcn_global_load_lds((const unsigned*)((const char*)(gbase) + (voff)[_i]), (PG8_LAS unsigned*)(lds + (bufoff) + ldsw + _i * 8192), 16, 0, 0); } while (0)
; #define PG8_LDA(dst, b, h) do { _Pragma("unroll") for (int m = 0; m < 4; ++m) _Pragma("unroll") for (int k = 0; k < 2; ++k) dst[m][k] = *(const PG8_LAS bf16x8*)(lds + PG8_SA(b, h) + aoff + m * 2048 + k * 1024); } while (0)
; #define PG8_MMA(ai, bj, At, Bt) do { __builtin_amdgcn_s_setprio(1); _Pragma("unroll") for (int m = 0; m < 4; ++m) _Pragma("unroll") for (int n = 0; n < 2; ++n) _Pragma("unroll") for (int k = 0; k < 2; ++k) \
;         acc[ai][bj][m][n] = __builtin_amdgcn_mfma_f32_16x16x32_bf16(Bt[n][k], At[m][k], acc[ai][bj][m][n], 0, 0, 0); __builtin_amdgcn_s_setprio(0); } while (0)
; #define PG8_WAIT_V(n) asm volatile("s_waitcnt vmcnt(" #n ")" ::: "memory")
; #define PG8_WAIT_L(n) asm volatile("s_waitcnt lgkmcnt(" #n ")" ::: "memory")
; #define PG8_BAR __builtin_amdgcn_s_barrier()
; #define PG8_SCHED __builtin_amdgcn_sched_barrier(0)
; template <class Epi, class Sched, bool ALIGN_EPI = false, bool SP2 = false>
; __device__ __forceinline__ void gemm_phase(PG8_LAS unsigned char* lds, const Gemm g, const Sched& S, const Epi& E) {
;     ...
;         for (int t = 0; t < nt; t += 2) {
;             const bool last = (t == nt - 2);
;             const char* a1 = cA + (size_t)(t + 1) * kstep;
;             const char* a2 = last ? nA : cA + (size_t)(t + 2) * kstep; const char* b2 = last ? nB : cB + (size_t)(t + 2) * kstep;
;     ...
;             PG8_LDA(At, 1, 1); PG8_STAGE(PG8_SB(1, 0), b3, voffB); PG8_STAGE(PG8_SB(1, 1), b3 + hstep, voffB); PG8_STAGE(PG8_SA(1, 0), a3, voffA);
;             PG8_WAIT_V(8); PG8_WAIT_L(0); PG8_BAR; PG8_MMA(1, 0, At, B0); PG8_MMA(1, 1, At, B1); PG8_BAR; PG8_SCHED;
	s_add_i32 s28, s28, s24
	v_lshl_add_u64 v[174:175], v[174:175], 0, s[44:45]
	s_mov_b32 m0, s28
	ds_read_b128 v[182:185], v141 offset:49152
	ds_read_b128 v[186:189], v141 offset:50176
	ds_read_b128 v[190:193], v141 offset:51200
	ds_read_b128 v[194:197], v141 offset:52224
	ds_read_b128 v[198:201], v141 offset:53248
	ds_read_b128 v[202:205], v141 offset:54272
	ds_read_b128 v[206:209], v141 offset:55296
	ds_read_b128 v[210:213], v141 offset:56320
	global_load_lds_dwordx4 v[174:175], off
	v_lshl_add_u64 v[174:175], v[214:215], 0, s[44:45]
	s_add_i32 m0, s28, 0x2000
	s_add_i32 s28, s48, s24
	global_load_lds_dwordx4 v[174:175], off
	v_lshl_add_u64 v[174:175], v[216:217], 0, s[44:45]
	s_mov_b32 m0, s28
	s_nop 0
	global_load_lds_dwordx4 v[174:175], off
	v_lshl_add_u64 v[174:175], v[218:219], 0, s[44:45]
	s_add_i32 m0, s28, 0x2000
	s_nop 0
	global_load_lds_dwordx4 v[174:175], off
	v_lshl_add_u64 v[174:175], v[220:221], 0, s[44:45]
	s_mov_b32 m0, s72
	s_nop 0
	global_load_lds_dwordx4 v[174:175], off
	v_lshl_add_u64 v[174:175], v[222:223], 0, s[44:45]
	s_mov_b32 m0, s73
	s_nop 0
	global_load_lds_dwordx4 v[174:175], off
	s_waitcnt vmcnt(8)
	s_waitcnt lgkmcnt(0)
	s_barrier
	s_setprio 1
	s_waitcnt lgkmcnt(0)
	v_mfma_f32_16x16x32_bf16 v[60:63], v[142:145], v[182:185], v[60:63]
	v_mfma_f32_16x16x32_bf16 v[56:59], v[150:153], v[182:185], v[56:59]
	v_mfma_f32_16x16x32_bf16 v[44:47], v[142:145], v[190:193], v[44:47]
	v_mfma_f32_16x16x32_bf16 v[40:43], v[150:153], v[190:193], v[40:43]
	v_mfma_f32_16x16x32_bf16 v[28:31], v[142:145], v[198:201], v[28:31]
	v_mfma_f32_16x16x32_bf16 v[24:27], v[150:153], v[198:201], v[24:27]
	v_mfma_f32_16x16x32_bf16 v[12:15], v[142:145], v[206:209], v[12:15]
	v_mfma_f32_16x16x32_bf16 v[8:11], v[150:153], v[206:209], v[8:11]
	v_mfma_f32_16x16x32_bf16 v[60:63], v[146:149], v[186:189], v[60:63]
	v_mfma_f32_16x16x32_bf16 v[56:59], v[154:157], v[186:189], v[56:59]
	v_mfma_f32_16x16x32_bf16 v[44:47], v[146:149], v[194:197], v[44:47]
	v_mfma_f32_16x16x32_bf16 v[40:43], v[154:157], v[194:197], v[40:43]
	v_mfma_f32_16x16x32_bf16 v[28:31], v[146:149], v[202:205], v[28:31]
	v_mfma_f32_16x16x32_bf16 v[24:27], v[154:157], v[202:205], v[24:27]
	v_mfma_f32_16x16x32_bf16 v[12:15], v[146:149], v[210:213], v[12:15]
	v_mfma_f32_16x16x32_bf16 v[8:11], v[154:157], v[210:213], v[8:11]
	s_setprio 0
	s_setprio 1
	v_mfma_f32_16x16x32_bf16 v[52:55], v[158:161], v[182:185], v[52:55]
	v_mfma_f32_16x16x32_bf16 v[48:51], v[166:169], v[182:185], v[48:51]
	v_mfma_f32_16x16x32_bf16 v[36:39], v[158:161], v[190:193], v[36:39]
	v_mfma_f32_16x16x32_bf16 v[32:35], v[166:169], v[190:193], v[32:35]
	v_mfma_f32_16x16x32_bf16 v[20:23], v[158:161], v[198:201], v[20:23]
	v_mfma_f32_16x16x32_bf16 v[16:19], v[166:169], v[198:201], v[16:19]
	v_mfma_f32_16x16x32_bf16 v[4:7], v[158:161], v[206:209], v[4:7]
	v_mfma_f32_16x16x32_bf16 v[0:3], v[166:169], v[206:209], v[0:3]
	v_mfma_f32_16x16x32_bf16 v[52:55], v[162:165], v[186:189], v[52:55]
	v_mfma_f32_16x16x32_bf16 v[48:51], v[170:173], v[186:189], v[48:51]
	s_add_u32 s40, s40, 0x100
	v_mfma_f32_16x16x32_bf16 v[36:39], v[162:165], v[194:197], v[36:39]
	s_addc_u32 s41, s41, 0
	v_mfma_f32_16x16x32_bf16 v[32:35], v[170:173], v[194:197], v[32:35]
	s_add_u32 s78, s78, 0x100
	v_mfma_f32_16x16x32_bf16 v[20:23], v[162:165], v[202:205], v[20:23]
	s_addc_u32 s79, s79, 0
	v_mfma_f32_16x16x32_bf16 v[16:19], v[170:173], v[202:205], v[16:19]
	s_cmp_ge_i32 s80, s67
	v_mfma_f32_16x16x32_bf16 v[4:7], v[162:165], v[210:213], v[4:7]
	s_mov_b32 s64, s80
	v_mfma_f32_16x16x32_bf16 v[0:3], v[170:173], v[210:213], v[0:3]
	s_setprio 0
	s_barrier
	s_cbranch_scc0 .LBB0_375
	v_readlane_b32 s80, v254, 45
	v_readlane_b32 s78, v254, 43
	v_readlane_b32 s81, v254, 46
	v_readlane_b32 s82, v254, 47
	v_readlane_b32 s83, v254, 48
	v_readlane_b32 s84, v254, 49
	v_readlane_b32 s85, v254, 50
	v_readlane_b32 s86, v254, 51
	v_readlane_b32 s87, v254, 52
	v_readlane_b32 s88, v254, 53
	v_readlane_b32 s89, v254, 54
	v_readlane_b32 s92, v254, 57
	v_readlane_b32 s93, v254, 58
	v_readlane_b32 s94, v254, 59
	v_readlane_b32 s95, v254, 60
	v_readlane_b32 s79, v254, 44
	v_readlane_b32 s90, v254, 55
	v_readlane_b32 s91, v254, 56

; #define PG8_STAGE(bufoff, gbase, voff) do { _Pragma("unroll") for (int _i = 0; _i < 2; ++_i) \
;         __builtin_amdgcn_global_load_lds((const unsigned*)((const char*)(gbase) + (voff)[_i]), (PG8_LAS unsigned*)(lds + (bufoff) + ldsw + _i * 8192), 16, 0, 0); } while (0)
; #define PG8_LDA(dst, b, h) do { _Pragma("unroll") for (int m = 0; m < 4; ++m) _Pragma("unroll") for (int k = 0; k < 2; ++k) dst[m][k] = *(const PG8_LAS bf16x8*)(lds + PG8_SA(b, h) + aoff + m * 2048 + k * 1024); } while (0)
; #define PG8_LDB(dst, b, h) do { _Pragma("unroll") for (int n = 0; n < 2; ++n) _Pragma("unroll") for (int k = 0; k < 2; ++k) dst[n][k] = *(const PG8_LAS bf16x8*)(lds + PG8_SB(b, h) + boff + n * 2048 + k * 1024); } while (0)
; #define PG8_MMA(ai, bj, At, Bt) do { __builtin_amdgcn_s_setprio(1); _Pragma("unroll") for (int m = 0; m < 4; ++m) _Pragma("unroll") for (int n = 0; n < 2; ++n) _Pragma("unroll") for (int k = 0; k < 2; ++k) \
;         acc[ai][bj][m][n] = __builtin_amdgcn_mfma_f32_16x16x32_bf16(Bt[n][k], At[m][k], acc[ai][bj][m][n], 0, 0, 0); __builtin_amdgcn_s_setprio(0); } while (0)
; #define PG8_WAIT_V(n) asm volatile("s_waitcnt vmcnt(" #n ")" ::: "memory")
; #define PG8_BAR __builtin_amdgcn_s_barrier()
; template <class Epi, class Sched, bool ALIGN_EPI = false, bool SP2 = false>
; __device__ __forceinline__ void gemm_phase(PG8_LAS unsigned char* lds, const Gemm g, const Sched& S, const Epi& E) {
;     ...
;         for (int t = 0; t < nt; t += 2) {
;             const bool last = (t == nt - 2);
;             const char* a1 = cA + (size_t)(t + 1) * kstep;
;             const char* a2 = last ? nA : cA + (size_t)(t + 2) * kstep; const char* b2 = last ? nB : cB + (size_t)(t + 2) * kstep;
;             const char* a3 = a2 + kstep; const char* b3 = b2 + kstep;
;             if (last && has_next) S.a_ready(nxt);
;             if constexpr (SP2) {
;             PG8_LDB(B0, 0, 0); PG8_LDB(B1, 0, 1); PG8_SCHED; PG8_LDA(At, 0, 0); PG8_STAGE(PG8_SA(1, 1), a1 + hstep, voffA);
;             PG8_WAIT_V(8); PG8_WAIT_L(0); PG8_BAR; PG8_MMA(0, 0, At, B0); PG8_MMA(0, 1, At, B1); PG8_BAR; PG8_SCHED;
;             PG8_LDA(At, 0, 1); PG8_STAGE(PG8_SB(0, 0), b2, voffB); PG8_STAGE(PG8_SB(0, 1), b2 + hstep, voffB); PG8_STAGE(PG8_SA(0, 0), a2, voffA);
;             PG8_WAIT_V(8); PG8_WAIT_L(0); PG8_BAR; PG8_MMA(1, 0, At, B0); PG8_MMA(1, 1, At, B1); PG8_BAR; PG8_SCHED;
.LBB0_406:
	s_add_i32 s81, s66, 2
	s_add_u32 s28, s64, 0x80
	s_addc_u32 s38, s65, 0
	s_add_i32 s48, 0, 0x10000
	s_cmp_eq_u32 s75, s66
	s_cselect_b32 s67, s7, s38
	s_cselect_b32 s66, s6, s28
	s_cselect_b32 s39, s41, s80
	s_cselect_b32 s38, s40, s79
	s_add_i32 s28, 0, 0x14000
	v_add_u32_e32 v154, s48, v148
	v_add_u32_e32 v170, s28, v148
	ds_read_b128 v[138:141], v154
	ds_read_b128 v[142:145], v154 offset:1024
	ds_read_b128 v[150:153], v154 offset:2048
	ds_read_b128 v[154:157], v154 offset:3072
	ds_read_b128 v[158:161], v170
	ds_read_b128 v[162:165], v170 offset:1024
	ds_read_b128 v[166:169], v170 offset:2048
	ds_read_b128 v[170:173], v170 offset:3072
	v_lshl_add_u64 v[174:175], s[64:65], 0, v[134:135]
	s_add_i32 m0, s43, 0xc000
	ds_read_b128 v[182:185], v149
	ds_read_b128 v[186:189], v149 offset:1024
	ds_read_b128 v[190:193], v149 offset:2048
	ds_read_b128 v[194:197], v149 offset:3072
	ds_read_b128 v[198:201], v149 offset:4096
	ds_read_b128 v[202:205], v149 offset:5120
	ds_read_b128 v[206:209], v149 offset:6144
	ds_read_b128 v[210:213], v149 offset:7168
	global_load_lds_dwordx4 v[174:175], off
	v_lshl_add_u64 v[174:175], s[64:65], 0, v[136:137]
	s_add_i32 m0, s43, 0xe000
	s_nop 0
	global_load_lds_dwordx4 v[174:175], off
	s_waitcnt vmcnt(8)
	s_waitcnt lgkmcnt(0)
	s_barrier
	s_setprio 1
	s_waitcnt lgkmcnt(0)
	v_mfma_f32_16x16x32_bf16 v[124:127], v[138:141], v[182:185], v[124:127]
	v_mfma_f32_16x16x32_bf16 v[120:123], v[150:153], v[182:185], v[120:123]
	v_mfma_f32_16x16x32_bf16 v[116:119], v[138:141], v[190:193], v[116:119]
	v_mfma_f32_16x16x32_bf16 v[112:115], v[150:153], v[190:193], v[112:115]
	v_mfma_f32_16x16x32_bf16 v[104:107], v[138:141], v[198:201], v[104:107]
	v_mfma_f32_16x16x32_bf16 v[96:99], v[150:153], v[198:201], v[96:99]
	v_mfma_f32_16x16x32_bf16 v[88:91], v[138:141], v[206:209], v[88:91]
	v_mfma_f32_16x16x32_bf16 v[80:83], v[150:153], v[206:209], v[80:83]
	v_mfma_f32_16x16x32_bf16 v[124:127], v[142:145], v[186:189], v[124:127]
	v_mfma_f32_16x16x32_bf16 v[120:123], v[154:157], v[186:189], v[120:123]
	v_mfma_f32_16x16x32_bf16 v[116:119], v[142:145], v[194:197], v[116:119]
	v_mfma_f32_16x16x32_bf16 v[112:115], v[154:157], v[194:197], v[112:115]
	v_mfma_f32_16x16x32_bf16 v[104:107], v[142:145], v[202:205], v[104:107]
	v_mfma_f32_16x16x32_bf16 v[96:99], v[154:157], v[202:205], v[96:99]
	v_mfma_f32_16x16x32_bf16 v[88:91], v[142:145], v[210:213], v[88:91]
	v_mfma_f32_16x16x32_bf16 v[80:83], v[154:157], v[210:213], v[80:83]
	s_setprio 0
	s_setprio 1
	v_mfma_f32_16x16x32_bf16 v[108:111], v[158:161], v[182:185], v[108:111]
	v_mfma_f32_16x16x32_bf16 v[100:103], v[166:169], v[182:185], v[100:103]
	v_mfma_f32_16x16x32_bf16 v[92:95], v[158:161], v[190:193], v[92:95]
	v_mfma_f32_16x16x32_bf16 v[84:87], v[166:169], v[190:193], v[84:87]
	v_mfma_f32_16x16x32_bf16 v[76:79], v[158:161], v[198:201], v[76:79]
	v_mfma_f32_16x16x32_bf16 v[72:75], v[166:169], v[198:201], v[72:75]
	v_mfma_f32_16x16x32_bf16 v[68:71], v[158:161], v[206:209], v[68:71]
	v_mfma_f32_16x16x32_bf16 v[64:67], v[166:169], v[206:209], v[64:67]
	v_mfma_f32_16x16x32_bf16 v[108:111], v[162:165], v[186:189], v[108:111]
	v_mfma_f32_16x16x32_bf16 v[100:103], v[170:173], v[186:189], v[100:103]
	v_mfma_f32_16x16x32_bf16 v[92:95], v[162:165], v[194:197], v[92:95]
	v_mfma_f32_16x16x32_bf16 v[84:87], v[170:173], v[194:197], v[84:87]
	v_mfma_f32_16x16x32_bf16 v[76:79], v[162:165], v[202:205], v[76:79]
	v_mfma_f32_16x16x32_bf16 v[72:75], v[170:173], v[202:205], v[72:75]
	v_mfma_f32_16x16x32_bf16 v[68:71], v[162:165], v[210:213], v[68:71]
	v_mfma_f32_16x16x32_bf16 v[64:67], v[170:173], v[210:213], v[64:67]
	s_setprio 0
	s_barrier
	s_add_i32 s48, s48, s24
	v_lshl_add_u64 v[174:175], s[38:39], 0, v[176:177]
	s_mov_b32 m0, s48
	ds_read_b128 v[182:185], v149 offset:16384
	ds_read_b128 v[186:189], v149 offset:17408
	ds_read_b128 v[190:193], v149 offset:18432
	ds_read_b128 v[194:197], v149 offset:19456
	ds_read_b128 v[198:201], v149 offset:20480
	ds_read_b128 v[202:205], v149 offset:21504
	ds_read_b128 v[206:209], v149 offset:22528
	ds_read_b128 v[210:213], v149 offset:23552
	global_load_lds_dwordx4 v[174:175], off
	s_add_i32 m0, s48, 0x2000
	v_lshl_add_u64 v[214:215], s[38:39], 0, v[132:133]
	s_add_u32 s38, s38, s10
	s_addc_u32 s39, s39, s11
	s_add_i32 s28, s28, s24
	global_load_lds_dwordx4 v[214:215], off
	v_lshl_add_u64 v[216:217], s[38:39], 0, v[176:177]
	s_mov_b32 m0, s28
	v_lshl_add_u64 v[218:219], s[38:39], 0, v[132:133]
	global_load_lds_dwordx4 v[216:217], off
	s_add_i32 m0, s28, 0x2000
	v_lshl_add_u64 v[220:221], s[66:67], 0, v[128:129]
	global_load_lds_dwordx4 v[218:219], off
	s_mov_b32 m0, s43
	v_lshl_add_u64 v[222:223], s[66:67], 0, v[130:131]
	global_load_lds_dwordx4 v[220:221], off
	s_mov_b32 m0, s46
	s_nop 0
	global_load_lds_dwordx4 v[222:223], off
	s_waitcnt vmcnt(8)
	s_waitcnt lgkmcnt(0)
	s_barrier
; #define PG8_STAGE(bufoff, gbase, voff) do { _Pragma("unroll") for (int _i = 0; _i < 2; ++_i) \
;         __builtin_amdgcn_global_load_lds((const unsigned*)((const char*)(gbase) + (voff)[_i]), (PG8_LAS unsigned*)(lds + (bufoff) + ldsw + _i * 8192), 16, 0, 0); } while (0)
; #define PG8_LDA(dst, b, h) do { _Pragma("unroll") for (int m = 0; m < 4; ++m) _Pragma("unroll") for (int k = 0; k < 2; ++k) dst[m][k] = *(const PG8_LAS bf16x8*)(lds + PG8_SA(b, h) + aoff + m * 2048 + k * 1024); } while (0)
; #define PG8_LDB(dst, b, h) do { _Pragma("unroll") for (int n = 0; n < 2; ++n) _Pragma("unroll") for (int k = 0; k < 2; ++k) dst[n][k] = *(const PG8_LAS bf16x8*)(lds + PG8_SB(b, h) + boff + n * 2048 + k * 1024); } while (0)
; #define PG8_MMA(ai, bj, At, Bt) do { __builtin_amdgcn_s_setprio(1); _Pragma("unroll") for (int m = 0; m < 4; ++m) _Pragma("unroll") for (int n = 0; n < 2; ++n) _Pragma("unroll") for (int k = 0; k < 2; ++k) \
;         acc[ai][bj][m][n] = __builtin_amdgcn_mfma_f32_16x16x32_bf16(Bt[n][k], At[m][k], acc[ai][bj][m][n], 0, 0, 0); __builtin_amdgcn_s_setprio(0); } while (0)
; #define PG8_WAIT_V(n) asm volatile("s_waitcnt vmcnt(" #n ")" ::: "memory")
; #define PG8_WAIT_L(n) asm volatile("s_waitcnt lgkmcnt(" #n ")" ::: "memory")
; #define PG8_BAR __builtin_amdgcn_s_barrier()
; #define PG8_SCHED __builtin_amdgcn_sched_barrier(0)
; template <class Epi, class Sched, bool ALIGN_EPI = false, bool SP2 = false>
; __device__ __forceinline__ void gemm_phase(PG8_LAS unsigned char* lds, const Gemm g, const Sched& S, const Epi& E) {
;     ...
;             PG8_WAIT_V(8); PG8_WAIT_L(0); PG8_BAR; PG8_MMA(1, 0, At, B0); PG8_MMA(1, 1, At, B1); PG8_BAR; PG8_SCHED;
;             PG8_LDB(B0, 1, 0); PG8_LDB(B1, 1, 1); PG8_SCHED; PG8_LDA(At, 1, 0); PG8_STAGE(PG8_SA(0, 1), a2 + hstep, voffA);
;             PG8_WAIT_V(8); PG8_WAIT_L(0); PG8_BAR; PG8_MMA(0, 0, At, B0); PG8_MMA(0, 1, At, B1); PG8_BAR; PG8_SCHED;
;             PG8_LDA(At, 1, 1); PG8_STAGE(PG8_SB(1, 0), b3, voffB); PG8_STAGE(PG8_SB(1, 1), b3 + hstep, voffB); PG8_STAGE(PG8_SA(1, 0), a3, voffA);
;             PG8_WAIT_V(8); PG8_WAIT_L(0); PG8_BAR; PG8_MMA(1, 0, At, B0); PG8_MMA(1, 1, At, B1); PG8_BAR; PG8_SCHED;
	s_setprio 1
	s_waitcnt lgkmcnt(0)
	v_mfma_f32_16x16x32_bf16 v[60:63], v[138:141], v[182:185], v[60:63]
	v_mfma_f32_16x16x32_bf16 v[56:59], v[150:153], v[182:185], v[56:59]
	v_mfma_f32_16x16x32_bf16 v[52:55], v[138:141], v[190:193], v[52:55]
	v_mfma_f32_16x16x32_bf16 v[48:51], v[150:153], v[190:193], v[48:51]
	v_mfma_f32_16x16x32_bf16 v[40:43], v[138:141], v[198:201], v[40:43]
	v_mfma_f32_16x16x32_bf16 v[32:35], v[150:153], v[198:201], v[32:35]
	v_mfma_f32_16x16x32_bf16 v[24:27], v[138:141], v[206:209], v[24:27]
	v_mfma_f32_16x16x32_bf16 v[16:19], v[150:153], v[206:209], v[16:19]
	v_mfma_f32_16x16x32_bf16 v[60:63], v[142:145], v[186:189], v[60:63]
	v_mfma_f32_16x16x32_bf16 v[56:59], v[154:157], v[186:189], v[56:59]
	v_mfma_f32_16x16x32_bf16 v[52:55], v[142:145], v[194:197], v[52:55]
	v_mfma_f32_16x16x32_bf16 v[48:51], v[154:157], v[194:197], v[48:51]
	v_mfma_f32_16x16x32_bf16 v[40:43], v[142:145], v[202:205], v[40:43]
	v_mfma_f32_16x16x32_bf16 v[32:35], v[154:157], v[202:205], v[32:35]
	v_mfma_f32_16x16x32_bf16 v[24:27], v[142:145], v[210:213], v[24:27]
	v_mfma_f32_16x16x32_bf16 v[16:19], v[154:157], v[210:213], v[16:19]
	s_setprio 0
	s_setprio 1
	v_mfma_f32_16x16x32_bf16 v[44:47], v[158:161], v[182:185], v[44:47]
	v_mfma_f32_16x16x32_bf16 v[36:39], v[166:169], v[182:185], v[36:39]
	v_mfma_f32_16x16x32_bf16 v[28:31], v[158:161], v[190:193], v[28:31]
	v_mfma_f32_16x16x32_bf16 v[20:23], v[166:169], v[190:193], v[20:23]
	v_mfma_f32_16x16x32_bf16 v[12:15], v[158:161], v[198:201], v[12:15]
	v_mfma_f32_16x16x32_bf16 v[8:11], v[166:169], v[198:201], v[8:11]
	v_mfma_f32_16x16x32_bf16 v[4:7], v[158:161], v[206:209], v[4:7]
	v_mfma_f32_16x16x32_bf16 v[0:3], v[166:169], v[206:209], v[0:3]
	v_mfma_f32_16x16x32_bf16 v[44:47], v[162:165], v[186:189], v[44:47]
	v_mfma_f32_16x16x32_bf16 v[36:39], v[170:173], v[186:189], v[36:39]
	v_mfma_f32_16x16x32_bf16 v[28:31], v[162:165], v[194:197], v[28:31]
	v_mfma_f32_16x16x32_bf16 v[20:23], v[170:173], v[194:197], v[20:23]
	v_mfma_f32_16x16x32_bf16 v[12:15], v[162:165], v[202:205], v[12:15]
	v_mfma_f32_16x16x32_bf16 v[8:11], v[170:173], v[202:205], v[8:11]
	v_mfma_f32_16x16x32_bf16 v[4:7], v[162:165], v[210:213], v[4:7]
	v_mfma_f32_16x16x32_bf16 v[0:3], v[170:173], v[210:213], v[0:3]
	s_setprio 0
	s_barrier
	s_add_i32 s28, 0, 0x18000
	s_add_i32 s48, 0, 0x1c000
	v_add_u32_e32 v154, s28, v148
	v_add_u32_e32 v170, s48, v148
	ds_read_b128 v[138:141], v154
	ds_read_b128 v[142:145], v154 offset:1024
	ds_read_b128 v[150:153], v154 offset:2048
	ds_read_b128 v[154:157], v154 offset:3072
	ds_read_b128 v[158:161], v170
	ds_read_b128 v[162:165], v170 offset:1024
	ds_read_b128 v[166:169], v170 offset:2048
	ds_read_b128 v[170:173], v170 offset:3072
	s_add_u32 s38, s66, s10
	s_addc_u32 s39, s67, s11
	s_mov_b32 m0, s63
	v_lshl_add_u64 v[224:225], s[38:39], 0, v[128:129]
	ds_read_b128 v[182:185], v149 offset:32768
	ds_read_b128 v[186:189], v149 offset:33792
	ds_read_b128 v[190:193], v149 offset:34816
	ds_read_b128 v[194:197], v149 offset:35840
	ds_read_b128 v[198:201], v149 offset:36864
	ds_read_b128 v[202:205], v149 offset:37888
	ds_read_b128 v[206:209], v149 offset:38912
	ds_read_b128 v[210:213], v149 offset:39936
	global_load_lds_dwordx4 v[224:225], off
	v_lshl_add_u64 v[224:225], s[38:39], 0, v[130:131]
	s_mov_b32 m0, s68
	s_nop 0
	global_load_lds_dwordx4 v[224:225], off
	s_waitcnt vmcnt(8)
	s_waitcnt lgkmcnt(0)
	s_barrier
	s_setprio 1
	s_waitcnt lgkmcnt(0)
	v_mfma_f32_16x16x32_bf16 v[124:127], v[138:141], v[182:185], v[124:127]
	v_mfma_f32_16x16x32_bf16 v[120:123], v[150:153], v[182:185], v[120:123]
	v_mfma_f32_16x16x32_bf16 v[116:119], v[138:141], v[190:193], v[116:119]
	v_mfma_f32_16x16x32_bf16 v[112:115], v[150:153], v[190:193], v[112:115]
	v_mfma_f32_16x16x32_bf16 v[104:107], v[138:141], v[198:201], v[104:107]
	v_mfma_f32_16x16x32_bf16 v[96:99], v[150:153], v[198:201], v[96:99]
	v_mfma_f32_16x16x32_bf16 v[88:91], v[138:141], v[206:209], v[88:91]
	v_mfma_f32_16x16x32_bf16 v[80:83], v[150:153], v[206:209], v[80:83]
	v_mfma_f32_16x16x32_bf16 v[124:127], v[142:145], v[186:189], v[124:127]
	v_mfma_f32_16x16x32_bf16 v[120:123], v[154:157], v[186:189], v[120:123]
	v_mfma_f32_16x16x32_bf16 v[116:119], v[142:145], v[194:197], v[116:119]
	v_mfma_f32_16x16x32_bf16 v[112:115], v[154:157], v[194:197], v[112:115]
	v_mfma_f32_16x16x32_bf16 v[104:107], v[142:145], v[202:205], v[104:107]
	v_mfma_f32_16x16x32_bf16 v[96:99], v[154:157], v[202:205], v[96:99]
	v_mfma_f32_16x16x32_bf16 v[88:91], v[142:145], v[210:213], v[88:91]
	v_mfma_f32_16x16x32_bf16 v[80:83], v[154:157], v[210:213], v[80:83]
	s_setprio 0
	s_setprio 1
	v_mfma_f32_16x16x32_bf16 v[108:111], v[158:161], v[182:185], v[108:111]
	v_mfma_f32_16x16x32_bf16 v[100:103], v[166:169], v[182:185], v[100:103]
	v_mfma_f32_16x16x32_bf16 v[92:95], v[158:161], v[190:193], v[92:95]
	v_mfma_f32_16x16x32_bf16 v[84:87], v[166:169], v[190:193], v[84:87]
	v_mfma_f32_16x16x32_bf16 v[76:79], v[158:161], v[198:201], v[76:79]
	v_mfma_f32_16x16x32_bf16 v[72:75], v[166:169], v[198:201], v[72:75]
	v_mfma_f32_16x16x32_bf16 v[68:71], v[158:161], v[206:209], v[68:71]
	v_mfma_f32_16x16x32_bf16 v[64:67], v[166:169], v[206:209], v[64:67]
	v_mfma_f32_16x16x32_bf16 v[108:111], v[162:165], v[186:189], v[108:111]
	v_mfma_f32_16x16x32_bf16 v[100:103], v[170:173], v[186:189], v[100:103]
	v_mfma_f32_16x16x32_bf16 v[92:95], v[162:165], v[194:197], v[92:95]
	v_mfma_f32_16x16x32_bf16 v[84:87], v[170:173], v[194:197], v[84:87]
	v_mfma_f32_16x16x32_bf16 v[76:79], v[162:165], v[202:205], v[76:79]
	v_mfma_f32_16x16x32_bf16 v[72:75], v[170:173], v[202:205], v[72:75]
	v_mfma_f32_16x16x32_bf16 v[68:71], v[162:165], v[210:213], v[68:71]
	v_mfma_f32_16x16x32_bf16 v[64:67], v[170:173], v[210:213], v[64:67]
	s_setprio 0
	s_barrier
; #define PG8_STAGE(bufoff, gbase, voff) do { _Pragma("unroll") for (int _i = 0; _i < 2; ++_i) \
;         __builtin_amdgcn_global_load_lds((const unsigned*)((const char*)(gbase) + (voff)[_i]), (PG8_LAS unsigned*)(lds + (bufoff) + ldsw + _i * 8192), 16, 0, 0); } while (0)
; #define PG8_LDA(dst, b, h) do { _Pragma("unroll") for (int m = 0; m < 4; ++m) _Pragma("unroll") for (int k = 0; k < 2; ++k) dst[m][k] = *(const PG8_LAS bf16x8*)(lds + PG8_SA(b, h) + aoff + m * 2048 + k * 1024); } while (0)
; #define PG8_MMA(ai, bj, At, Bt) do { __builtin_amdgcn_s_setprio(1); _Pragma("unroll") for (int m = 0; m < 4; ++m) _Pragma("unroll") for (int n = 0; n < 2; ++n) _Pragma("unroll") for (int k = 0; k < 2; ++k) \
;         acc[ai][bj][m][n] = __builtin_amdgcn_mfma_f32_16x16x32_bf16(Bt[n][k], At[m][k], acc[ai][bj][m][n], 0, 0, 0); __builtin_amdgcn_s_setprio(0); } while (0)
; #define PG8_WAIT_V(n) asm volatile("s_waitcnt vmcnt(" #n ")" ::: "memory")
; #define PG8_WAIT_L(n) asm volatile("s_waitcnt lgkmcnt(" #n ")" ::: "memory")
; #define PG8_BAR __builtin_amdgcn_s_barrier()
; #define PG8_SCHED __builtin_amdgcn_sched_barrier(0)
; template <class Epi, class Sched, bool ALIGN_EPI = false, bool SP2 = false>
; __device__ __forceinline__ void gemm_phase(PG8_LAS unsigned char* lds, const Gemm g, const Sched& S, const Epi& E) {
;     ...
;         for (int t = 0; t < nt; t += 2) {
;             const bool last = (t == nt - 2);
;             const char* a1 = cA + (size_t)(t + 1) * kstep;
;             const char* a2 = last ? nA : cA + (size_t)(t + 2) * kstep; const char* b2 = last ? nB : cB + (size_t)(t + 2) * kstep;
;     ...
;             PG8_LDA(At, 1, 1); PG8_STAGE(PG8_SB(1, 0), b3, voffB); PG8_STAGE(PG8_SB(1, 1), b3 + hstep, voffB); PG8_STAGE(PG8_SA(1, 0), a3, voffA);
;             PG8_WAIT_V(8); PG8_WAIT_L(0); PG8_BAR; PG8_MMA(1, 0, At, B0); PG8_MMA(1, 1, At, B1); PG8_BAR; PG8_SCHED;
	s_add_i32 s28, s28, s24
	v_lshl_add_u64 v[174:175], v[174:175], 0, s[44:45]
	s_mov_b32 m0, s28
	ds_read_b128 v[182:185], v149 offset:49152
	ds_read_b128 v[186:189], v149 offset:50176
	ds_read_b128 v[190:193], v149 offset:51200
	ds_read_b128 v[194:197], v149 offset:52224
	ds_read_b128 v[198:201], v149 offset:53248
	ds_read_b128 v[202:205], v149 offset:54272
	ds_read_b128 v[206:209], v149 offset:55296
	ds_read_b128 v[210:213], v149 offset:56320
	global_load_lds_dwordx4 v[174:175], off
	v_lshl_add_u64 v[174:175], v[214:215], 0, s[44:45]
	s_add_i32 m0, s28, 0x2000
	s_add_i32 s28, s48, s24
	global_load_lds_dwordx4 v[174:175], off
	v_lshl_add_u64 v[174:175], v[216:217], 0, s[44:45]
	s_mov_b32 m0, s28
	s_nop 0
	global_load_lds_dwordx4 v[174:175], off
	v_lshl_add_u64 v[174:175], v[218:219], 0, s[44:45]
	s_add_i32 m0, s28, 0x2000
	s_nop 0
	global_load_lds_dwordx4 v[174:175], off
	v_lshl_add_u64 v[174:175], v[220:221], 0, s[44:45]
	s_mov_b32 m0, s73
	s_nop 0
	global_load_lds_dwordx4 v[174:175], off
	v_lshl_add_u64 v[174:175], v[222:223], 0, s[44:45]
	s_mov_b32 m0, s74
	s_nop 0
	global_load_lds_dwordx4 v[174:175], off
	s_waitcnt vmcnt(8)
	s_waitcnt lgkmcnt(0)
	s_barrier
	s_setprio 1
	s_waitcnt lgkmcnt(0)
	v_mfma_f32_16x16x32_bf16 v[60:63], v[138:141], v[182:185], v[60:63]
	v_mfma_f32_16x16x32_bf16 v[56:59], v[150:153], v[182:185], v[56:59]
	v_mfma_f32_16x16x32_bf16 v[52:55], v[138:141], v[190:193], v[52:55]
	v_mfma_f32_16x16x32_bf16 v[48:51], v[150:153], v[190:193], v[48:51]
	v_mfma_f32_16x16x32_bf16 v[40:43], v[138:141], v[198:201], v[40:43]
	v_mfma_f32_16x16x32_bf16 v[32:35], v[150:153], v[198:201], v[32:35]
	v_mfma_f32_16x16x32_bf16 v[24:27], v[138:141], v[206:209], v[24:27]
	v_mfma_f32_16x16x32_bf16 v[16:19], v[150:153], v[206:209], v[16:19]
	v_mfma_f32_16x16x32_bf16 v[60:63], v[142:145], v[186:189], v[60:63]
	v_mfma_f32_16x16x32_bf16 v[56:59], v[154:157], v[186:189], v[56:59]
	v_mfma_f32_16x16x32_bf16 v[52:55], v[142:145], v[194:197], v[52:55]
	v_mfma_f32_16x16x32_bf16 v[48:51], v[154:157], v[194:197], v[48:51]
	v_mfma_f32_16x16x32_bf16 v[40:43], v[142:145], v[202:205], v[40:43]
	v_mfma_f32_16x16x32_bf16 v[32:35], v[154:157], v[202:205], v[32:35]
	v_mfma_f32_16x16x32_bf16 v[24:27], v[142:145], v[210:213], v[24:27]
	v_mfma_f32_16x16x32_bf16 v[16:19], v[154:157], v[210:213], v[16:19]
	s_setprio 0
	s_setprio 1
	v_mfma_f32_16x16x32_bf16 v[44:47], v[158:161], v[182:185], v[44:47]
	v_mfma_f32_16x16x32_bf16 v[36:39], v[166:169], v[182:185], v[36:39]
	v_mfma_f32_16x16x32_bf16 v[28:31], v[158:161], v[190:193], v[28:31]
	v_mfma_f32_16x16x32_bf16 v[20:23], v[166:169], v[190:193], v[20:23]
	v_mfma_f32_16x16x32_bf16 v[12:15], v[158:161], v[198:201], v[12:15]
	v_mfma_f32_16x16x32_bf16 v[8:11], v[166:169], v[198:201], v[8:11]
	v_mfma_f32_16x16x32_bf16 v[4:7], v[158:161], v[206:209], v[4:7]
	v_mfma_f32_16x16x32_bf16 v[0:3], v[166:169], v[206:209], v[0:3]
	v_mfma_f32_16x16x32_bf16 v[44:47], v[162:165], v[186:189], v[44:47]
	v_mfma_f32_16x16x32_bf16 v[36:39], v[170:173], v[186:189], v[36:39]
	s_add_u32 s64, s64, 0x100
	v_mfma_f32_16x16x32_bf16 v[28:31], v[162:165], v[194:197], v[28:31]
	s_addc_u32 s65, s65, 0
	v_mfma_f32_16x16x32_bf16 v[20:23], v[170:173], v[194:197], v[20:23]
	s_add_u32 s79, s79, 0x100
	v_mfma_f32_16x16x32_bf16 v[12:15], v[162:165], v[202:205], v[12:15]
	s_addc_u32 s80, s80, 0
	v_mfma_f32_16x16x32_bf16 v[8:11], v[170:173], v[202:205], v[8:11]
	s_cmp_ge_i32 s81, s69
	v_mfma_f32_16x16x32_bf16 v[4:7], v[162:165], v[210:213], v[4:7]
	s_mov_b32 s66, s81
	v_mfma_f32_16x16x32_bf16 v[0:3], v[170:173], v[210:213], v[0:3]
	s_setprio 0
	s_barrier
	s_cbranch_scc0 .LBB0_406
; __device__ __forceinline__ unsigned cvt_pk_bf16(float lo, float hi) { unsigned r; asm volatile("v_cvt_pk_bf16_f32 %0, %1, %2" : "=v"(r) : "v"(lo), "v"(hi)); return r; }
;     __device__ __forceinline__ void operator()(const f32x4 (&acc)[2][2][4][2], const Unit& u, int wr, int wc, int fr, int fq) const {
;     ...
;         const int row0 = (REMAP ? u.pn * BM : u.pm * BM) + wr * 64 + fr; const int col0 = (REMAP ? 0 : u.pn * BM) + wc * 32 + 8 * fq;
; #pragma unroll
;         for (int ai = 0; ai < 2; ++ai)
; #pragma unroll
;             for (int m = 0; m < 4; ++m) { bf16_t* rowp = O + (size_t)(row0 + ai * HALF + m * 16) * ldc + col0;
; #pragma unroll
;                 for (int bj = 0; bj < 2; ++bj) { f32x4 v0 = acc[ai][bj][m][0], v1 = acc[ai][bj][m][1];
;                     if (ACT == 1) {
; #pragma unroll
;                         for (int j = 0; j < 4; ++j) { float a = fmaxf(v0[j], 0.f), b = fmaxf(v1[j], 0.f); v0[j] = a * a; v1[j] = b * b; } }
;                     v0 = v0 * scale; v1 = v1 * scale;
;                     u32x4 w; w.x = cvt_pk_bf16(v0[0], v0[1]); w.y = cvt_pk_bf16(v0[2], v0[3]); w.z = cvt_pk_bf16(v1[0], v1[1]); w.w = cvt_pk_bf16(v1[2], v1[3]);
;                     *(u32x4*)(rowp + bj * HALF) = w; } }
	s_brev_b32 s28, 60
	v_readlane_b32 s80, v254, 45
	v_pk_mul_f32 v[126:127], v[126:127], s[28:29] op_sel_hi:[1,0]
	v_pk_mul_f32 v[124:125], v[124:125], s[28:29] op_sel_hi:[1,0]
	v_pk_mul_f32 v[122:123], v[122:123], s[28:29] op_sel_hi:[1,0]
	v_pk_mul_f32 v[120:121], v[120:121], s[28:29] op_sel_hi:[1,0]
	v_pk_mul_f32 v[138:139], v[110:111], s[28:29] op_sel_hi:[1,0]
	v_pk_mul_f32 v[140:141], v[108:109], s[28:29] op_sel_hi:[1,0]
	v_pk_mul_f32 v[142:143], v[102:103], s[28:29] op_sel_hi:[1,0]
	v_pk_mul_f32 v[144:145], v[100:101], s[28:29] op_sel_hi:[1,0]
	v_pk_mul_f32 v[100:101], v[118:119], s[28:29] op_sel_hi:[1,0]
	v_pk_mul_f32 v[102:103], v[116:117], s[28:29] op_sel_hi:[1,0]
	v_pk_mul_f32 v[108:109], v[114:115], s[28:29] op_sel_hi:[1,0]
	v_pk_mul_f32 v[110:111], v[112:113], s[28:29] op_sel_hi:[1,0]
	v_pk_mul_f32 v[112:113], v[94:95], s[28:29] op_sel_hi:[1,0]
	v_pk_mul_f32 v[114:115], v[92:93], s[28:29] op_sel_hi:[1,0]
	v_pk_mul_f32 v[116:117], v[86:87], s[28:29] op_sel_hi:[1,0]
	v_pk_mul_f32 v[118:119], v[84:85], s[28:29] op_sel_hi:[1,0]
	v_pk_mul_f32 v[84:85], v[106:107], s[28:29] op_sel_hi:[1,0]
	v_pk_mul_f32 v[86:87], v[104:105], s[28:29] op_sel_hi:[1,0]
	v_pk_mul_f32 v[92:93], v[98:99], s[28:29] op_sel_hi:[1,0]
	v_pk_mul_f32 v[94:95], v[96:97], s[28:29] op_sel_hi:[1,0]
	v_pk_mul_f32 v[96:97], v[78:79], s[28:29] op_sel_hi:[1,0]
	v_pk_mul_f32 v[98:99], v[76:77], s[28:29] op_sel_hi:[1,0]
	v_pk_mul_f32 v[104:105], v[74:75], s[28:29] op_sel_hi:[1,0]
	v_pk_mul_f32 v[106:107], v[72:73], s[28:29] op_sel_hi:[1,0]
	v_pk_mul_f32 v[72:73], v[90:91], s[28:29] op_sel_hi:[1,0]
	v_pk_mul_f32 v[74:75], v[88:89], s[28:29] op_sel_hi:[1,0]
	v_pk_mul_f32 v[76:77], v[82:83], s[28:29] op_sel_hi:[1,0]
	v_pk_mul_f32 v[78:79], v[80:81], s[28:29] op_sel_hi:[1,0]
	v_pk_mul_f32 v[70:71], v[70:71], s[28:29] op_sel_hi:[1,0]
	v_pk_mul_f32 v[68:69], v[68:69], s[28:29] op_sel_hi:[1,0]
	v_pk_mul_f32 v[66:67], v[66:67], s[28:29] op_sel_hi:[1,0]
	v_pk_mul_f32 v[64:65], v[64:65], s[28:29] op_sel_hi:[1,0]
	v_pk_mul_f32 v[62:63], v[62:63], s[28:29] op_sel_hi:[1,0]
	v_pk_mul_f32 v[60:61], v[60:61], s[28:29] op_sel_hi:[1,0]
	v_pk_mul_f32 v[58:59], v[58:59], s[28:29] op_sel_hi:[1,0]
	v_pk_mul_f32 v[56:57], v[56:57], s[28:29] op_sel_hi:[1,0]
	v_pk_mul_f32 v[80:81], v[46:47], s[28:29] op_sel_hi:[1,0]
	v_pk_mul_f32 v[82:83], v[44:45], s[28:29] op_sel_hi:[1,0]
	v_pk_mul_f32 v[88:89], v[38:39], s[28:29] op_sel_hi:[1,0]
	v_pk_mul_f32 v[90:91], v[36:37], s[28:29] op_sel_hi:[1,0]
	v_pk_mul_f32 v[36:37], v[54:55], s[28:29] op_sel_hi:[1,0]
	v_pk_mul_f32 v[38:39], v[52:53], s[28:29] op_sel_hi:[1,0]
	v_pk_mul_f32 v[44:45], v[50:51], s[28:29] op_sel_hi:[1,0]
	v_pk_mul_f32 v[46:47], v[48:49], s[28:29] op_sel_hi:[1,0]
	v_pk_mul_f32 v[48:49], v[30:31], s[28:29] op_sel_hi:[1,0]
	v_pk_mul_f32 v[50:51], v[28:29], s[28:29] op_sel_hi:[1,0]
	v_pk_mul_f32 v[52:53], v[22:23], s[28:29] op_sel_hi:[1,0]
	v_pk_mul_f32 v[54:55], v[20:21], s[28:29] op_sel_hi:[1,0]
	v_pk_mul_f32 v[20:21], v[42:43], s[28:29] op_sel_hi:[1,0]
	v_pk_mul_f32 v[22:23], v[40:41], s[28:29] op_sel_hi:[1,0]
	v_pk_mul_f32 v[28:29], v[34:35], s[28:29] op_sel_hi:[1,0]
	v_pk_mul_f32 v[30:31], v[32:33], s[28:29] op_sel_hi:[1,0]
	v_pk_mul_f32 v[32:33], v[14:15], s[28:29] op_sel_hi:[1,0]
	v_pk_mul_f32 v[34:35], v[12:13], s[28:29] op_sel_hi:[1,0]
	v_pk_mul_f32 v[40:41], v[10:11], s[28:29] op_sel_hi:[1,0]
	v_pk_mul_f32 v[42:43], v[8:9], s[28:29] op_sel_hi:[1,0]
	v_pk_mul_f32 v[8:9], v[26:27], s[28:29] op_sel_hi:[1,0]
	v_pk_mul_f32 v[10:11], v[24:25], s[28:29] op_sel_hi:[1,0]
	v_pk_mul_f32 v[12:13], v[18:19], s[28:29] op_sel_hi:[1,0]
	v_pk_mul_f32 v[14:15], v[16:17], s[28:29] op_sel_hi:[1,0]
	v_pk_mul_f32 v[6:7], v[6:7], s[28:29] op_sel_hi:[1,0]
	v_pk_mul_f32 v[4:5], v[4:5], s[28:29] op_sel_hi:[1,0]
	v_pk_mul_f32 v[2:3], v[2:3], s[28:29] op_sel_hi:[1,0]
	v_pk_mul_f32 v[0:1], v[0:1], s[28:29] op_sel_hi:[1,0]
	v_readlane_b32 s81, v254, 46
	v_readlane_b32 s82, v254, 47
	v_readlane_b32 s83, v254, 48
	v_readlane_b32 s84, v254, 49
	v_readlane_b32 s85, v254, 50
	v_readlane_b32 s86, v254, 51
	v_readlane_b32 s87, v254, 52
	v_readlane_b32 s88, v254, 53
	v_readlane_b32 s89, v254, 54
	v_readlane_b32 s92, v254, 57
	v_readlane_b32 s93, v254, 58
	v_readlane_b32 s94, v254, 59
	v_readlane_b32 s95, v254, 60
	v_readlane_b32 s90, v254, 55
	v_readlane_b32 s91, v254, 56

; #define PG8_STAGE(bufoff, gbase, voff) do { _Pragma("unroll") for (int _i = 0; _i < 2; ++_i) \
;         __builtin_amdgcn_global_load_lds((const unsigned*)((const char*)(gbase) + (voff)[_i]), (PG8_LAS unsigned*)(lds + (bufoff) + ldsw + _i * 8192), 16, 0, 0); } while (0)
; #define PG8_LDA(dst, b, h) do { _Pragma("unroll") for (int m = 0; m < 4; ++m) _Pragma("unroll") for (int k = 0; k < 2; ++k) dst[m][k] = *(const PG8_LAS bf16x8*)(lds + PG8_SA(b, h) + aoff + m * 2048 + k * 1024); } while (0)
; #define PG8_LDB(dst, b, h) do { _Pragma("unroll") for (int n = 0; n < 2; ++n) _Pragma("unroll") for (int k = 0; k < 2; ++k) dst[n][k] = *(const PG8_LAS bf16x8*)(lds + PG8_SB(b, h) + boff + n * 2048 + k * 1024); } while (0)
; #define PG8_MMA(ai, bj, At, Bt) do { __builtin_amdgcn_s_setprio(1); _Pragma("unroll") for (int m = 0; m < 4; ++m) _Pragma("unroll") for (int n = 0; n < 2; ++n) _Pragma("unroll") for (int k = 0; k < 2; ++k) \
;         acc[ai][bj][m][n] = __builtin_amdgcn_mfma_f32_16x16x32_bf16(Bt[n][k], At[m][k], acc[ai][bj][m][n], 0, 0, 0); __builtin_amdgcn_s_setprio(0); } while (0)
; #define PG8_WAIT_V(n) asm volatile("s_waitcnt vmcnt(" #n ")" ::: "memory")
; #define PG8_BAR __builtin_amdgcn_s_barrier()
; template <class Epi, class Sched, bool ALIGN_EPI = false, bool SP2 = false>
; __device__ __forceinline__ void gemm_phase(PG8_LAS unsigned char* lds, const Gemm g, const Sched& S, const Epi& E) {
;     ...
;         for (int t = 0; t < nt; t += 2) {
;             const bool last = (t == nt - 2);
;             const char* a1 = cA + (size_t)(t + 1) * kstep;
;             const char* a2 = last ? nA : cA + (size_t)(t + 2) * kstep; const char* b2 = last ? nB : cB + (size_t)(t + 2) * kstep;
;             const char* a3 = a2 + kstep; const char* b3 = b2 + kstep;
;             if (last && has_next) S.a_ready(nxt);
;             if constexpr (SP2) {
;             PG8_LDB(B0, 0, 0); PG8_LDB(B1, 0, 1); PG8_SCHED; PG8_LDA(At, 0, 0); PG8_STAGE(PG8_SA(1, 1), a1 + hstep, voffA);
;             PG8_WAIT_V(8); PG8_WAIT_L(0); PG8_BAR; PG8_MMA(0, 0, At, B0); PG8_MMA(0, 1, At, B1); PG8_BAR; PG8_SCHED;
;             PG8_LDA(At, 0, 1); PG8_STAGE(PG8_SB(0, 0), b2, voffB); PG8_STAGE(PG8_SB(0, 1), b2 + hstep, voffB); PG8_STAGE(PG8_SA(0, 0), a2, voffA);
;             PG8_WAIT_V(8); PG8_WAIT_L(0); PG8_BAR; PG8_MMA(1, 0, At, B0); PG8_MMA(1, 1, At, B1); PG8_BAR; PG8_SCHED;
.LBB0_570:
	s_add_u32 s4, s40, 0xfffc0080
	s_addc_u32 s5, s41, -1
	s_add_i32 s28, 0, 0x10000
	s_cmp_eq_u32 s72, 12
	s_cselect_b32 s65, s18, s5
	s_cselect_b32 s64, s19, s4
	v_add_u32_e32 v138, s28, v142
	s_cselect_b32 s5, s13, s71
	s_cselect_b32 s4, s27, s70
	s_add_i32 s48, 0, 0x14000
	ds_read_b128 v[144:147], v138
	ds_read_b128 v[148:151], v138 offset:1024
	ds_read_b128 v[152:155], v138 offset:2048
	ds_read_b128 v[156:159], v138 offset:3072
	v_add_u32_e32 v138, s48, v142
	ds_read_b128 v[160:163], v138
	ds_read_b128 v[164:167], v138 offset:1024
	ds_read_b128 v[168:171], v138 offset:2048
	ds_read_b128 v[172:175], v138 offset:3072
	v_lshl_add_u64 v[138:139], s[40:41], 0, v[134:135]
	s_add_i32 m0, s25, 0xc000
	ds_read_b128 v[182:185], v143
	ds_read_b128 v[186:189], v143 offset:1024
	ds_read_b128 v[190:193], v143 offset:2048
	ds_read_b128 v[194:197], v143 offset:3072
	ds_read_b128 v[198:201], v143 offset:4096
	ds_read_b128 v[202:205], v143 offset:5120
	ds_read_b128 v[206:209], v143 offset:6144
	ds_read_b128 v[210:213], v143 offset:7168
	global_load_lds_dwordx4 v[138:139], off
	v_lshl_add_u64 v[138:139], s[40:41], 0, v[136:137]
	s_add_i32 m0, s25, 0xe000
	s_nop 0
	global_load_lds_dwordx4 v[138:139], off
	s_waitcnt vmcnt(8)
	s_waitcnt lgkmcnt(0)
	s_barrier
	s_setprio 1
	s_waitcnt lgkmcnt(0)
	v_mfma_f32_16x16x32_bf16 v[124:127], v[144:147], v[182:185], v[124:127]
	v_mfma_f32_16x16x32_bf16 v[120:123], v[152:155], v[182:185], v[120:123]
	v_mfma_f32_16x16x32_bf16 v[116:119], v[144:147], v[190:193], v[116:119]
	v_mfma_f32_16x16x32_bf16 v[108:111], v[152:155], v[190:193], v[108:111]
	v_mfma_f32_16x16x32_bf16 v[100:103], v[144:147], v[198:201], v[100:103]
	v_mfma_f32_16x16x32_bf16 v[92:95], v[152:155], v[198:201], v[92:95]
	v_mfma_f32_16x16x32_bf16 v[84:87], v[144:147], v[206:209], v[84:87]
	v_mfma_f32_16x16x32_bf16 v[76:79], v[152:155], v[206:209], v[76:79]
	v_mfma_f32_16x16x32_bf16 v[124:127], v[148:151], v[186:189], v[124:127]
	v_mfma_f32_16x16x32_bf16 v[120:123], v[156:159], v[186:189], v[120:123]
	v_mfma_f32_16x16x32_bf16 v[116:119], v[148:151], v[194:197], v[116:119]
	v_mfma_f32_16x16x32_bf16 v[108:111], v[156:159], v[194:197], v[108:111]
	v_mfma_f32_16x16x32_bf16 v[100:103], v[148:151], v[202:205], v[100:103]
	v_mfma_f32_16x16x32_bf16 v[92:95], v[156:159], v[202:205], v[92:95]
	v_mfma_f32_16x16x32_bf16 v[84:87], v[148:151], v[210:213], v[84:87]
	v_mfma_f32_16x16x32_bf16 v[76:79], v[156:159], v[210:213], v[76:79]
	s_setprio 0
	s_setprio 1
	v_mfma_f32_16x16x32_bf16 v[112:115], v[160:163], v[182:185], v[112:115]
	v_mfma_f32_16x16x32_bf16 v[104:107], v[168:171], v[182:185], v[104:107]
	v_mfma_f32_16x16x32_bf16 v[96:99], v[160:163], v[190:193], v[96:99]
	v_mfma_f32_16x16x32_bf16 v[88:91], v[168:171], v[190:193], v[88:91]
	v_mfma_f32_16x16x32_bf16 v[80:83], v[160:163], v[198:201], v[80:83]
	v_mfma_f32_16x16x32_bf16 v[72:75], v[168:171], v[198:201], v[72:75]
	v_mfma_f32_16x16x32_bf16 v[68:71], v[160:163], v[206:209], v[68:71]
	v_mfma_f32_16x16x32_bf16 v[64:67], v[168:171], v[206:209], v[64:67]
	v_mfma_f32_16x16x32_bf16 v[112:115], v[164:167], v[186:189], v[112:115]
	v_mfma_f32_16x16x32_bf16 v[104:107], v[172:175], v[186:189], v[104:107]
	v_mfma_f32_16x16x32_bf16 v[96:99], v[164:167], v[194:197], v[96:99]
	v_mfma_f32_16x16x32_bf16 v[88:91], v[172:175], v[194:197], v[88:91]
	v_mfma_f32_16x16x32_bf16 v[80:83], v[164:167], v[202:205], v[80:83]
	v_mfma_f32_16x16x32_bf16 v[72:75], v[172:175], v[202:205], v[72:75]
	v_mfma_f32_16x16x32_bf16 v[68:71], v[164:167], v[210:213], v[68:71]
	v_mfma_f32_16x16x32_bf16 v[64:67], v[172:175], v[210:213], v[64:67]
	s_setprio 0
	s_barrier
	s_add_i32 s28, s28, s24
	v_lshl_add_u64 v[138:139], s[4:5], 0, v[176:177]
	s_mov_b32 m0, s28
	ds_read_b128 v[182:185], v143 offset:16384
	ds_read_b128 v[186:189], v143 offset:17408
	ds_read_b128 v[190:193], v143 offset:18432
	ds_read_b128 v[194:197], v143 offset:19456
	ds_read_b128 v[198:201], v143 offset:20480
	ds_read_b128 v[202:205], v143 offset:21504
	ds_read_b128 v[206:209], v143 offset:22528
	ds_read_b128 v[210:213], v143 offset:23552
	global_load_lds_dwordx4 v[138:139], off
	s_add_i32 m0, s28, 0x2000
	s_add_u32 s38, s4, 0x40000
	v_lshl_add_u64 v[214:215], s[4:5], 0, v[128:129]
	s_addc_u32 s39, s5, 0
	s_add_i32 s28, s48, s24
	global_load_lds_dwordx4 v[214:215], off
	v_lshl_add_u64 v[216:217], s[38:39], 0, v[176:177]
	s_mov_b32 m0, s28
	v_lshl_add_u64 v[218:219], s[64:65], 0, v[130:131]
	global_load_lds_dwordx4 v[216:217], off
	v_lshl_add_u64 v[216:217], s[38:39], 0, v[128:129]
	s_add_i32 m0, s28, 0x2000
	s_nop 0
	global_load_lds_dwordx4 v[216:217], off
	v_lshl_add_u64 v[216:217], s[64:65], 0, v[132:133]
	s_mov_b32 m0, s25
	s_nop 0
	global_load_lds_dwordx4 v[216:217], off
	s_mov_b32 m0, s30
	s_nop 0
	global_load_lds_dwordx4 v[218:219], off
	s_waitcnt vmcnt(8)
	s_waitcnt lgkmcnt(0)
	s_barrier
; #define PG8_STAGE(bufoff, gbase, voff) do { _Pragma("unroll") for (int _i = 0; _i < 2; ++_i) \
;         __builtin_amdgcn_global_load_lds((const unsigned*)((const char*)(gbase) + (voff)[_i]), (PG8_LAS unsigned*)(lds + (bufoff) + ldsw + _i * 8192), 16, 0, 0); } while (0)
; #define PG8_LDA(dst, b, h) do { _Pragma("unroll") for (int m = 0; m < 4; ++m) _Pragma("unroll") for (int k = 0; k < 2; ++k) dst[m][k] = *(const PG8_LAS bf16x8*)(lds + PG8_SA(b, h) + aoff + m * 2048 + k * 1024); } while (0)
; #define PG8_LDB(dst, b, h) do { _Pragma("unroll") for (int n = 0; n < 2; ++n) _Pragma("unroll") for (int k = 0; k < 2; ++k) dst[n][k] = *(const PG8_LAS bf16x8*)(lds + PG8_SB(b, h) + boff + n * 2048 + k * 1024); } while (0)
; #define PG8_MMA(ai, bj, At, Bt) do { __builtin_amdgcn_s_setprio(1); _Pragma("unroll") for (int m = 0; m < 4; ++m) _Pragma("unroll") for (int n = 0; n < 2; ++n) _Pragma("unroll") for (int k = 0; k < 2; ++k) \
;         acc[ai][bj][m][n] = __builtin_amdgcn_mfma_f32_16x16x32_bf16(Bt[n][k], At[m][k], acc[ai][bj][m][n], 0, 0, 0); __builtin_amdgcn_s_setprio(0); } while (0)
; #define PG8_WAIT_V(n) asm volatile("s_waitcnt vmcnt(" #n ")" ::: "memory")
; #define PG8_WAIT_L(n) asm volatile("s_waitcnt lgkmcnt(" #n ")" ::: "memory")
; #define PG8_BAR __builtin_amdgcn_s_barrier()
; #define PG8_SCHED __builtin_amdgcn_sched_barrier(0)
; template <class Epi, class Sched, bool ALIGN_EPI = false, bool SP2 = false>
; __device__ __forceinline__ void gemm_phase(PG8_LAS unsigned char* lds, const Gemm g, const Sched& S, const Epi& E) {
;     ...
;             PG8_WAIT_V(8); PG8_WAIT_L(0); PG8_BAR; PG8_MMA(1, 0, At, B0); PG8_MMA(1, 1, At, B1); PG8_BAR; PG8_SCHED;
;             PG8_LDB(B0, 1, 0); PG8_LDB(B1, 1, 1); PG8_SCHED; PG8_LDA(At, 1, 0); PG8_STAGE(PG8_SA(0, 1), a2 + hstep, voffA);
;             PG8_WAIT_V(8); PG8_WAIT_L(0); PG8_BAR; PG8_MMA(0, 0, At, B0); PG8_MMA(0, 1, At, B1); PG8_BAR; PG8_SCHED;
;             PG8_LDA(At, 1, 1); PG8_STAGE(PG8_SB(1, 0), b3, voffB); PG8_STAGE(PG8_SB(1, 1), b3 + hstep, voffB); PG8_STAGE(PG8_SA(1, 0), a3, voffA);
;             PG8_WAIT_V(8); PG8_WAIT_L(0); PG8_BAR; PG8_MMA(1, 0, At, B0); PG8_MMA(1, 1, At, B1); PG8_BAR; PG8_SCHED;
	s_setprio 1
	s_waitcnt lgkmcnt(0)
	v_mfma_f32_16x16x32_bf16 v[60:63], v[144:147], v[182:185], v[60:63]
	v_mfma_f32_16x16x32_bf16 v[56:59], v[152:155], v[182:185], v[56:59]
	v_mfma_f32_16x16x32_bf16 v[52:55], v[144:147], v[190:193], v[52:55]
	v_mfma_f32_16x16x32_bf16 v[44:47], v[152:155], v[190:193], v[44:47]
	v_mfma_f32_16x16x32_bf16 v[36:39], v[144:147], v[198:201], v[36:39]
	v_mfma_f32_16x16x32_bf16 v[28:31], v[152:155], v[198:201], v[28:31]
	v_mfma_f32_16x16x32_bf16 v[20:23], v[144:147], v[206:209], v[20:23]
	v_mfma_f32_16x16x32_bf16 v[12:15], v[152:155], v[206:209], v[12:15]
	v_mfma_f32_16x16x32_bf16 v[60:63], v[148:151], v[186:189], v[60:63]
	v_mfma_f32_16x16x32_bf16 v[56:59], v[156:159], v[186:189], v[56:59]
	v_mfma_f32_16x16x32_bf16 v[52:55], v[148:151], v[194:197], v[52:55]
	v_mfma_f32_16x16x32_bf16 v[44:47], v[156:159], v[194:197], v[44:47]
	v_mfma_f32_16x16x32_bf16 v[36:39], v[148:151], v[202:205], v[36:39]
	v_mfma_f32_16x16x32_bf16 v[28:31], v[156:159], v[202:205], v[28:31]
	v_mfma_f32_16x16x32_bf16 v[20:23], v[148:151], v[210:213], v[20:23]
	v_mfma_f32_16x16x32_bf16 v[12:15], v[156:159], v[210:213], v[12:15]
	s_setprio 0
	s_setprio 1
	v_mfma_f32_16x16x32_bf16 v[48:51], v[160:163], v[182:185], v[48:51]
	v_mfma_f32_16x16x32_bf16 v[40:43], v[168:171], v[182:185], v[40:43]
	v_mfma_f32_16x16x32_bf16 v[32:35], v[160:163], v[190:193], v[32:35]
	v_mfma_f32_16x16x32_bf16 v[24:27], v[168:171], v[190:193], v[24:27]
	v_mfma_f32_16x16x32_bf16 v[16:19], v[160:163], v[198:201], v[16:19]
	v_mfma_f32_16x16x32_bf16 v[8:11], v[168:171], v[198:201], v[8:11]
	v_mfma_f32_16x16x32_bf16 v[4:7], v[160:163], v[206:209], v[4:7]
	v_mfma_f32_16x16x32_bf16 v[0:3], v[168:171], v[206:209], v[0:3]
	v_mfma_f32_16x16x32_bf16 v[48:51], v[164:167], v[186:189], v[48:51]
	v_mfma_f32_16x16x32_bf16 v[40:43], v[172:175], v[186:189], v[40:43]
	v_mfma_f32_16x16x32_bf16 v[32:35], v[164:167], v[194:197], v[32:35]
	v_mfma_f32_16x16x32_bf16 v[24:27], v[172:175], v[194:197], v[24:27]
	v_mfma_f32_16x16x32_bf16 v[16:19], v[164:167], v[202:205], v[16:19]
	v_mfma_f32_16x16x32_bf16 v[8:11], v[172:175], v[202:205], v[8:11]
	v_mfma_f32_16x16x32_bf16 v[4:7], v[164:167], v[210:213], v[4:7]
	v_mfma_f32_16x16x32_bf16 v[0:3], v[172:175], v[210:213], v[0:3]
	s_setprio 0
	s_barrier
	s_add_i32 s28, 0, 0x18000
	s_add_i32 s48, 0, 0x1c000
	v_add_u32_e32 v156, s28, v142
	v_add_u32_e32 v172, s48, v142
	ds_read_b128 v[144:147], v156
	ds_read_b128 v[148:151], v156 offset:1024
	ds_read_b128 v[152:155], v156 offset:2048
	ds_read_b128 v[156:159], v156 offset:3072
	ds_read_b128 v[160:163], v172
	ds_read_b128 v[164:167], v172 offset:1024
	ds_read_b128 v[168:171], v172 offset:2048
	ds_read_b128 v[172:175], v172 offset:3072
	s_add_u32 s38, s64, 0x40000
	s_addc_u32 s39, s65, 0
	s_mov_b32 m0, s31
	v_lshl_add_u64 v[220:221], s[38:39], 0, v[132:133]
	ds_read_b128 v[182:185], v143 offset:32768
	ds_read_b128 v[186:189], v143 offset:33792
	ds_read_b128 v[190:193], v143 offset:34816
	ds_read_b128 v[194:197], v143 offset:35840
	ds_read_b128 v[198:201], v143 offset:36864
	ds_read_b128 v[202:205], v143 offset:37888
	ds_read_b128 v[206:209], v143 offset:38912
	ds_read_b128 v[210:213], v143 offset:39936
	global_load_lds_dwordx4 v[220:221], off
	v_lshl_add_u64 v[220:221], s[38:39], 0, v[130:131]
	s_mov_b32 m0, s42
	s_nop 0
	global_load_lds_dwordx4 v[220:221], off
	s_waitcnt vmcnt(8)
	s_waitcnt lgkmcnt(0)
	s_barrier
	s_setprio 1
	s_waitcnt lgkmcnt(0)
	v_mfma_f32_16x16x32_bf16 v[124:127], v[144:147], v[182:185], v[124:127]
	v_mfma_f32_16x16x32_bf16 v[120:123], v[152:155], v[182:185], v[120:123]
	v_mfma_f32_16x16x32_bf16 v[116:119], v[144:147], v[190:193], v[116:119]
	v_mfma_f32_16x16x32_bf16 v[108:111], v[152:155], v[190:193], v[108:111]
	v_mfma_f32_16x16x32_bf16 v[100:103], v[144:147], v[198:201], v[100:103]
	v_mfma_f32_16x16x32_bf16 v[92:95], v[152:155], v[198:201], v[92:95]
	v_mfma_f32_16x16x32_bf16 v[84:87], v[144:147], v[206:209], v[84:87]
	v_mfma_f32_16x16x32_bf16 v[76:79], v[152:155], v[206:209], v[76:79]
	v_mfma_f32_16x16x32_bf16 v[124:127], v[148:151], v[186:189], v[124:127]
	v_mfma_f32_16x16x32_bf16 v[120:123], v[156:159], v[186:189], v[120:123]
	v_mfma_f32_16x16x32_bf16 v[116:119], v[148:151], v[194:197], v[116:119]
	v_mfma_f32_16x16x32_bf16 v[108:111], v[156:159], v[194:197], v[108:111]
	v_mfma_f32_16x16x32_bf16 v[100:103], v[148:151], v[202:205], v[100:103]
	v_mfma_f32_16x16x32_bf16 v[92:95], v[156:159], v[202:205], v[92:95]
	v_mfma_f32_16x16x32_bf16 v[84:87], v[148:151], v[210:213], v[84:87]
	v_mfma_f32_16x16x32_bf16 v[76:79], v[156:159], v[210:213], v[76:79]
	s_setprio 0
	s_setprio 1
	v_mfma_f32_16x16x32_bf16 v[112:115], v[160:163], v[182:185], v[112:115]
	v_mfma_f32_16x16x32_bf16 v[104:107], v[168:171], v[182:185], v[104:107]
	v_mfma_f32_16x16x32_bf16 v[96:99], v[160:163], v[190:193], v[96:99]
	v_mfma_f32_16x16x32_bf16 v[88:91], v[168:171], v[190:193], v[88:91]
	v_mfma_f32_16x16x32_bf16 v[80:83], v[160:163], v[198:201], v[80:83]
	v_mfma_f32_16x16x32_bf16 v[72:75], v[168:171], v[198:201], v[72:75]
	v_mfma_f32_16x16x32_bf16 v[68:71], v[160:163], v[206:209], v[68:71]
	v_mfma_f32_16x16x32_bf16 v[64:67], v[168:171], v[206:209], v[64:67]
	v_mfma_f32_16x16x32_bf16 v[112:115], v[164:167], v[186:189], v[112:115]
	v_mfma_f32_16x16x32_bf16 v[104:107], v[172:175], v[186:189], v[104:107]
	v_mfma_f32_16x16x32_bf16 v[96:99], v[164:167], v[194:197], v[96:99]
	v_mfma_f32_16x16x32_bf16 v[88:91], v[172:175], v[194:197], v[88:91]
	v_mfma_f32_16x16x32_bf16 v[80:83], v[164:167], v[202:205], v[80:83]
	v_mfma_f32_16x16x32_bf16 v[72:75], v[172:175], v[202:205], v[72:75]
	v_mfma_f32_16x16x32_bf16 v[68:71], v[164:167], v[210:213], v[68:71]
	v_mfma_f32_16x16x32_bf16 v[64:67], v[172:175], v[210:213], v[64:67]
	s_setprio 0
	s_barrier
; #define PG8_STAGE(bufoff, gbase, voff) do { _Pragma("unroll") for (int _i = 0; _i < 2; ++_i) \
;         __builtin_amdgcn_global_load_lds((const unsigned*)((const char*)(gbase) + (voff)[_i]), (PG8_LAS unsigned*)(lds + (bufoff) + ldsw + _i * 8192), 16, 0, 0); } while (0)
; #define PG8_LDA(dst, b, h) do { _Pragma("unroll") for (int m = 0; m < 4; ++m) _Pragma("unroll") for (int k = 0; k < 2; ++k) dst[m][k] = *(const PG8_LAS bf16x8*)(lds + PG8_SA(b, h) + aoff + m * 2048 + k * 1024); } while (0)
; #define PG8_MMA(ai, bj, At, Bt) do { __builtin_amdgcn_s_setprio(1); _Pragma("unroll") for (int m = 0; m < 4; ++m) _Pragma("unroll") for (int n = 0; n < 2; ++n) _Pragma("unroll") for (int k = 0; k < 2; ++k) \
;         acc[ai][bj][m][n] = __builtin_amdgcn_mfma_f32_16x16x32_bf16(Bt[n][k], At[m][k], acc[ai][bj][m][n], 0, 0, 0); __builtin_amdgcn_s_setprio(0); } while (0)
; #define PG8_WAIT_V(n) asm volatile("s_waitcnt vmcnt(" #n ")" ::: "memory")
; #define PG8_WAIT_L(n) asm volatile("s_waitcnt lgkmcnt(" #n ")" ::: "memory")
; #define PG8_BAR __builtin_amdgcn_s_barrier()
; #define PG8_SCHED __builtin_amdgcn_sched_barrier(0)
; template <class Epi, class Sched, bool ALIGN_EPI = false, bool SP2 = false>
; __device__ __forceinline__ void gemm_phase(PG8_LAS unsigned char* lds, const Gemm g, const Sched& S, const Epi& E) {
;     ...
;         for (int t = 0; t < nt; t += 2) {
;             const bool last = (t == nt - 2);
;             const char* a1 = cA + (size_t)(t + 1) * kstep;
;             const char* a2 = last ? nA : cA + (size_t)(t + 2) * kstep; const char* b2 = last ? nB : cB + (size_t)(t + 2) * kstep;
;     ...
;             PG8_LDA(At, 1, 1); PG8_STAGE(PG8_SB(1, 0), b3, voffB); PG8_STAGE(PG8_SB(1, 1), b3 + hstep, voffB); PG8_STAGE(PG8_SA(1, 0), a3, voffA);
;             PG8_WAIT_V(8); PG8_WAIT_L(0); PG8_BAR; PG8_MMA(1, 0, At, B0); PG8_MMA(1, 1, At, B1); PG8_BAR; PG8_SCHED;
	s_add_i32 s28, s28, s24
	v_lshl_add_u64 v[138:139], v[138:139], 0, s[44:45]
	s_mov_b32 m0, s28
	ds_read_b128 v[182:185], v143 offset:49152
	ds_read_b128 v[186:189], v143 offset:50176
	ds_read_b128 v[190:193], v143 offset:51200
	ds_read_b128 v[194:197], v143 offset:52224
	ds_read_b128 v[198:201], v143 offset:53248
	ds_read_b128 v[202:205], v143 offset:54272
	ds_read_b128 v[206:209], v143 offset:55296
	ds_read_b128 v[210:213], v143 offset:56320
	global_load_lds_dwordx4 v[138:139], off
	s_add_i32 m0, s28, 0x2000
	s_add_u32 s4, s4, 0x40080
	v_lshl_add_u64 v[138:139], v[214:215], 0, s[44:45]
	s_addc_u32 s5, s5, 0
	s_add_i32 s28, s48, s24
	global_load_lds_dwordx4 v[138:139], off
	v_lshl_add_u64 v[138:139], s[4:5], 0, v[176:177]
	s_mov_b32 m0, s28
	s_nop 0
	global_load_lds_dwordx4 v[138:139], off
	v_lshl_add_u64 v[138:139], s[4:5], 0, v[128:129]
	s_add_i32 m0, s28, 0x2000
	s_nop 0
	global_load_lds_dwordx4 v[138:139], off
	v_lshl_add_u64 v[138:139], v[216:217], 0, s[44:45]
	s_mov_b32 m0, s63
	s_nop 0
	global_load_lds_dwordx4 v[138:139], off
	v_lshl_add_u64 v[138:139], v[218:219], 0, s[44:45]
	s_mov_b32 m0, s66
	s_nop 0
	global_load_lds_dwordx4 v[138:139], off
	s_waitcnt vmcnt(8)
	s_waitcnt lgkmcnt(0)
	s_barrier
	s_setprio 1
	s_waitcnt lgkmcnt(0)
	v_mfma_f32_16x16x32_bf16 v[60:63], v[144:147], v[182:185], v[60:63]
	v_mfma_f32_16x16x32_bf16 v[56:59], v[152:155], v[182:185], v[56:59]
	v_mfma_f32_16x16x32_bf16 v[52:55], v[144:147], v[190:193], v[52:55]
	v_mfma_f32_16x16x32_bf16 v[44:47], v[152:155], v[190:193], v[44:47]
	v_mfma_f32_16x16x32_bf16 v[36:39], v[144:147], v[198:201], v[36:39]
	v_mfma_f32_16x16x32_bf16 v[28:31], v[152:155], v[198:201], v[28:31]
	v_mfma_f32_16x16x32_bf16 v[20:23], v[144:147], v[206:209], v[20:23]
	v_mfma_f32_16x16x32_bf16 v[12:15], v[152:155], v[206:209], v[12:15]
	v_mfma_f32_16x16x32_bf16 v[60:63], v[148:151], v[186:189], v[60:63]
	v_mfma_f32_16x16x32_bf16 v[56:59], v[156:159], v[186:189], v[56:59]
	v_mfma_f32_16x16x32_bf16 v[52:55], v[148:151], v[194:197], v[52:55]
	v_mfma_f32_16x16x32_bf16 v[44:47], v[156:159], v[194:197], v[44:47]
	v_mfma_f32_16x16x32_bf16 v[36:39], v[148:151], v[202:205], v[36:39]
	v_mfma_f32_16x16x32_bf16 v[28:31], v[156:159], v[202:205], v[28:31]
	v_mfma_f32_16x16x32_bf16 v[20:23], v[148:151], v[210:213], v[20:23]
	v_mfma_f32_16x16x32_bf16 v[12:15], v[156:159], v[210:213], v[12:15]
	s_setprio 0
	s_setprio 1
	v_mfma_f32_16x16x32_bf16 v[48:51], v[160:163], v[182:185], v[48:51]
	v_mfma_f32_16x16x32_bf16 v[40:43], v[168:171], v[182:185], v[40:43]
	v_mfma_f32_16x16x32_bf16 v[32:35], v[160:163], v[190:193], v[32:35]
	v_mfma_f32_16x16x32_bf16 v[24:27], v[168:171], v[190:193], v[24:27]
	v_mfma_f32_16x16x32_bf16 v[16:19], v[160:163], v[198:201], v[16:19]
	v_mfma_f32_16x16x32_bf16 v[8:11], v[168:171], v[198:201], v[8:11]
	v_mfma_f32_16x16x32_bf16 v[4:7], v[160:163], v[206:209], v[4:7]
	v_mfma_f32_16x16x32_bf16 v[0:3], v[168:171], v[206:209], v[0:3]
	v_mfma_f32_16x16x32_bf16 v[48:51], v[164:167], v[186:189], v[48:51]
	v_mfma_f32_16x16x32_bf16 v[40:43], v[172:175], v[186:189], v[40:43]
	s_add_i32 s72, s72, 2
	v_mfma_f32_16x16x32_bf16 v[32:35], v[164:167], v[194:197], v[32:35]
	s_add_u32 s40, s40, 0x100
	v_mfma_f32_16x16x32_bf16 v[24:27], v[172:175], v[194:197], v[24:27]
	s_addc_u32 s41, s41, 0
	v_mfma_f32_16x16x32_bf16 v[16:19], v[164:167], v[202:205], v[16:19]
	s_add_u32 s70, s70, 0x100
	v_mfma_f32_16x16x32_bf16 v[8:11], v[172:175], v[202:205], v[8:11]
	s_addc_u32 s71, s71, 0
	v_mfma_f32_16x16x32_bf16 v[4:7], v[164:167], v[210:213], v[4:7]
	s_cmp_gt_u32 s72, 13
	v_mfma_f32_16x16x32_bf16 v[0:3], v[172:175], v[210:213], v[0:3]
	s_setprio 0
	s_barrier
	s_cbranch_scc0 .LBB0_570

; #define PG8_STAGE(bufoff, gbase, voff) do { _Pragma("unroll") for (int _i = 0; _i < 2; ++_i) \
;         __builtin_amdgcn_global_load_lds((const unsigned*)((const char*)(gbase) + (voff)[_i]), (PG8_LAS unsigned*)(lds + (bufoff) + ldsw + _i * 8192), 16, 0, 0); } while (0)
; #define PG8_LDA(dst, b, h) do { _Pragma("unroll") for (int m = 0; m < 4; ++m) _Pragma("unroll") for (int k = 0; k < 2; ++k) dst[m][k] = *(const PG8_LAS bf16x8*)(lds + PG8_SA(b, h) + aoff + m * 2048 + k * 1024); } while (0)
; #define PG8_LDB(dst, b, h) do { _Pragma("unroll") for (int n = 0; n < 2; ++n) _Pragma("unroll") for (int k = 0; k < 2; ++k) dst[n][k] = *(const PG8_LAS bf16x8*)(lds + PG8_SB(b, h) + boff + n * 2048 + k * 1024); } while (0)
; #define PG8_MMA(ai, bj, At, Bt) do { __builtin_amdgcn_s_setprio(1); _Pragma("unroll") for (int m = 0; m < 4; ++m) _Pragma("unroll") for (int n = 0; n < 2; ++n) _Pragma("unroll") for (int k = 0; k < 2; ++k) \
;         acc[ai][bj][m][n] = __builtin_amdgcn_mfma_f32_16x16x32_bf16(Bt[n][k], At[m][k], acc[ai][bj][m][n], 0, 0, 0); __builtin_amdgcn_s_setprio(0); } while (0)
; #define PG8_WAIT_V(n) asm volatile("s_waitcnt vmcnt(" #n ")" ::: "memory")
; #define PG8_WAIT_L(n) asm volatile("s_waitcnt lgkmcnt(" #n ")" ::: "memory")
; template <class Epi, class Sched, bool ALIGN_EPI = false, bool SP2 = false>
; __device__ __forceinline__ void gemm_phase(PG8_LAS unsigned char* lds, const Gemm g, const Sched& S, const Epi& E) {
;     ...
;             const bool last = (t == nt - 2);
;             const char* a1 = cA + (size_t)(t + 1) * kstep;
;             const char* a2 = last ? nA : cA + (size_t)(t + 2) * kstep; const char* b2 = last ? nB : cB + (size_t)(t + 2) * kstep;
;             const char* a3 = a2 + kstep; const char* b3 = b2 + kstep;
;             if (last && has_next) S.a_ready(nxt);
;             if constexpr (SP2) {
;             PG8_LDB(B0, 0, 0); PG8_LDB(B1, 0, 1); PG8_SCHED; PG8_LDA(At, 0, 0); PG8_STAGE(PG8_SA(1, 1), a1 + hstep, voffA);
;             PG8_WAIT_V(8); PG8_WAIT_L(0); PG8_BAR; PG8_MMA(0, 0, At, B0); PG8_MMA(0, 1, At, B1); PG8_BAR; PG8_SCHED;
;             PG8_LDA(At, 0, 1); PG8_STAGE(PG8_SB(0, 0), b2, voffB); PG8_STAGE(PG8_SB(0, 1), b2 + hstep, voffB); PG8_STAGE(PG8_SA(0, 0), a2, voffA);
;             PG8_WAIT_V(8); PG8_WAIT_L(0); PG8_BAR; PG8_MMA(1, 0, At, B0); PG8_MMA(1, 1, At, B1); PG8_BAR; PG8_SCHED;
.Lg2_peel:
	s_add_u32 s4, s40, 0xfffc0080
	s_addc_u32 s5, s41, -1
	s_add_i32 s28, 0, 0x10000
	s_cmp_eq_u32 s72, 12
	s_cselect_b32 s65, s18, s5
	s_cselect_b32 s64, s19, s4
	v_add_u32_e32 v138, s28, v142
	s_cselect_b32 s5, s13, s71
	s_cselect_b32 s4, s27, s70
	s_add_i32 s48, 0, 0x14000
	ds_read_b128 v[144:147], v138
	ds_read_b128 v[148:151], v138 offset:1024
	ds_read_b128 v[152:155], v138 offset:2048
	ds_read_b128 v[156:159], v138 offset:3072
	v_add_u32_e32 v138, s48, v142
	ds_read_b128 v[160:163], v138
	ds_read_b128 v[164:167], v138 offset:1024
	ds_read_b128 v[168:171], v138 offset:2048
	ds_read_b128 v[172:175], v138 offset:3072
	v_lshl_add_u64 v[138:139], s[40:41], 0, v[134:135]
	s_add_i32 m0, s25, 0xc000
	ds_read_b128 v[182:185], v143
	ds_read_b128 v[186:189], v143 offset:1024
	ds_read_b128 v[190:193], v143 offset:2048
	ds_read_b128 v[194:197], v143 offset:3072
	ds_read_b128 v[198:201], v143 offset:4096
	ds_read_b128 v[202:205], v143 offset:5120
	ds_read_b128 v[206:209], v143 offset:6144
	ds_read_b128 v[210:213], v143 offset:7168
	global_load_lds_dwordx4 v[138:139], off
	v_lshl_add_u64 v[138:139], s[40:41], 0, v[136:137]
	s_add_i32 m0, s25, 0xe000
	s_nop 0
	global_load_lds_dwordx4 v[138:139], off
	s_waitcnt vmcnt(24)
	s_waitcnt lgkmcnt(0)
	s_barrier
	s_setprio 1
	s_waitcnt lgkmcnt(0)
	v_mfma_f32_16x16x32_bf16 v[124:127], v[144:147], v[182:185], 0
	v_mfma_f32_16x16x32_bf16 v[120:123], v[152:155], v[182:185], 0
	v_mfma_f32_16x16x32_bf16 v[116:119], v[144:147], v[190:193], 0
	v_mfma_f32_16x16x32_bf16 v[108:111], v[152:155], v[190:193], 0
	v_mfma_f32_16x16x32_bf16 v[100:103], v[144:147], v[198:201], 0
	v_mfma_f32_16x16x32_bf16 v[92:95], v[152:155], v[198:201], 0
	v_mfma_f32_16x16x32_bf16 v[84:87], v[144:147], v[206:209], 0
	v_mfma_f32_16x16x32_bf16 v[76:79], v[152:155], v[206:209], 0
	v_mfma_f32_16x16x32_bf16 v[124:127], v[148:151], v[186:189], v[124:127]
	v_mfma_f32_16x16x32_bf16 v[120:123], v[156:159], v[186:189], v[120:123]
	v_mfma_f32_16x16x32_bf16 v[116:119], v[148:151], v[194:197], v[116:119]
	v_mfma_f32_16x16x32_bf16 v[108:111], v[156:159], v[194:197], v[108:111]
	v_mfma_f32_16x16x32_bf16 v[100:103], v[148:151], v[202:205], v[100:103]
	v_mfma_f32_16x16x32_bf16 v[92:95], v[156:159], v[202:205], v[92:95]
	v_mfma_f32_16x16x32_bf16 v[84:87], v[148:151], v[210:213], v[84:87]
	v_mfma_f32_16x16x32_bf16 v[76:79], v[156:159], v[210:213], v[76:79]
	s_setprio 0
	s_setprio 1
	v_mfma_f32_16x16x32_bf16 v[112:115], v[160:163], v[182:185], 0
	v_mfma_f32_16x16x32_bf16 v[104:107], v[168:171], v[182:185], 0
	v_mfma_f32_16x16x32_bf16 v[96:99], v[160:163], v[190:193], 0
	v_mfma_f32_16x16x32_bf16 v[88:91], v[168:171], v[190:193], 0
	v_mfma_f32_16x16x32_bf16 v[80:83], v[160:163], v[198:201], 0
	v_mfma_f32_16x16x32_bf16 v[72:75], v[168:171], v[198:201], 0
	v_mfma_f32_16x16x32_bf16 v[68:71], v[160:163], v[206:209], 0
	v_mfma_f32_16x16x32_bf16 v[64:67], v[168:171], v[206:209], 0
	v_mfma_f32_16x16x32_bf16 v[112:115], v[164:167], v[186:189], v[112:115]
	v_mfma_f32_16x16x32_bf16 v[104:107], v[172:175], v[186:189], v[104:107]
	v_mfma_f32_16x16x32_bf16 v[96:99], v[164:167], v[194:197], v[96:99]
	v_mfma_f32_16x16x32_bf16 v[88:91], v[172:175], v[194:197], v[88:91]
	v_mfma_f32_16x16x32_bf16 v[80:83], v[164:167], v[202:205], v[80:83]
	v_mfma_f32_16x16x32_bf16 v[72:75], v[172:175], v[202:205], v[72:75]
	v_mfma_f32_16x16x32_bf16 v[68:71], v[164:167], v[210:213], v[68:71]
	v_mfma_f32_16x16x32_bf16 v[64:67], v[172:175], v[210:213], v[64:67]
	s_setprio 0
	s_barrier
	s_add_i32 s28, s28, s24
	v_lshl_add_u64 v[138:139], s[4:5], 0, v[176:177]
	s_mov_b32 m0, s28
	ds_read_b128 v[182:185], v143 offset:16384
	ds_read_b128 v[186:189], v143 offset:17408
	ds_read_b128 v[190:193], v143 offset:18432
	ds_read_b128 v[194:197], v143 offset:19456
	ds_read_b128 v[198:201], v143 offset:20480
	ds_read_b128 v[202:205], v143 offset:21504
	ds_read_b128 v[206:209], v143 offset:22528
	ds_read_b128 v[210:213], v143 offset:23552
	global_load_lds_dwordx4 v[138:139], off
	s_add_i32 m0, s28, 0x2000
	s_add_u32 s38, s4, 0x40000
	v_lshl_add_u64 v[214:215], s[4:5], 0, v[128:129]
	s_addc_u32 s39, s5, 0
	s_add_i32 s28, s48, s24
	global_load_lds_dwordx4 v[214:215], off
	v_lshl_add_u64 v[216:217], s[38:39], 0, v[176:177]
	s_mov_b32 m0, s28
	v_lshl_add_u64 v[218:219], s[64:65], 0, v[130:131]
	global_load_lds_dwordx4 v[216:217], off
	v_lshl_add_u64 v[216:217], s[38:39], 0, v[128:129]
	s_add_i32 m0, s28, 0x2000
	s_nop 0
	global_load_lds_dwordx4 v[216:217], off
	v_lshl_add_u64 v[216:217], s[64:65], 0, v[132:133]
	s_mov_b32 m0, s25
	s_nop 0
	global_load_lds_dwordx4 v[216:217], off
	s_mov_b32 m0, s30
	s_nop 0
	global_load_lds_dwordx4 v[218:219], off
	s_waitcnt vmcnt(24)
	s_waitcnt lgkmcnt(0)
	s_barrier
; #define PG8_STAGE(bufoff, gbase, voff) do { _Pragma("unroll") for (int _i = 0; _i < 2; ++_i) \
;         __builtin_amdgcn_global_load_lds((const unsigned*)((const char*)(gbase) + (voff)[_i]), (PG8_LAS unsigned*)(lds + (bufoff) + ldsw + _i * 8192), 16, 0, 0); } while (0)
; #define PG8_LDA(dst, b, h) do { _Pragma("unroll") for (int m = 0; m < 4; ++m) _Pragma("unroll") for (int k = 0; k < 2; ++k) dst[m][k] = *(const PG8_LAS bf16x8*)(lds + PG8_SA(b, h) + aoff + m * 2048 + k * 1024); } while (0)
; #define PG8_LDB(dst, b, h) do { _Pragma("unroll") for (int n = 0; n < 2; ++n) _Pragma("unroll") for (int k = 0; k < 2; ++k) dst[n][k] = *(const PG8_LAS bf16x8*)(lds + PG8_SB(b, h) + boff + n * 2048 + k * 1024); } while (0)
; #define PG8_MMA(ai, bj, At, Bt) do { __builtin_amdgcn_s_setprio(1); _Pragma("unroll") for (int m = 0; m < 4; ++m) _Pragma("unroll") for (int n = 0; n < 2; ++n) _Pragma("unroll") for (int k = 0; k < 2; ++k) \
;         acc[ai][bj][m][n] = __builtin_amdgcn_mfma_f32_16x16x32_bf16(Bt[n][k], At[m][k], acc[ai][bj][m][n], 0, 0, 0); __builtin_amdgcn_s_setprio(0); } while (0)
; #define PG8_WAIT_V(n) asm volatile("s_waitcnt vmcnt(" #n ")" ::: "memory")
; #define PG8_WAIT_L(n) asm volatile("s_waitcnt lgkmcnt(" #n ")" ::: "memory")
; #define PG8_BAR __builtin_amdgcn_s_barrier()
; #define PG8_SCHED __builtin_amdgcn_sched_barrier(0)
; template <class Epi, class Sched, bool ALIGN_EPI = false, bool SP2 = false>
; __device__ __forceinline__ void gemm_phase(PG8_LAS unsigned char* lds, const Gemm g, const Sched& S, const Epi& E) {
;     ...
;             PG8_WAIT_V(8); PG8_WAIT_L(0); PG8_BAR; PG8_MMA(1, 0, At, B0); PG8_MMA(1, 1, At, B1); PG8_BAR; PG8_SCHED;
;             PG8_LDB(B0, 1, 0); PG8_LDB(B1, 1, 1); PG8_SCHED; PG8_LDA(At, 1, 0); PG8_STAGE(PG8_SA(0, 1), a2 + hstep, voffA);
;             PG8_WAIT_V(8); PG8_WAIT_L(0); PG8_BAR; PG8_MMA(0, 0, At, B0); PG8_MMA(0, 1, At, B1); PG8_BAR; PG8_SCHED;
	s_setprio 1
	s_waitcnt lgkmcnt(0)
	v_mfma_f32_16x16x32_bf16 v[60:63], v[144:147], v[182:185], 0
	v_mfma_f32_16x16x32_bf16 v[56:59], v[152:155], v[182:185], 0
	v_mfma_f32_16x16x32_bf16 v[52:55], v[144:147], v[190:193], 0
	v_mfma_f32_16x16x32_bf16 v[44:47], v[152:155], v[190:193], 0
	v_mfma_f32_16x16x32_bf16 v[36:39], v[144:147], v[198:201], 0
	v_mfma_f32_16x16x32_bf16 v[28:31], v[152:155], v[198:201], 0
	v_mfma_f32_16x16x32_bf16 v[20:23], v[144:147], v[206:209], 0
	v_mfma_f32_16x16x32_bf16 v[12:15], v[152:155], v[206:209], 0
	v_mfma_f32_16x16x32_bf16 v[60:63], v[148:151], v[186:189], v[60:63]
	v_mfma_f32_16x16x32_bf16 v[56:59], v[156:159], v[186:189], v[56:59]
	v_mfma_f32_16x16x32_bf16 v[52:55], v[148:151], v[194:197], v[52:55]
	v_mfma_f32_16x16x32_bf16 v[44:47], v[156:159], v[194:197], v[44:47]
	v_mfma_f32_16x16x32_bf16 v[36:39], v[148:151], v[202:205], v[36:39]
	v_mfma_f32_16x16x32_bf16 v[28:31], v[156:159], v[202:205], v[28:31]
	v_mfma_f32_16x16x32_bf16 v[20:23], v[148:151], v[210:213], v[20:23]
	v_mfma_f32_16x16x32_bf16 v[12:15], v[156:159], v[210:213], v[12:15]
	s_setprio 0
	s_setprio 1
	v_mfma_f32_16x16x32_bf16 v[48:51], v[160:163], v[182:185], 0
	v_mfma_f32_16x16x32_bf16 v[40:43], v[168:171], v[182:185], 0
	v_mfma_f32_16x16x32_bf16 v[32:35], v[160:163], v[190:193], 0
	v_mfma_f32_16x16x32_bf16 v[24:27], v[168:171], v[190:193], 0
	v_mfma_f32_16x16x32_bf16 v[16:19], v[160:163], v[198:201], 0
	v_mfma_f32_16x16x32_bf16 v[8:11], v[168:171], v[198:201], 0
	v_mfma_f32_16x16x32_bf16 v[4:7], v[160:163], v[206:209], 0
	v_mfma_f32_16x16x32_bf16 v[0:3], v[168:171], v[206:209], 0
	v_mfma_f32_16x16x32_bf16 v[48:51], v[164:167], v[186:189], v[48:51]
	v_mfma_f32_16x16x32_bf16 v[40:43], v[172:175], v[186:189], v[40:43]
	v_mfma_f32_16x16x32_bf16 v[32:35], v[164:167], v[194:197], v[32:35]
	v_mfma_f32_16x16x32_bf16 v[24:27], v[172:175], v[194:197], v[24:27]
	v_mfma_f32_16x16x32_bf16 v[16:19], v[164:167], v[202:205], v[16:19]
	v_mfma_f32_16x16x32_bf16 v[8:11], v[172:175], v[202:205], v[8:11]
	v_mfma_f32_16x16x32_bf16 v[4:7], v[164:167], v[210:213], v[4:7]
	v_mfma_f32_16x16x32_bf16 v[0:3], v[172:175], v[210:213], v[0:3]
	s_setprio 0
	s_barrier
	s_add_i32 s28, 0, 0x18000
	s_add_i32 s48, 0, 0x1c000
	v_add_u32_e32 v156, s28, v142
	v_add_u32_e32 v172, s48, v142
	ds_read_b128 v[144:147], v156
	ds_read_b128 v[148:151], v156 offset:1024
	ds_read_b128 v[152:155], v156 offset:2048
	ds_read_b128 v[156:159], v156 offset:3072
	ds_read_b128 v[160:163], v172
	ds_read_b128 v[164:167], v172 offset:1024
	ds_read_b128 v[168:171], v172 offset:2048
	ds_read_b128 v[172:175], v172 offset:3072
	s_add_u32 s38, s64, 0x40000
	s_addc_u32 s39, s65, 0
	s_mov_b32 m0, s31
	v_lshl_add_u64 v[220:221], s[38:39], 0, v[132:133]
	ds_read_b128 v[182:185], v143 offset:32768
	ds_read_b128 v[186:189], v143 offset:33792
	ds_read_b128 v[190:193], v143 offset:34816
	ds_read_b128 v[194:197], v143 offset:35840
	ds_read_b128 v[198:201], v143 offset:36864
	ds_read_b128 v[202:205], v143 offset:37888
	ds_read_b128 v[206:209], v143 offset:38912
	ds_read_b128 v[210:213], v143 offset:39936
	global_load_lds_dwordx4 v[220:221], off
	v_lshl_add_u64 v[220:221], s[38:39], 0, v[130:131]
	s_mov_b32 m0, s42
	s_nop 0
	global_load_lds_dwordx4 v[220:221], off
	s_waitcnt vmcnt(8)
	s_waitcnt lgkmcnt(0)
	s_barrier
	s_setprio 1
	s_waitcnt lgkmcnt(0)
	v_mfma_f32_16x16x32_bf16 v[124:127], v[144:147], v[182:185], v[124:127]
	v_mfma_f32_16x16x32_bf16 v[120:123], v[152:155], v[182:185], v[120:123]
	v_mfma_f32_16x16x32_bf16 v[116:119], v[144:147], v[190:193], v[116:119]
	v_mfma_f32_16x16x32_bf16 v[108:111], v[152:155], v[190:193], v[108:111]
	v_mfma_f32_16x16x32_bf16 v[100:103], v[144:147], v[198:201], v[100:103]
	v_mfma_f32_16x16x32_bf16 v[92:95], v[152:155], v[198:201], v[92:95]
	v_mfma_f32_16x16x32_bf16 v[84:87], v[144:147], v[206:209], v[84:87]
	v_mfma_f32_16x16x32_bf16 v[76:79], v[152:155], v[206:209], v[76:79]
	v_mfma_f32_16x16x32_bf16 v[124:127], v[148:151], v[186:189], v[124:127]
	v_mfma_f32_16x16x32_bf16 v[120:123], v[156:159], v[186:189], v[120:123]
	v_mfma_f32_16x16x32_bf16 v[116:119], v[148:151], v[194:197], v[116:119]
	v_mfma_f32_16x16x32_bf16 v[108:111], v[156:159], v[194:197], v[108:111]
	v_mfma_f32_16x16x32_bf16 v[100:103], v[148:151], v[202:205], v[100:103]
	v_mfma_f32_16x16x32_bf16 v[92:95], v[156:159], v[202:205], v[92:95]
	v_mfma_f32_16x16x32_bf16 v[84:87], v[148:151], v[210:213], v[84:87]
	v_mfma_f32_16x16x32_bf16 v[76:79], v[156:159], v[210:213], v[76:79]
	s_setprio 0
	s_setprio 1
	v_mfma_f32_16x16x32_bf16 v[112:115], v[160:163], v[182:185], v[112:115]
	v_mfma_f32_16x16x32_bf16 v[104:107], v[168:171], v[182:185], v[104:107]
	v_mfma_f32_16x16x32_bf16 v[96:99], v[160:163], v[190:193], v[96:99]
	v_mfma_f32_16x16x32_bf16 v[88:91], v[168:171], v[190:193], v[88:91]
	v_mfma_f32_16x16x32_bf16 v[80:83], v[160:163], v[198:201], v[80:83]
	v_mfma_f32_16x16x32_bf16 v[72:75], v[168:171], v[198:201], v[72:75]
	v_mfma_f32_16x16x32_bf16 v[68:71], v[160:163], v[206:209], v[68:71]
	v_mfma_f32_16x16x32_bf16 v[64:67], v[168:171], v[206:209], v[64:67]
	v_mfma_f32_16x16x32_bf16 v[112:115], v[164:167], v[186:189], v[112:115]
	v_mfma_f32_16x16x32_bf16 v[104:107], v[172:175], v[186:189], v[104:107]
	v_mfma_f32_16x16x32_bf16 v[96:99], v[164:167], v[194:197], v[96:99]
	v_mfma_f32_16x16x32_bf16 v[88:91], v[172:175], v[194:197], v[88:91]
	v_mfma_f32_16x16x32_bf16 v[80:83], v[164:167], v[202:205], v[80:83]
	v_mfma_f32_16x16x32_bf16 v[72:75], v[172:175], v[202:205], v[72:75]
	v_mfma_f32_16x16x32_bf16 v[68:71], v[164:167], v[210:213], v[68:71]
	v_mfma_f32_16x16x32_bf16 v[64:67], v[172:175], v[210:213], v[64:67]
	s_setprio 0
	s_barrier
; #define PG8_STAGE(bufoff, gbase, voff) do { _Pragma("unroll") for (int _i = 0; _i < 2; ++_i) \
;         __builtin_amdgcn_global_load_lds((const unsigned*)((const char*)(gbase) + (voff)[_i]), (PG8_LAS unsigned*)(lds + (bufoff) + ldsw + _i * 8192), 16, 0, 0); } while (0)
; #define PG8_LDA(dst, b, h) do { _Pragma("unroll") for (int m = 0; m < 4; ++m) _Pragma("unroll") for (int k = 0; k < 2; ++k) dst[m][k] = *(const PG8_LAS bf16x8*)(lds + PG8_SA(b, h) + aoff + m * 2048 + k * 1024); } while (0)
; #define PG8_MMA(ai, bj, At, Bt) do { __builtin_amdgcn_s_setprio(1); _Pragma("unroll") for (int m = 0; m < 4; ++m) _Pragma("unroll") for (int n = 0; n < 2; ++n) _Pragma("unroll") for (int k = 0; k < 2; ++k) \
;         acc[ai][bj][m][n] = __builtin_amdgcn_mfma_f32_16x16x32_bf16(Bt[n][k], At[m][k], acc[ai][bj][m][n], 0, 0, 0); __builtin_amdgcn_s_setprio(0); } while (0)
; #define PG8_WAIT_V(n) asm volatile("s_waitcnt vmcnt(" #n ")" ::: "memory")
; #define PG8_WAIT_L(n) asm volatile("s_waitcnt lgkmcnt(" #n ")" ::: "memory")
; #define PG8_BAR __builtin_amdgcn_s_barrier()
; #define PG8_SCHED __builtin_amdgcn_sched_barrier(0)
; template <class Epi, class Sched, bool ALIGN_EPI = false, bool SP2 = false>
; __device__ __forceinline__ void gemm_phase(PG8_LAS unsigned char* lds, const Gemm g, const Sched& S, const Epi& E) {
;     ...
;         for (int t = 0; t < nt; t += 2) {
;             const bool last = (t == nt - 2);
;             const char* a1 = cA + (size_t)(t + 1) * kstep;
;             const char* a2 = last ? nA : cA + (size_t)(t + 2) * kstep; const char* b2 = last ? nB : cB + (size_t)(t + 2) * kstep;
;     ...
;             PG8_LDA(At, 1, 1); PG8_STAGE(PG8_SB(1, 0), b3, voffB); PG8_STAGE(PG8_SB(1, 1), b3 + hstep, voffB); PG8_STAGE(PG8_SA(1, 0), a3, voffA);
;             PG8_WAIT_V(8); PG8_WAIT_L(0); PG8_BAR; PG8_MMA(1, 0, At, B0); PG8_MMA(1, 1, At, B1); PG8_BAR; PG8_SCHED;
	s_add_i32 s28, s28, s24
	v_lshl_add_u64 v[138:139], v[138:139], 0, s[44:45]
	s_mov_b32 m0, s28
	ds_read_b128 v[182:185], v143 offset:49152
	ds_read_b128 v[186:189], v143 offset:50176
	ds_read_b128 v[190:193], v143 offset:51200
	ds_read_b128 v[194:197], v143 offset:52224
	ds_read_b128 v[198:201], v143 offset:53248
	ds_read_b128 v[202:205], v143 offset:54272
	ds_read_b128 v[206:209], v143 offset:55296
	ds_read_b128 v[210:213], v143 offset:56320
	global_load_lds_dwordx4 v[138:139], off
	s_add_i32 m0, s28, 0x2000
	s_add_u32 s4, s4, 0x40080
	v_lshl_add_u64 v[138:139], v[214:215], 0, s[44:45]
	s_addc_u32 s5, s5, 0
	s_add_i32 s28, s48, s24
	global_load_lds_dwordx4 v[138:139], off
	v_lshl_add_u64 v[138:139], s[4:5], 0, v[176:177]
	s_mov_b32 m0, s28
	s_nop 0
	global_load_lds_dwordx4 v[138:139], off
	v_lshl_add_u64 v[138:139], s[4:5], 0, v[128:129]
	s_add_i32 m0, s28, 0x2000
	s_nop 0
	global_load_lds_dwordx4 v[138:139], off
	v_lshl_add_u64 v[138:139], v[216:217], 0, s[44:45]
	s_mov_b32 m0, s63
	s_nop 0
	global_load_lds_dwordx4 v[138:139], off
	v_lshl_add_u64 v[138:139], v[218:219], 0, s[44:45]
	s_mov_b32 m0, s66
	s_nop 0
	global_load_lds_dwordx4 v[138:139], off
	s_waitcnt vmcnt(8)
	s_waitcnt lgkmcnt(0)
	s_barrier
	s_setprio 1
	s_waitcnt lgkmcnt(0)
	v_mfma_f32_16x16x32_bf16 v[60:63], v[144:147], v[182:185], v[60:63]
	v_mfma_f32_16x16x32_bf16 v[56:59], v[152:155], v[182:185], v[56:59]
	v_mfma_f32_16x16x32_bf16 v[52:55], v[144:147], v[190:193], v[52:55]
	v_mfma_f32_16x16x32_bf16 v[44:47], v[152:155], v[190:193], v[44:47]
	v_mfma_f32_16x16x32_bf16 v[36:39], v[144:147], v[198:201], v[36:39]
	v_mfma_f32_16x16x32_bf16 v[28:31], v[152:155], v[198:201], v[28:31]
	v_mfma_f32_16x16x32_bf16 v[20:23], v[144:147], v[206:209], v[20:23]
	v_mfma_f32_16x16x32_bf16 v[12:15], v[152:155], v[206:209], v[12:15]
	v_mfma_f32_16x16x32_bf16 v[60:63], v[148:151], v[186:189], v[60:63]
	v_mfma_f32_16x16x32_bf16 v[56:59], v[156:159], v[186:189], v[56:59]
	v_mfma_f32_16x16x32_bf16 v[52:55], v[148:151], v[194:197], v[52:55]
	v_mfma_f32_16x16x32_bf16 v[44:47], v[156:159], v[194:197], v[44:47]
	v_mfma_f32_16x16x32_bf16 v[36:39], v[148:151], v[202:205], v[36:39]
	v_mfma_f32_16x16x32_bf16 v[28:31], v[156:159], v[202:205], v[28:31]
	v_mfma_f32_16x16x32_bf16 v[20:23], v[148:151], v[210:213], v[20:23]
	v_mfma_f32_16x16x32_bf16 v[12:15], v[156:159], v[210:213], v[12:15]
	s_setprio 0
	s_setprio 1
	v_mfma_f32_16x16x32_bf16 v[48:51], v[160:163], v[182:185], v[48:51]
	v_mfma_f32_16x16x32_bf16 v[40:43], v[168:171], v[182:185], v[40:43]
	v_mfma_f32_16x16x32_bf16 v[32:35], v[160:163], v[190:193], v[32:35]
	v_mfma_f32_16x16x32_bf16 v[24:27], v[168:171], v[190:193], v[24:27]
	v_mfma_f32_16x16x32_bf16 v[16:19], v[160:163], v[198:201], v[16:19]
	v_mfma_f32_16x16x32_bf16 v[8:11], v[168:171], v[198:201], v[8:11]
	v_mfma_f32_16x16x32_bf16 v[4:7], v[160:163], v[206:209], v[4:7]
	v_mfma_f32_16x16x32_bf16 v[0:3], v[168:171], v[206:209], v[0:3]
	v_mfma_f32_16x16x32_bf16 v[48:51], v[164:167], v[186:189], v[48:51]
	v_mfma_f32_16x16x32_bf16 v[40:43], v[172:175], v[186:189], v[40:43]
	s_add_i32 s72, s72, 2
	v_mfma_f32_16x16x32_bf16 v[32:35], v[164:167], v[194:197], v[32:35]
	s_add_u32 s40, s40, 0x100
	v_mfma_f32_16x16x32_bf16 v[24:27], v[172:175], v[194:197], v[24:27]
	s_addc_u32 s41, s41, 0
	v_mfma_f32_16x16x32_bf16 v[16:19], v[164:167], v[202:205], v[16:19]
	s_add_u32 s70, s70, 0x100
	v_mfma_f32_16x16x32_bf16 v[8:11], v[172:175], v[202:205], v[8:11]
	s_addc_u32 s71, s71, 0
	v_mfma_f32_16x16x32_bf16 v[4:7], v[164:167], v[210:213], v[4:7]
	s_cmp_gt_u32 s72, 13
	v_mfma_f32_16x16x32_bf16 v[0:3], v[172:175], v[210:213], v[0:3]
	s_setprio 0
	s_barrier
	s_cbranch_scc0 .LBB0_570
	s_branch .Lg2_post

; #define PG8_STAGE(bufoff, gbase, voff) do { _Pragma("unroll") for (int _i = 0; _i < 2; ++_i) \
;         __builtin_amdgcn_global_load_lds((const unsigned*)((const char*)(gbase) + (voff)[_i]), (PG8_LAS unsigned*)(lds + (bufoff) + ldsw + _i * 8192), 16, 0, 0); } while (0)
; #define PG8_LDA(dst, b, h) do { _Pragma("unroll") for (int m = 0; m < 4; ++m) _Pragma("unroll") for (int k = 0; k < 2; ++k) dst[m][k] = *(const PG8_LAS bf16x8*)(lds + PG8_SA(b, h) + aoff + m * 2048 + k * 1024); } while (0)
; #define PG8_LDB(dst, b, h) do { _Pragma("unroll") for (int n = 0; n < 2; ++n) _Pragma("unroll") for (int k = 0; k < 2; ++k) dst[n][k] = *(const PG8_LAS bf16x8*)(lds + PG8_SB(b, h) + boff + n * 2048 + k * 1024); } while (0)
; #define PG8_MMA(ai, bj, At, Bt) do { __builtin_amdgcn_s_setprio(1); _Pragma("unroll") for (int m = 0; m < 4; ++m) _Pragma("unroll") for (int n = 0; n < 2; ++n) _Pragma("unroll") for (int k = 0; k < 2; ++k) \
;         acc[ai][bj][m][n] = __builtin_amdgcn_mfma_f32_16x16x32_bf16(Bt[n][k], At[m][k], acc[ai][bj][m][n], 0, 0, 0); __builtin_amdgcn_s_setprio(0); } while (0)
; #define PG8_WAIT_V(n) asm volatile("s_waitcnt vmcnt(" #n ")" ::: "memory")
; #define PG8_BAR __builtin_amdgcn_s_barrier()
; template <class Epi, class Sched, bool ALIGN_EPI = false, bool SP2 = false>
; __device__ __forceinline__ void gemm_phase(PG8_LAS unsigned char* lds, const Gemm g, const Sched& S, const Epi& E) {
;     ...
;         for (int t = 0; t < nt; t += 2) {
;             const bool last = (t == nt - 2);
;             const char* a1 = cA + (size_t)(t + 1) * kstep;
;             const char* a2 = last ? nA : cA + (size_t)(t + 2) * kstep; const char* b2 = last ? nB : cB + (size_t)(t + 2) * kstep;
;             const char* a3 = a2 + kstep; const char* b3 = b2 + kstep;
;             if (last && has_next) S.a_ready(nxt);
;             if constexpr (SP2) {
;             PG8_LDB(B0, 0, 0); PG8_LDB(B1, 0, 1); PG8_SCHED; PG8_LDA(At, 0, 0); PG8_STAGE(PG8_SA(1, 1), a1 + hstep, voffA);
;             PG8_WAIT_V(8); PG8_WAIT_L(0); PG8_BAR; PG8_MMA(0, 0, At, B0); PG8_MMA(0, 1, At, B1); PG8_BAR; PG8_SCHED;
;             PG8_LDA(At, 0, 1); PG8_STAGE(PG8_SB(0, 0), b2, voffB); PG8_STAGE(PG8_SB(0, 1), b2 + hstep, voffB); PG8_STAGE(PG8_SA(0, 0), a2, voffA);
;             PG8_WAIT_V(8); PG8_WAIT_L(0); PG8_BAR; PG8_MMA(1, 0, At, B0); PG8_MMA(1, 1, At, B1); PG8_BAR; PG8_SCHED;
.LBB0_592:
	s_add_i32 s81, s4, 2
	s_add_u32 s28, s66, 0x80
	s_addc_u32 s5, s67, 0
	s_add_i32 s48, 0, 0x10000
	s_cmp_eq_u32 s70, s4
	s_cselect_b32 s5, s41, s5
	s_cselect_b32 s4, s40, s28
	s_cselect_b32 s39, s65, s69
	s_cselect_b32 s38, s64, s68
	s_add_i32 s28, 0, 0x14000
	v_add_u32_e32 v154, s48, v140
	v_add_u32_e32 v170, s28, v140
	ds_read_b128 v[142:145], v154
	ds_read_b128 v[146:149], v154 offset:1024
	ds_read_b128 v[150:153], v154 offset:2048
	ds_read_b128 v[154:157], v154 offset:3072
	ds_read_b128 v[158:161], v170
	ds_read_b128 v[162:165], v170 offset:1024
	ds_read_b128 v[166:169], v170 offset:2048
	ds_read_b128 v[170:173], v170 offset:3072
	v_lshl_add_u64 v[174:175], s[66:67], 0, v[134:135]
	s_add_i32 m0, s19, 0xc000
	ds_read_b128 v[182:185], v141
	ds_read_b128 v[186:189], v141 offset:1024
	ds_read_b128 v[190:193], v141 offset:2048
	ds_read_b128 v[194:197], v141 offset:3072
	ds_read_b128 v[198:201], v141 offset:4096
	ds_read_b128 v[202:205], v141 offset:5120
	ds_read_b128 v[206:209], v141 offset:6144
	ds_read_b128 v[210:213], v141 offset:7168
	global_load_lds_dwordx4 v[174:175], off
	v_lshl_add_u64 v[174:175], s[66:67], 0, v[136:137]
	s_add_i32 m0, s19, 0xe000
	s_nop 0
	global_load_lds_dwordx4 v[174:175], off
	s_waitcnt vmcnt(8)
	s_waitcnt lgkmcnt(0)
	s_barrier
	s_setprio 1
	s_waitcnt lgkmcnt(0)
	v_mfma_f32_16x16x32_bf16 v[124:127], v[142:145], v[182:185], v[124:127]
	v_mfma_f32_16x16x32_bf16 v[120:123], v[150:153], v[182:185], v[120:123]
	v_mfma_f32_16x16x32_bf16 v[108:111], v[142:145], v[190:193], v[108:111]
	v_mfma_f32_16x16x32_bf16 v[104:107], v[150:153], v[190:193], v[104:107]
	v_mfma_f32_16x16x32_bf16 v[92:95], v[142:145], v[198:201], v[92:95]
	v_mfma_f32_16x16x32_bf16 v[88:91], v[150:153], v[198:201], v[88:91]
	v_mfma_f32_16x16x32_bf16 v[76:79], v[142:145], v[206:209], v[76:79]
	v_mfma_f32_16x16x32_bf16 v[72:75], v[150:153], v[206:209], v[72:75]
	v_mfma_f32_16x16x32_bf16 v[124:127], v[146:149], v[186:189], v[124:127]
	v_mfma_f32_16x16x32_bf16 v[120:123], v[154:157], v[186:189], v[120:123]
	v_mfma_f32_16x16x32_bf16 v[108:111], v[146:149], v[194:197], v[108:111]
	v_mfma_f32_16x16x32_bf16 v[104:107], v[154:157], v[194:197], v[104:107]
	v_mfma_f32_16x16x32_bf16 v[92:95], v[146:149], v[202:205], v[92:95]
	v_mfma_f32_16x16x32_bf16 v[88:91], v[154:157], v[202:205], v[88:91]
	v_mfma_f32_16x16x32_bf16 v[76:79], v[146:149], v[210:213], v[76:79]
	v_mfma_f32_16x16x32_bf16 v[72:75], v[154:157], v[210:213], v[72:75]
	s_setprio 0
	s_setprio 1
	v_mfma_f32_16x16x32_bf16 v[116:119], v[158:161], v[182:185], v[116:119]
	v_mfma_f32_16x16x32_bf16 v[112:115], v[166:169], v[182:185], v[112:115]
	v_mfma_f32_16x16x32_bf16 v[100:103], v[158:161], v[190:193], v[100:103]
	v_mfma_f32_16x16x32_bf16 v[96:99], v[166:169], v[190:193], v[96:99]
	v_mfma_f32_16x16x32_bf16 v[84:87], v[158:161], v[198:201], v[84:87]
	v_mfma_f32_16x16x32_bf16 v[80:83], v[166:169], v[198:201], v[80:83]
	v_mfma_f32_16x16x32_bf16 v[68:71], v[158:161], v[206:209], v[68:71]
	v_mfma_f32_16x16x32_bf16 v[64:67], v[166:169], v[206:209], v[64:67]
	v_mfma_f32_16x16x32_bf16 v[116:119], v[162:165], v[186:189], v[116:119]
	v_mfma_f32_16x16x32_bf16 v[112:115], v[170:173], v[186:189], v[112:115]
	v_mfma_f32_16x16x32_bf16 v[100:103], v[162:165], v[194:197], v[100:103]
	v_mfma_f32_16x16x32_bf16 v[96:99], v[170:173], v[194:197], v[96:99]
	v_mfma_f32_16x16x32_bf16 v[84:87], v[162:165], v[202:205], v[84:87]
	v_mfma_f32_16x16x32_bf16 v[80:83], v[170:173], v[202:205], v[80:83]
	v_mfma_f32_16x16x32_bf16 v[68:71], v[162:165], v[210:213], v[68:71]
	v_mfma_f32_16x16x32_bf16 v[64:67], v[170:173], v[210:213], v[64:67]
	s_setprio 0
	s_barrier
	s_add_i32 s48, s48, s18
	v_lshl_add_u64 v[174:175], s[38:39], 0, v[176:177]
	s_mov_b32 m0, s48
	ds_read_b128 v[182:185], v141 offset:16384
	ds_read_b128 v[186:189], v141 offset:17408
	ds_read_b128 v[190:193], v141 offset:18432
	ds_read_b128 v[194:197], v141 offset:19456
	ds_read_b128 v[198:201], v141 offset:20480
	ds_read_b128 v[202:205], v141 offset:21504
	ds_read_b128 v[206:209], v141 offset:22528
	ds_read_b128 v[210:213], v141 offset:23552
	global_load_lds_dwordx4 v[174:175], off
	s_add_i32 m0, s48, 0x2000
	v_lshl_add_u64 v[214:215], s[38:39], 0, v[128:129]
	s_add_u32 s38, s38, s0
	s_addc_u32 s39, s39, s1
	s_add_i32 s28, s28, s18
	global_load_lds_dwordx4 v[214:215], off
	v_lshl_add_u64 v[216:217], s[38:39], 0, v[176:177]
	s_mov_b32 m0, s28
	v_lshl_add_u64 v[218:219], s[38:39], 0, v[128:129]
	global_load_lds_dwordx4 v[216:217], off
	s_add_i32 m0, s28, 0x2000
	v_lshl_add_u64 v[220:221], s[4:5], 0, v[132:133]
	global_load_lds_dwordx4 v[218:219], off
	s_mov_b32 m0, s19
	v_lshl_add_u64 v[222:223], s[4:5], 0, v[130:131]
	global_load_lds_dwordx4 v[220:221], off
	s_mov_b32 m0, s24
	s_nop 0
	global_load_lds_dwordx4 v[222:223], off
	s_waitcnt vmcnt(8)
	s_waitcnt lgkmcnt(0)
	s_barrier
; #define PG8_STAGE(bufoff, gbase, voff) do { _Pragma("unroll") for (int _i = 0; _i < 2; ++_i) \
;         __builtin_amdgcn_global_load_lds((const unsigned*)((const char*)(gbase) + (voff)[_i]), (PG8_LAS unsigned*)(lds + (bufoff) + ldsw + _i * 8192), 16, 0, 0); } while (0)
; #define PG8_LDA(dst, b, h) do { _Pragma("unroll") for (int m = 0; m < 4; ++m) _Pragma("unroll") for (int k = 0; k < 2; ++k) dst[m][k] = *(const PG8_LAS bf16x8*)(lds + PG8_SA(b, h) + aoff + m * 2048 + k * 1024); } while (0)
; #define PG8_LDB(dst, b, h) do { _Pragma("unroll") for (int n = 0; n < 2; ++n) _Pragma("unroll") for (int k = 0; k < 2; ++k) dst[n][k] = *(const PG8_LAS bf16x8*)(lds + PG8_SB(b, h) + boff + n * 2048 + k * 1024); } while (0)
; #define PG8_MMA(ai, bj, At, Bt) do { __builtin_amdgcn_s_setprio(1); _Pragma("unroll") for (int m = 0; m < 4; ++m) _Pragma("unroll") for (int n = 0; n < 2; ++n) _Pragma("unroll") for (int k = 0; k < 2; ++k) \
;         acc[ai][bj][m][n] = __builtin_amdgcn_mfma_f32_16x16x32_bf16(Bt[n][k], At[m][k], acc[ai][bj][m][n], 0, 0, 0); __builtin_amdgcn_s_setprio(0); } while (0)
; #define PG8_WAIT_V(n) asm volatile("s_waitcnt vmcnt(" #n ")" ::: "memory")
; #define PG8_WAIT_L(n) asm volatile("s_waitcnt lgkmcnt(" #n ")" ::: "memory")
; #define PG8_BAR __builtin_amdgcn_s_barrier()
; #define PG8_SCHED __builtin_amdgcn_sched_barrier(0)
; template <class Epi, class Sched, bool ALIGN_EPI = false, bool SP2 = false>
; __device__ __forceinline__ void gemm_phase(PG8_LAS unsigned char* lds, const Gemm g, const Sched& S, const Epi& E) {
;     ...
;             PG8_WAIT_V(8); PG8_WAIT_L(0); PG8_BAR; PG8_MMA(1, 0, At, B0); PG8_MMA(1, 1, At, B1); PG8_BAR; PG8_SCHED;
;             PG8_LDB(B0, 1, 0); PG8_LDB(B1, 1, 1); PG8_SCHED; PG8_LDA(At, 1, 0); PG8_STAGE(PG8_SA(0, 1), a2 + hstep, voffA);
;             PG8_WAIT_V(8); PG8_WAIT_L(0); PG8_BAR; PG8_MMA(0, 0, At, B0); PG8_MMA(0, 1, At, B1); PG8_BAR; PG8_SCHED;
	s_setprio 1
	s_waitcnt lgkmcnt(0)
	v_mfma_f32_16x16x32_bf16 v[60:63], v[142:145], v[182:185], v[60:63]
	v_mfma_f32_16x16x32_bf16 v[56:59], v[150:153], v[182:185], v[56:59]
	v_mfma_f32_16x16x32_bf16 v[44:47], v[142:145], v[190:193], v[44:47]
	v_mfma_f32_16x16x32_bf16 v[40:43], v[150:153], v[190:193], v[40:43]
	v_mfma_f32_16x16x32_bf16 v[28:31], v[142:145], v[198:201], v[28:31]
	v_mfma_f32_16x16x32_bf16 v[24:27], v[150:153], v[198:201], v[24:27]
	v_mfma_f32_16x16x32_bf16 v[12:15], v[142:145], v[206:209], v[12:15]
	v_mfma_f32_16x16x32_bf16 v[8:11], v[150:153], v[206:209], v[8:11]
	v_mfma_f32_16x16x32_bf16 v[60:63], v[146:149], v[186:189], v[60:63]
	v_mfma_f32_16x16x32_bf16 v[56:59], v[154:157], v[186:189], v[56:59]
	v_mfma_f32_16x16x32_bf16 v[44:47], v[146:149], v[194:197], v[44:47]
	v_mfma_f32_16x16x32_bf16 v[40:43], v[154:157], v[194:197], v[40:43]
	v_mfma_f32_16x16x32_bf16 v[28:31], v[146:149], v[202:205], v[28:31]
	v_mfma_f32_16x16x32_bf16 v[24:27], v[154:157], v[202:205], v[24:27]
	v_mfma_f32_16x16x32_bf16 v[12:15], v[146:149], v[210:213], v[12:15]
	v_mfma_f32_16x16x32_bf16 v[8:11], v[154:157], v[210:213], v[8:11]
	s_setprio 0
	s_setprio 1
	v_mfma_f32_16x16x32_bf16 v[52:55], v[158:161], v[182:185], v[52:55]
	v_mfma_f32_16x16x32_bf16 v[48:51], v[166:169], v[182:185], v[48:51]
	v_mfma_f32_16x16x32_bf16 v[36:39], v[158:161], v[190:193], v[36:39]
	v_mfma_f32_16x16x32_bf16 v[32:35], v[166:169], v[190:193], v[32:35]
	v_mfma_f32_16x16x32_bf16 v[20:23], v[158:161], v[198:201], v[20:23]
	v_mfma_f32_16x16x32_bf16 v[16:19], v[166:169], v[198:201], v[16:19]
	v_mfma_f32_16x16x32_bf16 v[4:7], v[158:161], v[206:209], v[4:7]
	v_mfma_f32_16x16x32_bf16 v[0:3], v[166:169], v[206:209], v[0:3]
	v_mfma_f32_16x16x32_bf16 v[52:55], v[162:165], v[186:189], v[52:55]
	v_mfma_f32_16x16x32_bf16 v[48:51], v[170:173], v[186:189], v[48:51]
	v_mfma_f32_16x16x32_bf16 v[36:39], v[162:165], v[194:197], v[36:39]
	v_mfma_f32_16x16x32_bf16 v[32:35], v[170:173], v[194:197], v[32:35]
	v_mfma_f32_16x16x32_bf16 v[20:23], v[162:165], v[202:205], v[20:23]
	v_mfma_f32_16x16x32_bf16 v[16:19], v[170:173], v[202:205], v[16:19]
	v_mfma_f32_16x16x32_bf16 v[4:7], v[162:165], v[210:213], v[4:7]
	v_mfma_f32_16x16x32_bf16 v[0:3], v[170:173], v[210:213], v[0:3]
	s_setprio 0
	s_barrier
	s_add_i32 s28, 0, 0x18000
	s_add_i32 s38, 0, 0x1c000
	v_add_u32_e32 v154, s28, v140
	v_add_u32_e32 v170, s38, v140
	ds_read_b128 v[142:145], v154
	ds_read_b128 v[146:149], v154 offset:1024
	ds_read_b128 v[150:153], v154 offset:2048
	ds_read_b128 v[154:157], v154 offset:3072
	ds_read_b128 v[158:161], v170
	ds_read_b128 v[162:165], v170 offset:1024
	ds_read_b128 v[166:169], v170 offset:2048
	ds_read_b128 v[170:173], v170 offset:3072
	s_add_u32 s4, s4, s0
	s_addc_u32 s5, s5, s1
	s_mov_b32 m0, s25
	v_lshl_add_u64 v[224:225], s[4:5], 0, v[132:133]
	ds_read_b128 v[182:185], v141 offset:32768
	ds_read_b128 v[186:189], v141 offset:33792
	ds_read_b128 v[190:193], v141 offset:34816
	ds_read_b128 v[194:197], v141 offset:35840
	ds_read_b128 v[198:201], v141 offset:36864
	ds_read_b128 v[202:205], v141 offset:37888
	ds_read_b128 v[206:209], v141 offset:38912
	ds_read_b128 v[210:213], v141 offset:39936
	global_load_lds_dwordx4 v[224:225], off
	v_lshl_add_u64 v[224:225], s[4:5], 0, v[130:131]
	s_mov_b32 m0, s30
	s_nop 0
	global_load_lds_dwordx4 v[224:225], off
	s_waitcnt vmcnt(8)
	s_waitcnt lgkmcnt(0)
	s_barrier
	s_setprio 1
	s_waitcnt lgkmcnt(0)
	v_mfma_f32_16x16x32_bf16 v[124:127], v[142:145], v[182:185], v[124:127]
	v_mfma_f32_16x16x32_bf16 v[120:123], v[150:153], v[182:185], v[120:123]
	v_mfma_f32_16x16x32_bf16 v[108:111], v[142:145], v[190:193], v[108:111]
	v_mfma_f32_16x16x32_bf16 v[104:107], v[150:153], v[190:193], v[104:107]
	v_mfma_f32_16x16x32_bf16 v[92:95], v[142:145], v[198:201], v[92:95]
	v_mfma_f32_16x16x32_bf16 v[88:91], v[150:153], v[198:201], v[88:91]
	v_mfma_f32_16x16x32_bf16 v[76:79], v[142:145], v[206:209], v[76:79]
	v_mfma_f32_16x16x32_bf16 v[72:75], v[150:153], v[206:209], v[72:75]
	v_mfma_f32_16x16x32_bf16 v[124:127], v[146:149], v[186:189], v[124:127]
	v_mfma_f32_16x16x32_bf16 v[120:123], v[154:157], v[186:189], v[120:123]
	v_mfma_f32_16x16x32_bf16 v[108:111], v[146:149], v[194:197], v[108:111]
	v_mfma_f32_16x16x32_bf16 v[104:107], v[154:157], v[194:197], v[104:107]
	v_mfma_f32_16x16x32_bf16 v[92:95], v[146:149], v[202:205], v[92:95]
	v_mfma_f32_16x16x32_bf16 v[88:91], v[154:157], v[202:205], v[88:91]
	v_mfma_f32_16x16x32_bf16 v[76:79], v[146:149], v[210:213], v[76:79]
	v_mfma_f32_16x16x32_bf16 v[72:75], v[154:157], v[210:213], v[72:75]
	s_setprio 0
	s_setprio 1
	v_mfma_f32_16x16x32_bf16 v[116:119], v[158:161], v[182:185], v[116:119]
	v_mfma_f32_16x16x32_bf16 v[112:115], v[166:169], v[182:185], v[112:115]
	v_mfma_f32_16x16x32_bf16 v[100:103], v[158:161], v[190:193], v[100:103]
	v_mfma_f32_16x16x32_bf16 v[96:99], v[166:169], v[190:193], v[96:99]
	v_mfma_f32_16x16x32_bf16 v[84:87], v[158:161], v[198:201], v[84:87]
	v_mfma_f32_16x16x32_bf16 v[80:83], v[166:169], v[198:201], v[80:83]
	v_mfma_f32_16x16x32_bf16 v[68:71], v[158:161], v[206:209], v[68:71]
	v_mfma_f32_16x16x32_bf16 v[64:67], v[166:169], v[206:209], v[64:67]
	v_mfma_f32_16x16x32_bf16 v[116:119], v[162:165], v[186:189], v[116:119]
	v_mfma_f32_16x16x32_bf16 v[112:115], v[170:173], v[186:189], v[112:115]
	v_mfma_f32_16x16x32_bf16 v[100:103], v[162:165], v[194:197], v[100:103]
	v_mfma_f32_16x16x32_bf16 v[96:99], v[170:173], v[194:197], v[96:99]
	v_mfma_f32_16x16x32_bf16 v[84:87], v[162:165], v[202:205], v[84:87]
	v_mfma_f32_16x16x32_bf16 v[80:83], v[170:173], v[202:205], v[80:83]
	v_mfma_f32_16x16x32_bf16 v[68:71], v[162:165], v[210:213], v[68:71]
	v_mfma_f32_16x16x32_bf16 v[64:67], v[170:173], v[210:213], v[64:67]
	s_setprio 0
	s_barrier
; #define PG8_STAGE(bufoff, gbase, voff) do { _Pragma("unroll") for (int _i = 0; _i < 2; ++_i) \
;         __builtin_amdgcn_global_load_lds((const unsigned*)((const char*)(gbase) + (voff)[_i]), (PG8_LAS unsigned*)(lds + (bufoff) + ldsw + _i * 8192), 16, 0, 0); } while (0)
; #define PG8_LDA(dst, b, h) do { _Pragma("unroll") for (int m = 0; m < 4; ++m) _Pragma("unroll") for (int k = 0; k < 2; ++k) dst[m][k] = *(const PG8_LAS bf16x8*)(lds + PG8_SA(b, h) + aoff + m * 2048 + k * 1024); } while (0)
; #define PG8_MMA(ai, bj, At, Bt) do { __builtin_amdgcn_s_setprio(1); _Pragma("unroll") for (int m = 0; m < 4; ++m) _Pragma("unroll") for (int n = 0; n < 2; ++n) _Pragma("unroll") for (int k = 0; k < 2; ++k) \
;         acc[ai][bj][m][n] = __builtin_amdgcn_mfma_f32_16x16x32_bf16(Bt[n][k], At[m][k], acc[ai][bj][m][n], 0, 0, 0); __builtin_amdgcn_s_setprio(0); } while (0)
; #define PG8_WAIT_V(n) asm volatile("s_waitcnt vmcnt(" #n ")" ::: "memory")
; #define PG8_WAIT_L(n) asm volatile("s_waitcnt lgkmcnt(" #n ")" ::: "memory")
; #define PG8_BAR __builtin_amdgcn_s_barrier()
; #define PG8_SCHED __builtin_amdgcn_sched_barrier(0)
; template <class Epi, class Sched, bool ALIGN_EPI = false, bool SP2 = false>
; __device__ __forceinline__ void gemm_phase(PG8_LAS unsigned char* lds, const Gemm g, const Sched& S, const Epi& E) {
;     ...
;             PG8_LDA(At, 1, 1); PG8_STAGE(PG8_SB(1, 0), b3, voffB); PG8_STAGE(PG8_SB(1, 1), b3 + hstep, voffB); PG8_STAGE(PG8_SA(1, 0), a3, voffA);
;             PG8_WAIT_V(8); PG8_WAIT_L(0); PG8_BAR; PG8_MMA(1, 0, At, B0); PG8_MMA(1, 1, At, B1); PG8_BAR; PG8_SCHED;
	s_add_i32 s4, s28, s18
	v_lshl_add_u64 v[174:175], v[174:175], 0, s[44:45]
	s_mov_b32 m0, s4
	ds_read_b128 v[182:185], v141 offset:49152
	ds_read_b128 v[186:189], v141 offset:50176
	ds_read_b128 v[190:193], v141 offset:51200
	ds_read_b128 v[194:197], v141 offset:52224
	ds_read_b128 v[198:201], v141 offset:53248
	ds_read_b128 v[202:205], v141 offset:54272
	ds_read_b128 v[206:209], v141 offset:55296
	ds_read_b128 v[210:213], v141 offset:56320
	global_load_lds_dwordx4 v[174:175], off
	v_lshl_add_u64 v[174:175], v[214:215], 0, s[44:45]
	s_add_i32 m0, s4, 0x2000
	s_add_i32 s4, s38, s18
	global_load_lds_dwordx4 v[174:175], off
	v_lshl_add_u64 v[174:175], v[216:217], 0, s[44:45]
	s_mov_b32 m0, s4
	s_nop 0
	global_load_lds_dwordx4 v[174:175], off
	v_lshl_add_u64 v[174:175], v[218:219], 0, s[44:45]
	s_add_i32 m0, s4, 0x2000
	s_nop 0
	global_load_lds_dwordx4 v[174:175], off
	v_lshl_add_u64 v[174:175], v[220:221], 0, s[44:45]
	s_mov_b32 m0, s43
	s_nop 0
	global_load_lds_dwordx4 v[174:175], off
	v_lshl_add_u64 v[174:175], v[222:223], 0, s[44:45]
	s_mov_b32 m0, s46
	s_nop 0
	global_load_lds_dwordx4 v[174:175], off
	s_waitcnt vmcnt(8)
	s_waitcnt lgkmcnt(0)
	s_barrier
	s_setprio 1
	s_waitcnt lgkmcnt(0)
	v_mfma_f32_16x16x32_bf16 v[60:63], v[142:145], v[182:185], v[60:63]
	v_mfma_f32_16x16x32_bf16 v[56:59], v[150:153], v[182:185], v[56:59]
	v_mfma_f32_16x16x32_bf16 v[44:47], v[142:145], v[190:193], v[44:47]
	v_mfma_f32_16x16x32_bf16 v[40:43], v[150:153], v[190:193], v[40:43]
	v_mfma_f32_16x16x32_bf16 v[28:31], v[142:145], v[198:201], v[28:31]
	v_mfma_f32_16x16x32_bf16 v[24:27], v[150:153], v[198:201], v[24:27]
	v_mfma_f32_16x16x32_bf16 v[12:15], v[142:145], v[206:209], v[12:15]
	v_mfma_f32_16x16x32_bf16 v[8:11], v[150:153], v[206:209], v[8:11]
	v_mfma_f32_16x16x32_bf16 v[60:63], v[146:149], v[186:189], v[60:63]
	v_mfma_f32_16x16x32_bf16 v[56:59], v[154:157], v[186:189], v[56:59]
	v_mfma_f32_16x16x32_bf16 v[44:47], v[146:149], v[194:197], v[44:47]
	v_mfma_f32_16x16x32_bf16 v[40:43], v[154:157], v[194:197], v[40:43]
	v_mfma_f32_16x16x32_bf16 v[28:31], v[146:149], v[202:205], v[28:31]
	v_mfma_f32_16x16x32_bf16 v[24:27], v[154:157], v[202:205], v[24:27]
	v_mfma_f32_16x16x32_bf16 v[12:15], v[146:149], v[210:213], v[12:15]
	v_mfma_f32_16x16x32_bf16 v[8:11], v[154:157], v[210:213], v[8:11]
	s_setprio 0
	s_setprio 1
	v_mfma_f32_16x16x32_bf16 v[52:55], v[158:161], v[182:185], v[52:55]
	v_mfma_f32_16x16x32_bf16 v[48:51], v[166:169], v[182:185], v[48:51]
	v_mfma_f32_16x16x32_bf16 v[36:39], v[158:161], v[190:193], v[36:39]
	v_mfma_f32_16x16x32_bf16 v[32:35], v[166:169], v[190:193], v[32:35]
	v_mfma_f32_16x16x32_bf16 v[20:23], v[158:161], v[198:201], v[20:23]
	v_mfma_f32_16x16x32_bf16 v[16:19], v[166:169], v[198:201], v[16:19]
	v_mfma_f32_16x16x32_bf16 v[4:7], v[158:161], v[206:209], v[4:7]
	v_mfma_f32_16x16x32_bf16 v[0:3], v[166:169], v[206:209], v[0:3]
	v_mfma_f32_16x16x32_bf16 v[52:55], v[162:165], v[186:189], v[52:55]
	v_mfma_f32_16x16x32_bf16 v[48:51], v[170:173], v[186:189], v[48:51]
	s_add_u32 s66, s66, 0x100
	v_mfma_f32_16x16x32_bf16 v[36:39], v[162:165], v[194:197], v[36:39]
	s_addc_u32 s67, s67, 0
	v_mfma_f32_16x16x32_bf16 v[32:35], v[170:173], v[194:197], v[32:35]
	s_add_u32 s68, s68, 0x100
	v_mfma_f32_16x16x32_bf16 v[20:23], v[162:165], v[202:205], v[20:23]
	s_addc_u32 s69, s69, 0
	v_mfma_f32_16x16x32_bf16 v[16:19], v[170:173], v[202:205], v[16:19]
	s_cmp_ge_i32 s81, s31
	v_mfma_f32_16x16x32_bf16 v[4:7], v[162:165], v[210:213], v[4:7]
	s_mov_b32 s4, s81
	v_mfma_f32_16x16x32_bf16 v[0:3], v[170:173], v[210:213], v[0:3]
	s_setprio 0
	s_barrier
	s_cbranch_scc0 .LBB0_592

; #define PG8_STAGE(bufoff, gbase, voff) do { _Pragma("unroll") for (int _i = 0; _i < 2; ++_i) \
;         __builtin_amdgcn_global_load_lds((const unsigned*)((const char*)(gbase) + (voff)[_i]), (PG8_LAS unsigned*)(lds + (bufoff) + ldsw + _i * 8192), 16, 0, 0); } while (0)
; #define PG8_LDA(dst, b, h) do { _Pragma("unroll") for (int m = 0; m < 4; ++m) _Pragma("unroll") for (int k = 0; k < 2; ++k) dst[m][k] = *(const PG8_LAS bf16x8*)(lds + PG8_SA(b, h) + aoff + m * 2048 + k * 1024); } while (0)
; #define PG8_LDB(dst, b, h) do { _Pragma("unroll") for (int n = 0; n < 2; ++n) _Pragma("unroll") for (int k = 0; k < 2; ++k) dst[n][k] = *(const PG8_LAS bf16x8*)(lds + PG8_SB(b, h) + boff + n * 2048 + k * 1024); } while (0)
; #define PG8_MMA(ai, bj, At, Bt) do { __builtin_amdgcn_s_setprio(1); _Pragma("unroll") for (int m = 0; m < 4; ++m) _Pragma("unroll") for (int n = 0; n < 2; ++n) _Pragma("unroll") for (int k = 0; k < 2; ++k) \
;         acc[ai][bj][m][n] = __builtin_amdgcn_mfma_f32_16x16x32_bf16(Bt[n][k], At[m][k], acc[ai][bj][m][n], 0, 0, 0); __builtin_amdgcn_s_setprio(0); } while (0)
; #define PG8_WAIT_V(n) asm volatile("s_waitcnt vmcnt(" #n ")" ::: "memory")
; #define PG8_WAIT_L(n) asm volatile("s_waitcnt lgkmcnt(" #n ")" ::: "memory")
; #define PG8_BAR __builtin_amdgcn_s_barrier()
; #define PG8_SCHED __builtin_amdgcn_sched_barrier(0)
; template <class Epi, class Sched, bool ALIGN_EPI = false, bool SP2 = false>
; __device__ __forceinline__ void gemm_phase(PG8_LAS unsigned char* lds, const Gemm g, const Sched& S, const Epi& E) {
;     ...
;             const bool last = (t == nt - 2);
;             const char* a1 = cA + (size_t)(t + 1) * kstep;
;             const char* a2 = last ? nA : cA + (size_t)(t + 2) * kstep; const char* b2 = last ? nB : cB + (size_t)(t + 2) * kstep;
;             const char* a3 = a2 + kstep; const char* b3 = b2 + kstep;
;             if (last && has_next) S.a_ready(nxt);
;             if constexpr (SP2) {
;             PG8_LDB(B0, 0, 0); PG8_LDB(B1, 0, 1); PG8_SCHED; PG8_LDA(At, 0, 0); PG8_STAGE(PG8_SA(1, 1), a1 + hstep, voffA);
;             PG8_WAIT_V(8); PG8_WAIT_L(0); PG8_BAR; PG8_MMA(0, 0, At, B0); PG8_MMA(0, 1, At, B1); PG8_BAR; PG8_SCHED;
;             PG8_LDA(At, 0, 1); PG8_STAGE(PG8_SB(0, 0), b2, voffB); PG8_STAGE(PG8_SB(0, 1), b2 + hstep, voffB); PG8_STAGE(PG8_SA(0, 0), a2, voffA);
.LBB0_718:
	s_add_u32 s28, vcc_lo, 0xfffc0080
	s_addc_u32 s38, vcc_hi, -1
	s_add_i32 s39, 0, 0x10000
	s_cmp_eq_u32 s80, 12
	s_cselect_b32 s67, s41, s38
	s_cselect_b32 s66, s76, s28
	v_add_u32_e32 v138, s39, v142
	s_cselect_b32 s65, s37, s79
	s_cselect_b32 s64, s77, s78
	s_add_i32 s28, 0, 0x14000
	ds_read_b128 v[144:147], v138
	ds_read_b128 v[148:151], v138 offset:1024
	ds_read_b128 v[152:155], v138 offset:2048
	ds_read_b128 v[156:159], v138 offset:3072
	v_add_u32_e32 v138, s28, v142
	ds_read_b128 v[160:163], v138
	ds_read_b128 v[164:167], v138 offset:1024
	ds_read_b128 v[168:171], v138 offset:2048
	ds_read_b128 v[172:175], v138 offset:3072
	v_lshl_add_u64 v[138:139], vcc, 0, v[134:135]
	s_add_i32 m0, s30, 0xc000
	ds_read_b128 v[182:185], v143
	ds_read_b128 v[186:189], v143 offset:1024
	ds_read_b128 v[190:193], v143 offset:2048
	ds_read_b128 v[194:197], v143 offset:3072
	ds_read_b128 v[198:201], v143 offset:4096
	ds_read_b128 v[202:205], v143 offset:5120
	ds_read_b128 v[206:209], v143 offset:6144
	ds_read_b128 v[210:213], v143 offset:7168
	global_load_lds_dwordx4 v[138:139], off
	v_lshl_add_u64 v[138:139], vcc, 0, v[136:137]
	s_add_i32 m0, s30, 0xe000
	s_nop 0
	global_load_lds_dwordx4 v[138:139], off
	s_waitcnt vmcnt(8)
	s_waitcnt lgkmcnt(0)
	s_barrier
	s_setprio 1
	s_waitcnt lgkmcnt(0)
	v_mfma_f32_16x16x32_bf16 v[124:127], v[144:147], v[182:185], v[124:127]
	v_mfma_f32_16x16x32_bf16 v[120:123], v[152:155], v[182:185], v[120:123]
	v_mfma_f32_16x16x32_bf16 v[108:111], v[144:147], v[190:193], v[108:111]
	v_mfma_f32_16x16x32_bf16 v[104:107], v[152:155], v[190:193], v[104:107]
	v_mfma_f32_16x16x32_bf16 v[92:95], v[144:147], v[198:201], v[92:95]
	v_mfma_f32_16x16x32_bf16 v[88:91], v[152:155], v[198:201], v[88:91]
	v_mfma_f32_16x16x32_bf16 v[76:79], v[144:147], v[206:209], v[76:79]
	v_mfma_f32_16x16x32_bf16 v[72:75], v[152:155], v[206:209], v[72:75]
	v_mfma_f32_16x16x32_bf16 v[124:127], v[148:151], v[186:189], v[124:127]
	v_mfma_f32_16x16x32_bf16 v[120:123], v[156:159], v[186:189], v[120:123]
	v_mfma_f32_16x16x32_bf16 v[108:111], v[148:151], v[194:197], v[108:111]
	v_mfma_f32_16x16x32_bf16 v[104:107], v[156:159], v[194:197], v[104:107]
	v_mfma_f32_16x16x32_bf16 v[92:95], v[148:151], v[202:205], v[92:95]
	v_mfma_f32_16x16x32_bf16 v[88:91], v[156:159], v[202:205], v[88:91]
	v_mfma_f32_16x16x32_bf16 v[76:79], v[148:151], v[210:213], v[76:79]
	v_mfma_f32_16x16x32_bf16 v[72:75], v[156:159], v[210:213], v[72:75]
	s_setprio 0
	s_setprio 1
	v_mfma_f32_16x16x32_bf16 v[116:119], v[160:163], v[182:185], v[116:119]
	v_mfma_f32_16x16x32_bf16 v[112:115], v[168:171], v[182:185], v[112:115]
	v_mfma_f32_16x16x32_bf16 v[100:103], v[160:163], v[190:193], v[100:103]
	v_mfma_f32_16x16x32_bf16 v[96:99], v[168:171], v[190:193], v[96:99]
	v_mfma_f32_16x16x32_bf16 v[84:87], v[160:163], v[198:201], v[84:87]
	v_mfma_f32_16x16x32_bf16 v[80:83], v[168:171], v[198:201], v[80:83]
	v_mfma_f32_16x16x32_bf16 v[68:71], v[160:163], v[206:209], v[68:71]
	v_mfma_f32_16x16x32_bf16 v[64:67], v[168:171], v[206:209], v[64:67]
	v_mfma_f32_16x16x32_bf16 v[116:119], v[164:167], v[186:189], v[116:119]
	v_mfma_f32_16x16x32_bf16 v[112:115], v[172:175], v[186:189], v[112:115]
	v_mfma_f32_16x16x32_bf16 v[100:103], v[164:167], v[194:197], v[100:103]
	v_mfma_f32_16x16x32_bf16 v[96:99], v[172:175], v[194:197], v[96:99]
	v_mfma_f32_16x16x32_bf16 v[84:87], v[164:167], v[202:205], v[84:87]
	v_mfma_f32_16x16x32_bf16 v[80:83], v[172:175], v[202:205], v[80:83]
	v_mfma_f32_16x16x32_bf16 v[68:71], v[164:167], v[210:213], v[68:71]
	v_mfma_f32_16x16x32_bf16 v[64:67], v[172:175], v[210:213], v[64:67]
	s_setprio 0
	s_barrier
	s_add_i32 s38, s39, s23
	v_lshl_add_u64 v[138:139], s[64:65], 0, v[176:177]
	s_mov_b32 m0, s38
	ds_read_b128 v[182:185], v143 offset:16384
	ds_read_b128 v[186:189], v143 offset:17408
	ds_read_b128 v[190:193], v143 offset:18432
	ds_read_b128 v[194:197], v143 offset:19456
	ds_read_b128 v[198:201], v143 offset:20480
	ds_read_b128 v[202:205], v143 offset:21504
	ds_read_b128 v[206:209], v143 offset:22528
	ds_read_b128 v[210:213], v143 offset:23552
	global_load_lds_dwordx4 v[138:139], off
	s_add_i32 m0, s38, 0x2000
	s_add_u32 s38, s64, 0x40000
	v_lshl_add_u64 v[214:215], s[64:65], 0, v[128:129]
	s_addc_u32 s39, s65, 0
	s_add_i32 s28, s28, s23
	global_load_lds_dwordx4 v[214:215], off
	v_lshl_add_u64 v[216:217], s[38:39], 0, v[176:177]
	s_mov_b32 m0, s28
	v_lshl_add_u64 v[218:219], s[66:67], 0, v[130:131]
	global_load_lds_dwordx4 v[216:217], off
	v_lshl_add_u64 v[216:217], s[38:39], 0, v[128:129]
	s_add_i32 m0, s28, 0x2000
	s_nop 0
	global_load_lds_dwordx4 v[216:217], off
	v_lshl_add_u64 v[216:217], s[66:67], 0, v[132:133]
	s_mov_b32 m0, s30
	s_nop 0
	global_load_lds_dwordx4 v[216:217], off
	s_mov_b32 m0, s31
	s_nop 0
	global_load_lds_dwordx4 v[218:219], off
	s_waitcnt vmcnt(8)
	s_waitcnt lgkmcnt(0)
	s_barrier
; #define PG8_STAGE(bufoff, gbase, voff) do { _Pragma("unroll") for (int _i = 0; _i < 2; ++_i) \
;         __builtin_amdgcn_global_load_lds((const unsigned*)((const char*)(gbase) + (voff)[_i]), (PG8_LAS unsigned*)(lds + (bufoff) + ldsw + _i * 8192), 16, 0, 0); } while (0)
; #define PG8_LDA(dst, b, h) do { _Pragma("unroll") for (int m = 0; m < 4; ++m) _Pragma("unroll") for (int k = 0; k < 2; ++k) dst[m][k] = *(const PG8_LAS bf16x8*)(lds + PG8_SA(b, h) + aoff + m * 2048 + k * 1024); } while (0)
; #define PG8_LDB(dst, b, h) do { _Pragma("unroll") for (int n = 0; n < 2; ++n) _Pragma("unroll") for (int k = 0; k < 2; ++k) dst[n][k] = *(const PG8_LAS bf16x8*)(lds + PG8_SB(b, h) + boff + n * 2048 + k * 1024); } while (0)
; #define PG8_MMA(ai, bj, At, Bt) do { __builtin_amdgcn_s_setprio(1); _Pragma("unroll") for (int m = 0; m < 4; ++m) _Pragma("unroll") for (int n = 0; n < 2; ++n) _Pragma("unroll") for (int k = 0; k < 2; ++k) \
;         acc[ai][bj][m][n] = __builtin_amdgcn_mfma_f32_16x16x32_bf16(Bt[n][k], At[m][k], acc[ai][bj][m][n], 0, 0, 0); __builtin_amdgcn_s_setprio(0); } while (0)
; #define PG8_WAIT_V(n) asm volatile("s_waitcnt vmcnt(" #n ")" ::: "memory")
; #define PG8_WAIT_L(n) asm volatile("s_waitcnt lgkmcnt(" #n ")" ::: "memory")
; #define PG8_BAR __builtin_amdgcn_s_barrier()
; #define PG8_SCHED __builtin_amdgcn_sched_barrier(0)
; template <class Epi, class Sched, bool ALIGN_EPI = false, bool SP2 = false>
; __device__ __forceinline__ void gemm_phase(PG8_LAS unsigned char* lds, const Gemm g, const Sched& S, const Epi& E) {
;     ...
;             PG8_WAIT_V(8); PG8_WAIT_L(0); PG8_BAR; PG8_MMA(1, 0, At, B0); PG8_MMA(1, 1, At, B1); PG8_BAR; PG8_SCHED;
;             PG8_LDB(B0, 1, 0); PG8_LDB(B1, 1, 1); PG8_SCHED; PG8_LDA(At, 1, 0); PG8_STAGE(PG8_SA(0, 1), a2 + hstep, voffA);
;             PG8_WAIT_V(8); PG8_WAIT_L(0); PG8_BAR; PG8_MMA(0, 0, At, B0); PG8_MMA(0, 1, At, B1); PG8_BAR; PG8_SCHED;
	s_setprio 1
	s_waitcnt lgkmcnt(0)
	v_mfma_f32_16x16x32_bf16 v[60:63], v[144:147], v[182:185], v[60:63]
	v_mfma_f32_16x16x32_bf16 v[56:59], v[152:155], v[182:185], v[56:59]
	v_mfma_f32_16x16x32_bf16 v[44:47], v[144:147], v[190:193], v[44:47]
	v_mfma_f32_16x16x32_bf16 v[40:43], v[152:155], v[190:193], v[40:43]
	v_mfma_f32_16x16x32_bf16 v[28:31], v[144:147], v[198:201], v[28:31]
	v_mfma_f32_16x16x32_bf16 v[24:27], v[152:155], v[198:201], v[24:27]
	v_mfma_f32_16x16x32_bf16 v[12:15], v[144:147], v[206:209], v[12:15]
	v_mfma_f32_16x16x32_bf16 v[8:11], v[152:155], v[206:209], v[8:11]
	v_mfma_f32_16x16x32_bf16 v[60:63], v[148:151], v[186:189], v[60:63]
	v_mfma_f32_16x16x32_bf16 v[56:59], v[156:159], v[186:189], v[56:59]
	v_mfma_f32_16x16x32_bf16 v[44:47], v[148:151], v[194:197], v[44:47]
	v_mfma_f32_16x16x32_bf16 v[40:43], v[156:159], v[194:197], v[40:43]
	v_mfma_f32_16x16x32_bf16 v[28:31], v[148:151], v[202:205], v[28:31]
	v_mfma_f32_16x16x32_bf16 v[24:27], v[156:159], v[202:205], v[24:27]
	v_mfma_f32_16x16x32_bf16 v[12:15], v[148:151], v[210:213], v[12:15]
	v_mfma_f32_16x16x32_bf16 v[8:11], v[156:159], v[210:213], v[8:11]
	s_setprio 0
	s_setprio 1
	v_mfma_f32_16x16x32_bf16 v[52:55], v[160:163], v[182:185], v[52:55]
	v_mfma_f32_16x16x32_bf16 v[48:51], v[168:171], v[182:185], v[48:51]
	v_mfma_f32_16x16x32_bf16 v[36:39], v[160:163], v[190:193], v[36:39]
	v_mfma_f32_16x16x32_bf16 v[32:35], v[168:171], v[190:193], v[32:35]
	v_mfma_f32_16x16x32_bf16 v[20:23], v[160:163], v[198:201], v[20:23]
	v_mfma_f32_16x16x32_bf16 v[16:19], v[168:171], v[198:201], v[16:19]
	v_mfma_f32_16x16x32_bf16 v[4:7], v[160:163], v[206:209], v[4:7]
	v_mfma_f32_16x16x32_bf16 v[0:3], v[168:171], v[206:209], v[0:3]
	v_mfma_f32_16x16x32_bf16 v[52:55], v[164:167], v[186:189], v[52:55]
	v_mfma_f32_16x16x32_bf16 v[48:51], v[172:175], v[186:189], v[48:51]
	v_mfma_f32_16x16x32_bf16 v[36:39], v[164:167], v[194:197], v[36:39]
	v_mfma_f32_16x16x32_bf16 v[32:35], v[172:175], v[194:197], v[32:35]
	v_mfma_f32_16x16x32_bf16 v[20:23], v[164:167], v[202:205], v[20:23]
	v_mfma_f32_16x16x32_bf16 v[16:19], v[172:175], v[202:205], v[16:19]
	v_mfma_f32_16x16x32_bf16 v[4:7], v[164:167], v[210:213], v[4:7]
	v_mfma_f32_16x16x32_bf16 v[0:3], v[172:175], v[210:213], v[0:3]
	s_setprio 0
	s_barrier
	s_add_i32 s28, 0, 0x18000
	s_add_i32 s48, 0, 0x1c000
	v_add_u32_e32 v156, s28, v142
	v_add_u32_e32 v172, s48, v142
	ds_read_b128 v[144:147], v156
	ds_read_b128 v[148:151], v156 offset:1024
	ds_read_b128 v[152:155], v156 offset:2048
	ds_read_b128 v[156:159], v156 offset:3072
	ds_read_b128 v[160:163], v172
	ds_read_b128 v[164:167], v172 offset:1024
	ds_read_b128 v[168:171], v172 offset:2048
	ds_read_b128 v[172:175], v172 offset:3072
	s_add_u32 s38, s66, 0x40000
	s_addc_u32 s39, s67, 0
	s_mov_b32 m0, s63
	v_lshl_add_u64 v[220:221], s[38:39], 0, v[132:133]
	ds_read_b128 v[182:185], v143 offset:32768
	ds_read_b128 v[186:189], v143 offset:33792
	ds_read_b128 v[190:193], v143 offset:34816
	ds_read_b128 v[194:197], v143 offset:35840
	ds_read_b128 v[198:201], v143 offset:36864
	ds_read_b128 v[202:205], v143 offset:37888
	ds_read_b128 v[206:209], v143 offset:38912
	ds_read_b128 v[210:213], v143 offset:39936
	global_load_lds_dwordx4 v[220:221], off
	v_lshl_add_u64 v[220:221], s[38:39], 0, v[130:131]
	s_mov_b32 m0, s69
	s_nop 0
	global_load_lds_dwordx4 v[220:221], off
	s_waitcnt vmcnt(8)
	s_waitcnt lgkmcnt(0)
	s_barrier
	s_setprio 1
	s_waitcnt lgkmcnt(0)
	v_mfma_f32_16x16x32_bf16 v[124:127], v[144:147], v[182:185], v[124:127]
	v_mfma_f32_16x16x32_bf16 v[120:123], v[152:155], v[182:185], v[120:123]
	v_mfma_f32_16x16x32_bf16 v[108:111], v[144:147], v[190:193], v[108:111]
	v_mfma_f32_16x16x32_bf16 v[104:107], v[152:155], v[190:193], v[104:107]
	v_mfma_f32_16x16x32_bf16 v[92:95], v[144:147], v[198:201], v[92:95]
	v_mfma_f32_16x16x32_bf16 v[88:91], v[152:155], v[198:201], v[88:91]
	v_mfma_f32_16x16x32_bf16 v[76:79], v[144:147], v[206:209], v[76:79]
	v_mfma_f32_16x16x32_bf16 v[72:75], v[152:155], v[206:209], v[72:75]
	v_mfma_f32_16x16x32_bf16 v[124:127], v[148:151], v[186:189], v[124:127]
	v_mfma_f32_16x16x32_bf16 v[120:123], v[156:159], v[186:189], v[120:123]
	v_mfma_f32_16x16x32_bf16 v[108:111], v[148:151], v[194:197], v[108:111]
	v_mfma_f32_16x16x32_bf16 v[104:107], v[156:159], v[194:197], v[104:107]
	v_mfma_f32_16x16x32_bf16 v[92:95], v[148:151], v[202:205], v[92:95]
	v_mfma_f32_16x16x32_bf16 v[88:91], v[156:159], v[202:205], v[88:91]
	v_mfma_f32_16x16x32_bf16 v[76:79], v[148:151], v[210:213], v[76:79]
	v_mfma_f32_16x16x32_bf16 v[72:75], v[156:159], v[210:213], v[72:75]
	s_setprio 0
	s_setprio 1
	v_mfma_f32_16x16x32_bf16 v[116:119], v[160:163], v[182:185], v[116:119]
	v_mfma_f32_16x16x32_bf16 v[112:115], v[168:171], v[182:185], v[112:115]
	v_mfma_f32_16x16x32_bf16 v[100:103], v[160:163], v[190:193], v[100:103]
	v_mfma_f32_16x16x32_bf16 v[96:99], v[168:171], v[190:193], v[96:99]
	v_mfma_f32_16x16x32_bf16 v[84:87], v[160:163], v[198:201], v[84:87]
	v_mfma_f32_16x16x32_bf16 v[80:83], v[168:171], v[198:201], v[80:83]
	v_mfma_f32_16x16x32_bf16 v[68:71], v[160:163], v[206:209], v[68:71]
	v_mfma_f32_16x16x32_bf16 v[64:67], v[168:171], v[206:209], v[64:67]
	v_mfma_f32_16x16x32_bf16 v[116:119], v[164:167], v[186:189], v[116:119]
	v_mfma_f32_16x16x32_bf16 v[112:115], v[172:175], v[186:189], v[112:115]
	v_mfma_f32_16x16x32_bf16 v[100:103], v[164:167], v[194:197], v[100:103]
	v_mfma_f32_16x16x32_bf16 v[96:99], v[172:175], v[194:197], v[96:99]
	v_mfma_f32_16x16x32_bf16 v[84:87], v[164:167], v[202:205], v[84:87]
	v_mfma_f32_16x16x32_bf16 v[80:83], v[172:175], v[202:205], v[80:83]
	v_mfma_f32_16x16x32_bf16 v[68:71], v[164:167], v[210:213], v[68:71]
	v_mfma_f32_16x16x32_bf16 v[64:67], v[172:175], v[210:213], v[64:67]
	s_setprio 0
	s_barrier
; #define PG8_STAGE(bufoff, gbase, voff) do { _Pragma("unroll") for (int _i = 0; _i < 2; ++_i) \
;         __builtin_amdgcn_global_load_lds((const unsigned*)((const char*)(gbase) + (voff)[_i]), (PG8_LAS unsigned*)(lds + (bufoff) + ldsw + _i * 8192), 16, 0, 0); } while (0)
; #define PG8_LDA(dst, b, h) do { _Pragma("unroll") for (int m = 0; m < 4; ++m) _Pragma("unroll") for (int k = 0; k < 2; ++k) dst[m][k] = *(const PG8_LAS bf16x8*)(lds + PG8_SA(b, h) + aoff + m * 2048 + k * 1024); } while (0)
; #define PG8_MMA(ai, bj, At, Bt) do { __builtin_amdgcn_s_setprio(1); _Pragma("unroll") for (int m = 0; m < 4; ++m) _Pragma("unroll") for (int n = 0; n < 2; ++n) _Pragma("unroll") for (int k = 0; k < 2; ++k) \
;         acc[ai][bj][m][n] = __builtin_amdgcn_mfma_f32_16x16x32_bf16(Bt[n][k], At[m][k], acc[ai][bj][m][n], 0, 0, 0); __builtin_amdgcn_s_setprio(0); } while (0)
; #define PG8_WAIT_V(n) asm volatile("s_waitcnt vmcnt(" #n ")" ::: "memory")
; #define PG8_WAIT_L(n) asm volatile("s_waitcnt lgkmcnt(" #n ")" ::: "memory")
; #define PG8_BAR __builtin_amdgcn_s_barrier()
; #define PG8_SCHED __builtin_amdgcn_sched_barrier(0)
; template <class Epi, class Sched, bool ALIGN_EPI = false, bool SP2 = false>
; __device__ __forceinline__ void gemm_phase(PG8_LAS unsigned char* lds, const Gemm g, const Sched& S, const Epi& E) {
;     ...
;             PG8_LDA(At, 1, 1); PG8_STAGE(PG8_SB(1, 0), b3, voffB); PG8_STAGE(PG8_SB(1, 1), b3 + hstep, voffB); PG8_STAGE(PG8_SA(1, 0), a3, voffA);
;             PG8_WAIT_V(8); PG8_WAIT_L(0); PG8_BAR; PG8_MMA(1, 0, At, B0); PG8_MMA(1, 1, At, B1); PG8_BAR; PG8_SCHED;
	s_add_i32 s28, s28, s23
	v_lshl_add_u64 v[138:139], v[138:139], 0, s[44:45]
	s_mov_b32 m0, s28
	ds_read_b128 v[182:185], v143 offset:49152
	ds_read_b128 v[186:189], v143 offset:50176
	ds_read_b128 v[190:193], v143 offset:51200
	ds_read_b128 v[194:197], v143 offset:52224
	ds_read_b128 v[198:201], v143 offset:53248
	ds_read_b128 v[202:205], v143 offset:54272
	ds_read_b128 v[206:209], v143 offset:55296
	ds_read_b128 v[210:213], v143 offset:56320
	global_load_lds_dwordx4 v[138:139], off
	s_add_i32 m0, s28, 0x2000
	s_add_u32 s38, s64, 0x40080
	v_lshl_add_u64 v[138:139], v[214:215], 0, s[44:45]
	s_addc_u32 s39, s65, 0
	s_add_i32 s28, s48, s23
	global_load_lds_dwordx4 v[138:139], off
	v_lshl_add_u64 v[138:139], s[38:39], 0, v[176:177]
	s_mov_b32 m0, s28
	s_nop 0
	global_load_lds_dwordx4 v[138:139], off
	v_lshl_add_u64 v[138:139], s[38:39], 0, v[128:129]
	s_add_i32 m0, s28, 0x2000
	s_nop 0
	global_load_lds_dwordx4 v[138:139], off
	v_lshl_add_u64 v[138:139], v[216:217], 0, s[44:45]
	s_mov_b32 m0, s73
	s_nop 0
	global_load_lds_dwordx4 v[138:139], off
	v_lshl_add_u64 v[138:139], v[218:219], 0, s[44:45]
	s_mov_b32 m0, s74
	s_nop 0
	global_load_lds_dwordx4 v[138:139], off
	s_waitcnt vmcnt(8)
	s_waitcnt lgkmcnt(0)
	s_barrier
	s_setprio 1
	s_waitcnt lgkmcnt(0)
	v_mfma_f32_16x16x32_bf16 v[60:63], v[144:147], v[182:185], v[60:63]
	v_mfma_f32_16x16x32_bf16 v[56:59], v[152:155], v[182:185], v[56:59]
	v_mfma_f32_16x16x32_bf16 v[44:47], v[144:147], v[190:193], v[44:47]
	v_mfma_f32_16x16x32_bf16 v[40:43], v[152:155], v[190:193], v[40:43]
	v_mfma_f32_16x16x32_bf16 v[28:31], v[144:147], v[198:201], v[28:31]
	v_mfma_f32_16x16x32_bf16 v[24:27], v[152:155], v[198:201], v[24:27]
	v_mfma_f32_16x16x32_bf16 v[12:15], v[144:147], v[206:209], v[12:15]
	v_mfma_f32_16x16x32_bf16 v[8:11], v[152:155], v[206:209], v[8:11]
	v_mfma_f32_16x16x32_bf16 v[60:63], v[148:151], v[186:189], v[60:63]
	v_mfma_f32_16x16x32_bf16 v[56:59], v[156:159], v[186:189], v[56:59]
	v_mfma_f32_16x16x32_bf16 v[44:47], v[148:151], v[194:197], v[44:47]
	v_mfma_f32_16x16x32_bf16 v[40:43], v[156:159], v[194:197], v[40:43]
	v_mfma_f32_16x16x32_bf16 v[28:31], v[148:151], v[202:205], v[28:31]
	v_mfma_f32_16x16x32_bf16 v[24:27], v[156:159], v[202:205], v[24:27]
	v_mfma_f32_16x16x32_bf16 v[12:15], v[148:151], v[210:213], v[12:15]
	v_mfma_f32_16x16x32_bf16 v[8:11], v[156:159], v[210:213], v[8:11]
	s_setprio 0
	s_setprio 1
	v_mfma_f32_16x16x32_bf16 v[52:55], v[160:163], v[182:185], v[52:55]
	v_mfma_f32_16x16x32_bf16 v[48:51], v[168:171], v[182:185], v[48:51]
	v_mfma_f32_16x16x32_bf16 v[36:39], v[160:163], v[190:193], v[36:39]
	v_mfma_f32_16x16x32_bf16 v[32:35], v[168:171], v[190:193], v[32:35]
	v_mfma_f32_16x16x32_bf16 v[20:23], v[160:163], v[198:201], v[20:23]
	v_mfma_f32_16x16x32_bf16 v[16:19], v[168:171], v[198:201], v[16:19]
	v_mfma_f32_16x16x32_bf16 v[4:7], v[160:163], v[206:209], v[4:7]
	v_mfma_f32_16x16x32_bf16 v[0:3], v[168:171], v[206:209], v[0:3]
	v_mfma_f32_16x16x32_bf16 v[52:55], v[164:167], v[186:189], v[52:55]
	v_mfma_f32_16x16x32_bf16 v[48:51], v[172:175], v[186:189], v[48:51]
	s_add_i32 s80, s80, 2
	v_mfma_f32_16x16x32_bf16 v[36:39], v[164:167], v[194:197], v[36:39]
	s_add_u32 vcc_lo, vcc_lo, 0x100
	v_mfma_f32_16x16x32_bf16 v[32:35], v[172:175], v[194:197], v[32:35]
	s_addc_u32 vcc_hi, vcc_hi, 0
	v_mfma_f32_16x16x32_bf16 v[20:23], v[164:167], v[202:205], v[20:23]
	s_add_u32 s78, s78, 0x100
	v_mfma_f32_16x16x32_bf16 v[16:19], v[172:175], v[202:205], v[16:19]
	s_addc_u32 s79, s79, 0
	v_mfma_f32_16x16x32_bf16 v[4:7], v[164:167], v[210:213], v[4:7]
	s_cmp_gt_u32 s80, 13
	v_mfma_f32_16x16x32_bf16 v[0:3], v[172:175], v[210:213], v[0:3]
	s_setprio 0
	s_barrier
	s_cbranch_scc0 .LBB0_718

; #define PG8_STAGE(bufoff, gbase, voff) do { _Pragma("unroll") for (int _i = 0; _i < 2; ++_i) \
;         __builtin_amdgcn_global_load_lds((const unsigned*)((const char*)(gbase) + (voff)[_i]), (PG8_LAS unsigned*)(lds + (bufoff) + ldsw + _i * 8192), 16, 0, 0); } while (0)
; #define PG8_LDA(dst, b, h) do { _Pragma("unroll") for (int m = 0; m < 4; ++m) _Pragma("unroll") for (int k = 0; k < 2; ++k) dst[m][k] = *(const PG8_LAS bf16x8*)(lds + PG8_SA(b, h) + aoff + m * 2048 + k * 1024); } while (0)
; #define PG8_LDB(dst, b, h) do { _Pragma("unroll") for (int n = 0; n < 2; ++n) _Pragma("unroll") for (int k = 0; k < 2; ++k) dst[n][k] = *(const PG8_LAS bf16x8*)(lds + PG8_SB(b, h) + boff + n * 2048 + k * 1024); } while (0)
; #define PG8_MMA(ai, bj, At, Bt) do { __builtin_amdgcn_s_setprio(1); _Pragma("unroll") for (int m = 0; m < 4; ++m) _Pragma("unroll") for (int n = 0; n < 2; ++n) _Pragma("unroll") for (int k = 0; k < 2; ++k) \
;         acc[ai][bj][m][n] = __builtin_amdgcn_mfma_f32_16x16x32_bf16(Bt[n][k], At[m][k], acc[ai][bj][m][n], 0, 0, 0); __builtin_amdgcn_s_setprio(0); } while (0)
; #define PG8_WAIT_V(n) asm volatile("s_waitcnt vmcnt(" #n ")" ::: "memory")
; #define PG8_WAIT_L(n) asm volatile("s_waitcnt lgkmcnt(" #n ")" ::: "memory")
; #define PG8_BAR __builtin_amdgcn_s_barrier()
; #define PG8_SCHED __builtin_amdgcn_sched_barrier(0)
; template <class Epi, class Sched, bool ALIGN_EPI = false, bool SP2 = false>
; __device__ __forceinline__ void gemm_phase(PG8_LAS unsigned char* lds, const Gemm g, const Sched& S, const Epi& E) {
;     ...
;             const bool last = (t == nt - 2);
;             const char* a1 = cA + (size_t)(t + 1) * kstep;
;             const char* a2 = last ? nA : cA + (size_t)(t + 2) * kstep; const char* b2 = last ? nB : cB + (size_t)(t + 2) * kstep;
;             const char* a3 = a2 + kstep; const char* b3 = b2 + kstep;
;             if (last && has_next) S.a_ready(nxt);
;             if constexpr (SP2) {
;             PG8_LDB(B0, 0, 0); PG8_LDB(B1, 0, 1); PG8_SCHED; PG8_LDA(At, 0, 0); PG8_STAGE(PG8_SA(1, 1), a1 + hstep, voffA);
;             PG8_WAIT_V(8); PG8_WAIT_L(0); PG8_BAR; PG8_MMA(0, 0, At, B0); PG8_MMA(0, 1, At, B1); PG8_BAR; PG8_SCHED;
;             PG8_LDA(At, 0, 1); PG8_STAGE(PG8_SB(0, 0), b2, voffB); PG8_STAGE(PG8_SB(0, 1), b2 + hstep, voffB); PG8_STAGE(PG8_SA(0, 0), a2, voffA);
.Lg3_peel:
	s_add_u32 s28, vcc_lo, 0xfffc0080
	s_addc_u32 s38, vcc_hi, -1
	s_add_i32 s39, 0, 0x10000
	s_cmp_eq_u32 s80, 12
	s_cselect_b32 s67, s41, s38
	s_cselect_b32 s66, s76, s28
	v_add_u32_e32 v138, s39, v142
	s_cselect_b32 s65, s37, s79
	s_cselect_b32 s64, s77, s78
	s_add_i32 s28, 0, 0x14000
	ds_read_b128 v[144:147], v138
	ds_read_b128 v[148:151], v138 offset:1024
	ds_read_b128 v[152:155], v138 offset:2048
	ds_read_b128 v[156:159], v138 offset:3072
	v_add_u32_e32 v138, s28, v142
	ds_read_b128 v[160:163], v138
	ds_read_b128 v[164:167], v138 offset:1024
	ds_read_b128 v[168:171], v138 offset:2048
	ds_read_b128 v[172:175], v138 offset:3072
	v_lshl_add_u64 v[138:139], vcc, 0, v[134:135]
	s_add_i32 m0, s30, 0xc000
	ds_read_b128 v[182:185], v143
	ds_read_b128 v[186:189], v143 offset:1024
	ds_read_b128 v[190:193], v143 offset:2048
	ds_read_b128 v[194:197], v143 offset:3072
	ds_read_b128 v[198:201], v143 offset:4096
	ds_read_b128 v[202:205], v143 offset:5120
	ds_read_b128 v[206:209], v143 offset:6144
	ds_read_b128 v[210:213], v143 offset:7168
	global_load_lds_dwordx4 v[138:139], off
	v_lshl_add_u64 v[138:139], vcc, 0, v[136:137]
	s_add_i32 m0, s30, 0xe000
	s_nop 0
	global_load_lds_dwordx4 v[138:139], off
	s_waitcnt vmcnt(24)
	s_waitcnt lgkmcnt(0)
	s_barrier
	s_setprio 1
	s_waitcnt lgkmcnt(0)
	v_mfma_f32_16x16x32_bf16 v[124:127], v[144:147], v[182:185], 0
	v_mfma_f32_16x16x32_bf16 v[120:123], v[152:155], v[182:185], 0
	v_mfma_f32_16x16x32_bf16 v[108:111], v[144:147], v[190:193], 0
	v_mfma_f32_16x16x32_bf16 v[104:107], v[152:155], v[190:193], 0
	v_mfma_f32_16x16x32_bf16 v[92:95], v[144:147], v[198:201], 0
	v_mfma_f32_16x16x32_bf16 v[88:91], v[152:155], v[198:201], 0
	v_mfma_f32_16x16x32_bf16 v[76:79], v[144:147], v[206:209], 0
	v_mfma_f32_16x16x32_bf16 v[72:75], v[152:155], v[206:209], 0
	v_mfma_f32_16x16x32_bf16 v[124:127], v[148:151], v[186:189], v[124:127]
	v_mfma_f32_16x16x32_bf16 v[120:123], v[156:159], v[186:189], v[120:123]
	v_mfma_f32_16x16x32_bf16 v[108:111], v[148:151], v[194:197], v[108:111]
	v_mfma_f32_16x16x32_bf16 v[104:107], v[156:159], v[194:197], v[104:107]
	v_mfma_f32_16x16x32_bf16 v[92:95], v[148:151], v[202:205], v[92:95]
	v_mfma_f32_16x16x32_bf16 v[88:91], v[156:159], v[202:205], v[88:91]
	v_mfma_f32_16x16x32_bf16 v[76:79], v[148:151], v[210:213], v[76:79]
	v_mfma_f32_16x16x32_bf16 v[72:75], v[156:159], v[210:213], v[72:75]
	s_setprio 0
	s_setprio 1
	v_mfma_f32_16x16x32_bf16 v[116:119], v[160:163], v[182:185], 0
	v_mfma_f32_16x16x32_bf16 v[112:115], v[168:171], v[182:185], 0
	v_mfma_f32_16x16x32_bf16 v[100:103], v[160:163], v[190:193], 0
	v_mfma_f32_16x16x32_bf16 v[96:99], v[168:171], v[190:193], 0
	v_mfma_f32_16x16x32_bf16 v[84:87], v[160:163], v[198:201], 0
	v_mfma_f32_16x16x32_bf16 v[80:83], v[168:171], v[198:201], 0
	v_mfma_f32_16x16x32_bf16 v[68:71], v[160:163], v[206:209], 0
	v_mfma_f32_16x16x32_bf16 v[64:67], v[168:171], v[206:209], 0
	v_mfma_f32_16x16x32_bf16 v[116:119], v[164:167], v[186:189], v[116:119]
	v_mfma_f32_16x16x32_bf16 v[112:115], v[172:175], v[186:189], v[112:115]
	v_mfma_f32_16x16x32_bf16 v[100:103], v[164:167], v[194:197], v[100:103]
	v_mfma_f32_16x16x32_bf16 v[96:99], v[172:175], v[194:197], v[96:99]
	v_mfma_f32_16x16x32_bf16 v[84:87], v[164:167], v[202:205], v[84:87]
	v_mfma_f32_16x16x32_bf16 v[80:83], v[172:175], v[202:205], v[80:83]
	v_mfma_f32_16x16x32_bf16 v[68:71], v[164:167], v[210:213], v[68:71]
	v_mfma_f32_16x16x32_bf16 v[64:67], v[172:175], v[210:213], v[64:67]
	s_setprio 0
	s_barrier
	s_add_i32 s38, s39, s23
	v_lshl_add_u64 v[138:139], s[64:65], 0, v[176:177]
	s_mov_b32 m0, s38
	ds_read_b128 v[182:185], v143 offset:16384
	ds_read_b128 v[186:189], v143 offset:17408
	ds_read_b128 v[190:193], v143 offset:18432
	ds_read_b128 v[194:197], v143 offset:19456
	ds_read_b128 v[198:201], v143 offset:20480
	ds_read_b128 v[202:205], v143 offset:21504
	ds_read_b128 v[206:209], v143 offset:22528
	ds_read_b128 v[210:213], v143 offset:23552
	global_load_lds_dwordx4 v[138:139], off
	s_add_i32 m0, s38, 0x2000
	s_add_u32 s38, s64, 0x40000
	v_lshl_add_u64 v[214:215], s[64:65], 0, v[128:129]
	s_addc_u32 s39, s65, 0
	s_add_i32 s28, s28, s23
	global_load_lds_dwordx4 v[214:215], off
	v_lshl_add_u64 v[216:217], s[38:39], 0, v[176:177]
	s_mov_b32 m0, s28
	v_lshl_add_u64 v[218:219], s[66:67], 0, v[130:131]
	global_load_lds_dwordx4 v[216:217], off
	v_lshl_add_u64 v[216:217], s[38:39], 0, v[128:129]
	s_add_i32 m0, s28, 0x2000
	s_nop 0
	global_load_lds_dwordx4 v[216:217], off
	v_lshl_add_u64 v[216:217], s[66:67], 0, v[132:133]
	s_mov_b32 m0, s30
	s_nop 0
	global_load_lds_dwordx4 v[216:217], off
	s_mov_b32 m0, s31
	s_nop 0
	global_load_lds_dwordx4 v[218:219], off
	s_waitcnt vmcnt(24)
	s_waitcnt lgkmcnt(0)
	s_barrier
; #define PG8_STAGE(bufoff, gbase, voff) do { _Pragma("unroll") for (int _i = 0; _i < 2; ++_i) \
;         __builtin_amdgcn_global_load_lds((const unsigned*)((const char*)(gbase) + (voff)[_i]), (PG8_LAS unsigned*)(lds + (bufoff) + ldsw + _i * 8192), 16, 0, 0); } while (0)
; #define PG8_LDA(dst, b, h) do { _Pragma("unroll") for (int m = 0; m < 4; ++m) _Pragma("unroll") for (int k = 0; k < 2; ++k) dst[m][k] = *(const PG8_LAS bf16x8*)(lds + PG8_SA(b, h) + aoff + m * 2048 + k * 1024); } while (0)
; #define PG8_LDB(dst, b, h) do { _Pragma("unroll") for (int n = 0; n < 2; ++n) _Pragma("unroll") for (int k = 0; k < 2; ++k) dst[n][k] = *(const PG8_LAS bf16x8*)(lds + PG8_SB(b, h) + boff + n * 2048 + k * 1024); } while (0)
; #define PG8_MMA(ai, bj, At, Bt) do { __builtin_amdgcn_s_setprio(1); _Pragma("unroll") for (int m = 0; m < 4; ++m) _Pragma("unroll") for (int n = 0; n < 2; ++n) _Pragma("unroll") for (int k = 0; k < 2; ++k) \
;         acc[ai][bj][m][n] = __builtin_amdgcn_mfma_f32_16x16x32_bf16(Bt[n][k], At[m][k], acc[ai][bj][m][n], 0, 0, 0); __builtin_amdgcn_s_setprio(0); } while (0)
; #define PG8_WAIT_V(n) asm volatile("s_waitcnt vmcnt(" #n ")" ::: "memory")
; #define PG8_WAIT_L(n) asm volatile("s_waitcnt lgkmcnt(" #n ")" ::: "memory")
; #define PG8_BAR __builtin_amdgcn_s_barrier()
; #define PG8_SCHED __builtin_amdgcn_sched_barrier(0)
; template <class Epi, class Sched, bool ALIGN_EPI = false, bool SP2 = false>
; __device__ __forceinline__ void gemm_phase(PG8_LAS unsigned char* lds, const Gemm g, const Sched& S, const Epi& E) {
;     ...
;             PG8_WAIT_V(8); PG8_WAIT_L(0); PG8_BAR; PG8_MMA(1, 0, At, B0); PG8_MMA(1, 1, At, B1); PG8_BAR; PG8_SCHED;
;             PG8_LDB(B0, 1, 0); PG8_LDB(B1, 1, 1); PG8_SCHED; PG8_LDA(At, 1, 0); PG8_STAGE(PG8_SA(0, 1), a2 + hstep, voffA);
;             PG8_WAIT_V(8); PG8_WAIT_L(0); PG8_BAR; PG8_MMA(0, 0, At, B0); PG8_MMA(0, 1, At, B1); PG8_BAR; PG8_SCHED;
	s_setprio 1
	s_waitcnt lgkmcnt(0)
	v_mfma_f32_16x16x32_bf16 v[60:63], v[144:147], v[182:185], 0
	v_mfma_f32_16x16x32_bf16 v[56:59], v[152:155], v[182:185], 0
	v_mfma_f32_16x16x32_bf16 v[44:47], v[144:147], v[190:193], 0
	v_mfma_f32_16x16x32_bf16 v[40:43], v[152:155], v[190:193], 0
	v_mfma_f32_16x16x32_bf16 v[28:31], v[144:147], v[198:201], 0
	v_mfma_f32_16x16x32_bf16 v[24:27], v[152:155], v[198:201], 0
	v_mfma_f32_16x16x32_bf16 v[12:15], v[144:147], v[206:209], 0
	v_mfma_f32_16x16x32_bf16 v[8:11], v[152:155], v[206:209], 0
	v_mfma_f32_16x16x32_bf16 v[60:63], v[148:151], v[186:189], v[60:63]
	v_mfma_f32_16x16x32_bf16 v[56:59], v[156:159], v[186:189], v[56:59]
	v_mfma_f32_16x16x32_bf16 v[44:47], v[148:151], v[194:197], v[44:47]
	v_mfma_f32_16x16x32_bf16 v[40:43], v[156:159], v[194:197], v[40:43]
	v_mfma_f32_16x16x32_bf16 v[28:31], v[148:151], v[202:205], v[28:31]
	v_mfma_f32_16x16x32_bf16 v[24:27], v[156:159], v[202:205], v[24:27]
	v_mfma_f32_16x16x32_bf16 v[12:15], v[148:151], v[210:213], v[12:15]
	v_mfma_f32_16x16x32_bf16 v[8:11], v[156:159], v[210:213], v[8:11]
	s_setprio 0
	s_setprio 1
	v_mfma_f32_16x16x32_bf16 v[52:55], v[160:163], v[182:185], 0
	v_mfma_f32_16x16x32_bf16 v[48:51], v[168:171], v[182:185], 0
	v_mfma_f32_16x16x32_bf16 v[36:39], v[160:163], v[190:193], 0
	v_mfma_f32_16x16x32_bf16 v[32:35], v[168:171], v[190:193], 0
	v_mfma_f32_16x16x32_bf16 v[20:23], v[160:163], v[198:201], 0
	v_mfma_f32_16x16x32_bf16 v[16:19], v[168:171], v[198:201], 0
	v_mfma_f32_16x16x32_bf16 v[4:7], v[160:163], v[206:209], 0
	v_mfma_f32_16x16x32_bf16 v[0:3], v[168:171], v[206:209], 0
	v_mfma_f32_16x16x32_bf16 v[52:55], v[164:167], v[186:189], v[52:55]
	v_mfma_f32_16x16x32_bf16 v[48:51], v[172:175], v[186:189], v[48:51]
	v_mfma_f32_16x16x32_bf16 v[36:39], v[164:167], v[194:197], v[36:39]
	v_mfma_f32_16x16x32_bf16 v[32:35], v[172:175], v[194:197], v[32:35]
	v_mfma_f32_16x16x32_bf16 v[20:23], v[164:167], v[202:205], v[20:23]
	v_mfma_f32_16x16x32_bf16 v[16:19], v[172:175], v[202:205], v[16:19]
	v_mfma_f32_16x16x32_bf16 v[4:7], v[164:167], v[210:213], v[4:7]
	v_mfma_f32_16x16x32_bf16 v[0:3], v[172:175], v[210:213], v[0:3]
	s_setprio 0
	s_barrier
	s_add_i32 s28, 0, 0x18000
	s_add_i32 s48, 0, 0x1c000
	v_add_u32_e32 v156, s28, v142
	v_add_u32_e32 v172, s48, v142
	ds_read_b128 v[144:147], v156
	ds_read_b128 v[148:151], v156 offset:1024
	ds_read_b128 v[152:155], v156 offset:2048
	ds_read_b128 v[156:159], v156 offset:3072
	ds_read_b128 v[160:163], v172
	ds_read_b128 v[164:167], v172 offset:1024
	ds_read_b128 v[168:171], v172 offset:2048
	ds_read_b128 v[172:175], v172 offset:3072
	s_add_u32 s38, s66, 0x40000
	s_addc_u32 s39, s67, 0
	s_mov_b32 m0, s63
	v_lshl_add_u64 v[220:221], s[38:39], 0, v[132:133]
	ds_read_b128 v[182:185], v143 offset:32768
	ds_read_b128 v[186:189], v143 offset:33792
	ds_read_b128 v[190:193], v143 offset:34816
	ds_read_b128 v[194:197], v143 offset:35840
	ds_read_b128 v[198:201], v143 offset:36864
	ds_read_b128 v[202:205], v143 offset:37888
	ds_read_b128 v[206:209], v143 offset:38912
	ds_read_b128 v[210:213], v143 offset:39936
	global_load_lds_dwordx4 v[220:221], off
	v_lshl_add_u64 v[220:221], s[38:39], 0, v[130:131]
	s_mov_b32 m0, s69
	s_nop 0
	global_load_lds_dwordx4 v[220:221], off
	s_waitcnt vmcnt(8)
	s_waitcnt lgkmcnt(0)
	s_barrier
	s_setprio 1
	s_waitcnt lgkmcnt(0)
	v_mfma_f32_16x16x32_bf16 v[124:127], v[144:147], v[182:185], v[124:127]
	v_mfma_f32_16x16x32_bf16 v[120:123], v[152:155], v[182:185], v[120:123]
	v_mfma_f32_16x16x32_bf16 v[108:111], v[144:147], v[190:193], v[108:111]
	v_mfma_f32_16x16x32_bf16 v[104:107], v[152:155], v[190:193], v[104:107]
	v_mfma_f32_16x16x32_bf16 v[92:95], v[144:147], v[198:201], v[92:95]
	v_mfma_f32_16x16x32_bf16 v[88:91], v[152:155], v[198:201], v[88:91]
	v_mfma_f32_16x16x32_bf16 v[76:79], v[144:147], v[206:209], v[76:79]
	v_mfma_f32_16x16x32_bf16 v[72:75], v[152:155], v[206:209], v[72:75]
	v_mfma_f32_16x16x32_bf16 v[124:127], v[148:151], v[186:189], v[124:127]
	v_mfma_f32_16x16x32_bf16 v[120:123], v[156:159], v[186:189], v[120:123]
	v_mfma_f32_16x16x32_bf16 v[108:111], v[148:151], v[194:197], v[108:111]
	v_mfma_f32_16x16x32_bf16 v[104:107], v[156:159], v[194:197], v[104:107]
	v_mfma_f32_16x16x32_bf16 v[92:95], v[148:151], v[202:205], v[92:95]
	v_mfma_f32_16x16x32_bf16 v[88:91], v[156:159], v[202:205], v[88:91]
	v_mfma_f32_16x16x32_bf16 v[76:79], v[148:151], v[210:213], v[76:79]
	v_mfma_f32_16x16x32_bf16 v[72:75], v[156:159], v[210:213], v[72:75]
	s_setprio 0
	s_setprio 1
	v_mfma_f32_16x16x32_bf16 v[116:119], v[160:163], v[182:185], v[116:119]
	v_mfma_f32_16x16x32_bf16 v[112:115], v[168:171], v[182:185], v[112:115]
	v_mfma_f32_16x16x32_bf16 v[100:103], v[160:163], v[190:193], v[100:103]
	v_mfma_f32_16x16x32_bf16 v[96:99], v[168:171], v[190:193], v[96:99]
	v_mfma_f32_16x16x32_bf16 v[84:87], v[160:163], v[198:201], v[84:87]
	v_mfma_f32_16x16x32_bf16 v[80:83], v[168:171], v[198:201], v[80:83]
	v_mfma_f32_16x16x32_bf16 v[68:71], v[160:163], v[206:209], v[68:71]
	v_mfma_f32_16x16x32_bf16 v[64:67], v[168:171], v[206:209], v[64:67]
	v_mfma_f32_16x16x32_bf16 v[116:119], v[164:167], v[186:189], v[116:119]
	v_mfma_f32_16x16x32_bf16 v[112:115], v[172:175], v[186:189], v[112:115]
	v_mfma_f32_16x16x32_bf16 v[100:103], v[164:167], v[194:197], v[100:103]
	v_mfma_f32_16x16x32_bf16 v[96:99], v[172:175], v[194:197], v[96:99]
	v_mfma_f32_16x16x32_bf16 v[84:87], v[164:167], v[202:205], v[84:87]
	v_mfma_f32_16x16x32_bf16 v[80:83], v[172:175], v[202:205], v[80:83]
	v_mfma_f32_16x16x32_bf16 v[68:71], v[164:167], v[210:213], v[68:71]
	v_mfma_f32_16x16x32_bf16 v[64:67], v[172:175], v[210:213], v[64:67]
	s_setprio 0
	s_barrier
; #define PG8_STAGE(bufoff, gbase, voff) do { _Pragma("unroll") for (int _i = 0; _i < 2; ++_i) \
;         __builtin_amdgcn_global_load_lds((const unsigned*)((const char*)(gbase) + (voff)[_i]), (PG8_LAS unsigned*)(lds + (bufoff) + ldsw + _i * 8192), 16, 0, 0); } while (0)
; #define PG8_LDA(dst, b, h) do { _Pragma("unroll") for (int m = 0; m < 4; ++m) _Pragma("unroll") for (int k = 0; k < 2; ++k) dst[m][k] = *(const PG8_LAS bf16x8*)(lds + PG8_SA(b, h) + aoff + m * 2048 + k * 1024); } while (0)
; #define PG8_MMA(ai, bj, At, Bt) do { __builtin_amdgcn_s_setprio(1); _Pragma("unroll") for (int m = 0; m < 4; ++m) _Pragma("unroll") for (int n = 0; n < 2; ++n) _Pragma("unroll") for (int k = 0; k < 2; ++k) \
;         acc[ai][bj][m][n] = __builtin_amdgcn_mfma_f32_16x16x32_bf16(Bt[n][k], At[m][k], acc[ai][bj][m][n], 0, 0, 0); __builtin_amdgcn_s_setprio(0); } while (0)
; #define PG8_WAIT_V(n) asm volatile("s_waitcnt vmcnt(" #n ")" ::: "memory")
; #define PG8_WAIT_L(n) asm volatile("s_waitcnt lgkmcnt(" #n ")" ::: "memory")
; #define PG8_BAR __builtin_amdgcn_s_barrier()
; #define PG8_SCHED __builtin_amdgcn_sched_barrier(0)
; template <class Epi, class Sched, bool ALIGN_EPI = false, bool SP2 = false>
; __device__ __forceinline__ void gemm_phase(PG8_LAS unsigned char* lds, const Gemm g, const Sched& S, const Epi& E) {
;     ...
;             PG8_LDA(At, 1, 1); PG8_STAGE(PG8_SB(1, 0), b3, voffB); PG8_STAGE(PG8_SB(1, 1), b3 + hstep, voffB); PG8_STAGE(PG8_SA(1, 0), a3, voffA);
;             PG8_WAIT_V(8); PG8_WAIT_L(0); PG8_BAR; PG8_MMA(1, 0, At, B0); PG8_MMA(1, 1, At, B1); PG8_BAR; PG8_SCHED;
	s_add_i32 s28, s28, s23
	v_lshl_add_u64 v[138:139], v[138:139], 0, s[44:45]
	s_mov_b32 m0, s28
	ds_read_b128 v[182:185], v143 offset:49152
	ds_read_b128 v[186:189], v143 offset:50176
	ds_read_b128 v[190:193], v143 offset:51200
	ds_read_b128 v[194:197], v143 offset:52224
	ds_read_b128 v[198:201], v143 offset:53248
	ds_read_b128 v[202:205], v143 offset:54272
	ds_read_b128 v[206:209], v143 offset:55296
	ds_read_b128 v[210:213], v143 offset:56320
	global_load_lds_dwordx4 v[138:139], off
	s_add_i32 m0, s28, 0x2000
	s_add_u32 s38, s64, 0x40080
	v_lshl_add_u64 v[138:139], v[214:215], 0, s[44:45]
	s_addc_u32 s39, s65, 0
	s_add_i32 s28, s48, s23
	global_load_lds_dwordx4 v[138:139], off
	v_lshl_add_u64 v[138:139], s[38:39], 0, v[176:177]
	s_mov_b32 m0, s28
	s_nop 0
	global_load_lds_dwordx4 v[138:139], off
	v_lshl_add_u64 v[138:139], s[38:39], 0, v[128:129]
	s_add_i32 m0, s28, 0x2000
	s_nop 0
	global_load_lds_dwordx4 v[138:139], off
	v_lshl_add_u64 v[138:139], v[216:217], 0, s[44:45]
	s_mov_b32 m0, s73
	s_nop 0
	global_load_lds_dwordx4 v[138:139], off
	v_lshl_add_u64 v[138:139], v[218:219], 0, s[44:45]
	s_mov_b32 m0, s74
	s_nop 0
	global_load_lds_dwordx4 v[138:139], off
	s_waitcnt vmcnt(8)
	s_waitcnt lgkmcnt(0)
	s_barrier
	s_setprio 1
	s_waitcnt lgkmcnt(0)
	v_mfma_f32_16x16x32_bf16 v[60:63], v[144:147], v[182:185], v[60:63]
	v_mfma_f32_16x16x32_bf16 v[56:59], v[152:155], v[182:185], v[56:59]
	v_mfma_f32_16x16x32_bf16 v[44:47], v[144:147], v[190:193], v[44:47]
	v_mfma_f32_16x16x32_bf16 v[40:43], v[152:155], v[190:193], v[40:43]
	v_mfma_f32_16x16x32_bf16 v[28:31], v[144:147], v[198:201], v[28:31]
	v_mfma_f32_16x16x32_bf16 v[24:27], v[152:155], v[198:201], v[24:27]
	v_mfma_f32_16x16x32_bf16 v[12:15], v[144:147], v[206:209], v[12:15]
	v_mfma_f32_16x16x32_bf16 v[8:11], v[152:155], v[206:209], v[8:11]
	v_mfma_f32_16x16x32_bf16 v[60:63], v[148:151], v[186:189], v[60:63]
	v_mfma_f32_16x16x32_bf16 v[56:59], v[156:159], v[186:189], v[56:59]
	v_mfma_f32_16x16x32_bf16 v[44:47], v[148:151], v[194:197], v[44:47]
	v_mfma_f32_16x16x32_bf16 v[40:43], v[156:159], v[194:197], v[40:43]
	v_mfma_f32_16x16x32_bf16 v[28:31], v[148:151], v[202:205], v[28:31]
	v_mfma_f32_16x16x32_bf16 v[24:27], v[156:159], v[202:205], v[24:27]
	v_mfma_f32_16x16x32_bf16 v[12:15], v[148:151], v[210:213], v[12:15]
	v_mfma_f32_16x16x32_bf16 v[8:11], v[156:159], v[210:213], v[8:11]
	s_setprio 0
	s_setprio 1
	v_mfma_f32_16x16x32_bf16 v[52:55], v[160:163], v[182:185], v[52:55]
	v_mfma_f32_16x16x32_bf16 v[48:51], v[168:171], v[182:185], v[48:51]
	v_mfma_f32_16x16x32_bf16 v[36:39], v[160:163], v[190:193], v[36:39]
	v_mfma_f32_16x16x32_bf16 v[32:35], v[168:171], v[190:193], v[32:35]
	v_mfma_f32_16x16x32_bf16 v[20:23], v[160:163], v[198:201], v[20:23]
	v_mfma_f32_16x16x32_bf16 v[16:19], v[168:171], v[198:201], v[16:19]
	v_mfma_f32_16x16x32_bf16 v[4:7], v[160:163], v[206:209], v[4:7]
	v_mfma_f32_16x16x32_bf16 v[0:3], v[168:171], v[206:209], v[0:3]
	v_mfma_f32_16x16x32_bf16 v[52:55], v[164:167], v[186:189], v[52:55]
	v_mfma_f32_16x16x32_bf16 v[48:51], v[172:175], v[186:189], v[48:51]
	s_add_i32 s80, s80, 2
	v_mfma_f32_16x16x32_bf16 v[36:39], v[164:167], v[194:197], v[36:39]
	s_add_u32 vcc_lo, vcc_lo, 0x100
	v_mfma_f32_16x16x32_bf16 v[32:35], v[172:175], v[194:197], v[32:35]
	s_addc_u32 vcc_hi, vcc_hi, 0
	v_mfma_f32_16x16x32_bf16 v[20:23], v[164:167], v[202:205], v[20:23]
	s_add_u32 s78, s78, 0x100
	v_mfma_f32_16x16x32_bf16 v[16:19], v[172:175], v[202:205], v[16:19]
	s_addc_u32 s79, s79, 0
	v_mfma_f32_16x16x32_bf16 v[4:7], v[164:167], v[210:213], v[4:7]
	s_cmp_gt_u32 s80, 13
	v_mfma_f32_16x16x32_bf16 v[0:3], v[172:175], v[210:213], v[0:3]
	s_setprio 0
	s_barrier
	s_cbranch_scc0 .LBB0_718
	s_branch .Lg3_post

; #define PG8_STAGE(bufoff, gbase, voff) do { _Pragma("unroll") for (int _i = 0; _i < 2; ++_i) \
;         __builtin_amdgcn_global_load_lds((const unsigned*)((const char*)(gbase) + (voff)[_i]), (PG8_LAS unsigned*)(lds + (bufoff) + ldsw + _i * 8192), 16, 0, 0); } while (0)
; #define PG8_LDA(dst, b, h) do { _Pragma("unroll") for (int m = 0; m < 4; ++m) _Pragma("unroll") for (int k = 0; k < 2; ++k) dst[m][k] = *(const PG8_LAS bf16x8*)(lds + PG8_SA(b, h) + aoff + m * 2048 + k * 1024); } while (0)
; #define PG8_LDB(dst, b, h) do { _Pragma("unroll") for (int n = 0; n < 2; ++n) _Pragma("unroll") for (int k = 0; k < 2; ++k) dst[n][k] = *(const PG8_LAS bf16x8*)(lds + PG8_SB(b, h) + boff + n * 2048 + k * 1024); } while (0)
; #define PG8_MMA(ai, bj, At, Bt) do { __builtin_amdgcn_s_setprio(1); _Pragma("unroll") for (int m = 0; m < 4; ++m) _Pragma("unroll") for (int n = 0; n < 2; ++n) _Pragma("unroll") for (int k = 0; k < 2; ++k) \
;         acc[ai][bj][m][n] = __builtin_amdgcn_mfma_f32_16x16x32_bf16(Bt[n][k], At[m][k], acc[ai][bj][m][n], 0, 0, 0); __builtin_amdgcn_s_setprio(0); } while (0)
; #define PG8_WAIT_V(n) asm volatile("s_waitcnt vmcnt(" #n ")" ::: "memory")
; #define PG8_WAIT_L(n) asm volatile("s_waitcnt lgkmcnt(" #n ")" ::: "memory")
; #define PG8_BAR __builtin_amdgcn_s_barrier()
; #define PG8_SCHED __builtin_amdgcn_sched_barrier(0)
; template <class Epi, class Sched, bool ALIGN_EPI = false, bool SP2 = false>
; __device__ __forceinline__ void gemm_phase(PG8_LAS unsigned char* lds, const Gemm g, const Sched& S, const Epi& E) {
;     ...
;             const bool last = (t == nt - 2);
;             const char* a1 = cA + (size_t)(t + 1) * kstep;
;             const char* a2 = last ? nA : cA + (size_t)(t + 2) * kstep; const char* b2 = last ? nB : cB + (size_t)(t + 2) * kstep;
;             const char* a3 = a2 + kstep; const char* b3 = b2 + kstep;
;             if (last && has_next) S.a_ready(nxt);
;             if constexpr (SP2) {
;             PG8_LDB(B0, 0, 0); PG8_LDB(B1, 0, 1); PG8_SCHED; PG8_LDA(At, 0, 0); PG8_STAGE(PG8_SA(1, 1), a1 + hstep, voffA);
;             PG8_WAIT_V(8); PG8_WAIT_L(0); PG8_BAR; PG8_MMA(0, 0, At, B0); PG8_MMA(0, 1, At, B1); PG8_BAR; PG8_SCHED;
;             PG8_LDA(At, 0, 1); PG8_STAGE(PG8_SB(0, 0), b2, voffB); PG8_STAGE(PG8_SB(0, 1), b2 + hstep, voffB); PG8_STAGE(PG8_SA(0, 0), a2, voffA);
.LBB0_790:
	s_add_u32 s4, s64, 0xfff00080
	s_addc_u32 s5, s65, -1
	s_add_i32 s28, 0, 0x10000
	s_cmp_eq_u32 s74, 60
	s_cselect_b32 s7, s35, s5
	s_cselect_b32 s6, s72, s4
	v_add_u32_e32 v138, s28, v142
	s_cselect_b32 s5, s27, s67
	s_cselect_b32 s4, s73, s66
	s_add_i32 s48, 0, 0x14000
	ds_read_b128 v[144:147], v138
	ds_read_b128 v[148:151], v138 offset:1024
	ds_read_b128 v[152:155], v138 offset:2048
	ds_read_b128 v[156:159], v138 offset:3072
	v_add_u32_e32 v138, s48, v142
	ds_read_b128 v[160:163], v138
	ds_read_b128 v[164:167], v138 offset:1024
	ds_read_b128 v[168:171], v138 offset:2048
	ds_read_b128 v[172:175], v138 offset:3072
	v_lshl_add_u64 v[138:139], s[64:65], 0, v[134:135]
	s_add_i32 m0, s23, 0xc000
	ds_read_b128 v[182:185], v143
	ds_read_b128 v[186:189], v143 offset:1024
	ds_read_b128 v[190:193], v143 offset:2048
	ds_read_b128 v[194:197], v143 offset:3072
	ds_read_b128 v[198:201], v143 offset:4096
	ds_read_b128 v[202:205], v143 offset:5120
	ds_read_b128 v[206:209], v143 offset:6144
	ds_read_b128 v[210:213], v143 offset:7168
	global_load_lds_dwordx4 v[138:139], off
	v_lshl_add_u64 v[138:139], s[64:65], 0, v[136:137]
	s_add_i32 m0, s23, 0xe000
	s_nop 0
	global_load_lds_dwordx4 v[138:139], off
	s_waitcnt vmcnt(8)
	s_waitcnt lgkmcnt(0)
	s_barrier
	s_setprio 1
	s_waitcnt lgkmcnt(0)
	v_mfma_f32_16x16x32_bf16 v[124:127], v[144:147], v[182:185], v[124:127]
	v_mfma_f32_16x16x32_bf16 v[120:123], v[152:155], v[182:185], v[120:123]
	v_mfma_f32_16x16x32_bf16 v[116:119], v[144:147], v[190:193], v[116:119]
	v_mfma_f32_16x16x32_bf16 v[108:111], v[152:155], v[190:193], v[108:111]
	v_mfma_f32_16x16x32_bf16 v[100:103], v[144:147], v[198:201], v[100:103]
	v_mfma_f32_16x16x32_bf16 v[92:95], v[152:155], v[198:201], v[92:95]
	v_mfma_f32_16x16x32_bf16 v[84:87], v[144:147], v[206:209], v[84:87]
	v_mfma_f32_16x16x32_bf16 v[76:79], v[152:155], v[206:209], v[76:79]
	v_mfma_f32_16x16x32_bf16 v[124:127], v[148:151], v[186:189], v[124:127]
	v_mfma_f32_16x16x32_bf16 v[120:123], v[156:159], v[186:189], v[120:123]
	v_mfma_f32_16x16x32_bf16 v[116:119], v[148:151], v[194:197], v[116:119]
	v_mfma_f32_16x16x32_bf16 v[108:111], v[156:159], v[194:197], v[108:111]
	v_mfma_f32_16x16x32_bf16 v[100:103], v[148:151], v[202:205], v[100:103]
	v_mfma_f32_16x16x32_bf16 v[92:95], v[156:159], v[202:205], v[92:95]
	v_mfma_f32_16x16x32_bf16 v[84:87], v[148:151], v[210:213], v[84:87]
	v_mfma_f32_16x16x32_bf16 v[76:79], v[156:159], v[210:213], v[76:79]
	s_setprio 0
	s_setprio 1
	v_mfma_f32_16x16x32_bf16 v[112:115], v[160:163], v[182:185], v[112:115]
	v_mfma_f32_16x16x32_bf16 v[104:107], v[168:171], v[182:185], v[104:107]
	v_mfma_f32_16x16x32_bf16 v[96:99], v[160:163], v[190:193], v[96:99]
	v_mfma_f32_16x16x32_bf16 v[88:91], v[168:171], v[190:193], v[88:91]
	v_mfma_f32_16x16x32_bf16 v[80:83], v[160:163], v[198:201], v[80:83]
	v_mfma_f32_16x16x32_bf16 v[72:75], v[168:171], v[198:201], v[72:75]
	v_mfma_f32_16x16x32_bf16 v[68:71], v[160:163], v[206:209], v[68:71]
	v_mfma_f32_16x16x32_bf16 v[64:67], v[168:171], v[206:209], v[64:67]
	v_mfma_f32_16x16x32_bf16 v[112:115], v[164:167], v[186:189], v[112:115]
	v_mfma_f32_16x16x32_bf16 v[104:107], v[172:175], v[186:189], v[104:107]
	v_mfma_f32_16x16x32_bf16 v[96:99], v[164:167], v[194:197], v[96:99]
	v_mfma_f32_16x16x32_bf16 v[88:91], v[172:175], v[194:197], v[88:91]
	v_mfma_f32_16x16x32_bf16 v[80:83], v[164:167], v[202:205], v[80:83]
	v_mfma_f32_16x16x32_bf16 v[72:75], v[172:175], v[202:205], v[72:75]
	v_mfma_f32_16x16x32_bf16 v[68:71], v[164:167], v[210:213], v[68:71]
	v_mfma_f32_16x16x32_bf16 v[64:67], v[172:175], v[210:213], v[64:67]
	s_setprio 0
	s_barrier
	s_add_i32 s28, s28, s22
	v_lshl_add_u64 v[138:139], s[4:5], 0, v[176:177]
	s_mov_b32 m0, s28
	ds_read_b128 v[182:185], v143 offset:16384
	ds_read_b128 v[186:189], v143 offset:17408
	ds_read_b128 v[190:193], v143 offset:18432
	ds_read_b128 v[194:197], v143 offset:19456
	ds_read_b128 v[198:201], v143 offset:20480
	ds_read_b128 v[202:205], v143 offset:21504
	ds_read_b128 v[206:209], v143 offset:22528
	ds_read_b128 v[210:213], v143 offset:23552
	global_load_lds_dwordx4 v[138:139], off
	s_add_i32 m0, s28, 0x2000
	s_add_u32 s38, s4, 0x100000
	v_lshl_add_u64 v[214:215], s[4:5], 0, v[128:129]
	s_addc_u32 s39, s5, 0
	s_add_i32 s28, s48, s22
	global_load_lds_dwordx4 v[214:215], off
	v_lshl_add_u64 v[216:217], s[38:39], 0, v[176:177]
	s_mov_b32 m0, s28
	v_lshl_add_u64 v[218:219], s[6:7], 0, v[130:131]
	global_load_lds_dwordx4 v[216:217], off
	v_lshl_add_u64 v[216:217], s[38:39], 0, v[128:129]
	s_add_i32 m0, s28, 0x2000
	s_nop 0
	global_load_lds_dwordx4 v[216:217], off
	v_lshl_add_u64 v[216:217], s[6:7], 0, v[132:133]
	s_mov_b32 m0, s23
	s_nop 0
	global_load_lds_dwordx4 v[216:217], off
	s_mov_b32 m0, s24
	s_nop 0
	global_load_lds_dwordx4 v[218:219], off
	s_waitcnt vmcnt(8)
	s_waitcnt lgkmcnt(0)
	s_barrier
; #define PG8_STAGE(bufoff, gbase, voff) do { _Pragma("unroll") for (int _i = 0; _i < 2; ++_i) \
;         __builtin_amdgcn_global_load_lds((const unsigned*)((const char*)(gbase) + (voff)[_i]), (PG8_LAS unsigned*)(lds + (bufoff) + ldsw + _i * 8192), 16, 0, 0); } while (0)
; #define PG8_LDA(dst, b, h) do { _Pragma("unroll") for (int m = 0; m < 4; ++m) _Pragma("unroll") for (int k = 0; k < 2; ++k) dst[m][k] = *(const PG8_LAS bf16x8*)(lds + PG8_SA(b, h) + aoff + m * 2048 + k * 1024); } while (0)
; #define PG8_LDB(dst, b, h) do { _Pragma("unroll") for (int n = 0; n < 2; ++n) _Pragma("unroll") for (int k = 0; k < 2; ++k) dst[n][k] = *(const PG8_LAS bf16x8*)(lds + PG8_SB(b, h) + boff + n * 2048 + k * 1024); } while (0)
; #define PG8_MMA(ai, bj, At, Bt) do { __builtin_amdgcn_s_setprio(1); _Pragma("unroll") for (int m = 0; m < 4; ++m) _Pragma("unroll") for (int n = 0; n < 2; ++n) _Pragma("unroll") for (int k = 0; k < 2; ++k) \
;         acc[ai][bj][m][n] = __builtin_amdgcn_mfma_f32_16x16x32_bf16(Bt[n][k], At[m][k], acc[ai][bj][m][n], 0, 0, 0); __builtin_amdgcn_s_setprio(0); } while (0)
; #define PG8_WAIT_V(n) asm volatile("s_waitcnt vmcnt(" #n ")" ::: "memory")
; #define PG8_WAIT_L(n) asm volatile("s_waitcnt lgkmcnt(" #n ")" ::: "memory")
; #define PG8_BAR __builtin_amdgcn_s_barrier()
; #define PG8_SCHED __builtin_amdgcn_sched_barrier(0)
; template <class Epi, class Sched, bool ALIGN_EPI = false, bool SP2 = false>
; __device__ __forceinline__ void gemm_phase(PG8_LAS unsigned char* lds, const Gemm g, const Sched& S, const Epi& E) {
;     ...
;             PG8_WAIT_V(8); PG8_WAIT_L(0); PG8_BAR; PG8_MMA(1, 0, At, B0); PG8_MMA(1, 1, At, B1); PG8_BAR; PG8_SCHED;
;             PG8_LDB(B0, 1, 0); PG8_LDB(B1, 1, 1); PG8_SCHED; PG8_LDA(At, 1, 0); PG8_STAGE(PG8_SA(0, 1), a2 + hstep, voffA);
;             PG8_WAIT_V(8); PG8_WAIT_L(0); PG8_BAR; PG8_MMA(0, 0, At, B0); PG8_MMA(0, 1, At, B1); PG8_BAR; PG8_SCHED;
	s_setprio 1
	s_waitcnt lgkmcnt(0)
	v_mfma_f32_16x16x32_bf16 v[60:63], v[144:147], v[182:185], v[60:63]
	v_mfma_f32_16x16x32_bf16 v[56:59], v[152:155], v[182:185], v[56:59]
	v_mfma_f32_16x16x32_bf16 v[52:55], v[144:147], v[190:193], v[52:55]
	v_mfma_f32_16x16x32_bf16 v[44:47], v[152:155], v[190:193], v[44:47]
	v_mfma_f32_16x16x32_bf16 v[36:39], v[144:147], v[198:201], v[36:39]
	v_mfma_f32_16x16x32_bf16 v[28:31], v[152:155], v[198:201], v[28:31]
	v_mfma_f32_16x16x32_bf16 v[20:23], v[144:147], v[206:209], v[20:23]
	v_mfma_f32_16x16x32_bf16 v[12:15], v[152:155], v[206:209], v[12:15]
	v_mfma_f32_16x16x32_bf16 v[60:63], v[148:151], v[186:189], v[60:63]
	v_mfma_f32_16x16x32_bf16 v[56:59], v[156:159], v[186:189], v[56:59]
	v_mfma_f32_16x16x32_bf16 v[52:55], v[148:151], v[194:197], v[52:55]
	v_mfma_f32_16x16x32_bf16 v[44:47], v[156:159], v[194:197], v[44:47]
	v_mfma_f32_16x16x32_bf16 v[36:39], v[148:151], v[202:205], v[36:39]
	v_mfma_f32_16x16x32_bf16 v[28:31], v[156:159], v[202:205], v[28:31]
	v_mfma_f32_16x16x32_bf16 v[20:23], v[148:151], v[210:213], v[20:23]
	v_mfma_f32_16x16x32_bf16 v[12:15], v[156:159], v[210:213], v[12:15]
	s_setprio 0
	s_setprio 1
	v_mfma_f32_16x16x32_bf16 v[48:51], v[160:163], v[182:185], v[48:51]
	v_mfma_f32_16x16x32_bf16 v[40:43], v[168:171], v[182:185], v[40:43]
	v_mfma_f32_16x16x32_bf16 v[32:35], v[160:163], v[190:193], v[32:35]
	v_mfma_f32_16x16x32_bf16 v[24:27], v[168:171], v[190:193], v[24:27]
	v_mfma_f32_16x16x32_bf16 v[16:19], v[160:163], v[198:201], v[16:19]
	v_mfma_f32_16x16x32_bf16 v[8:11], v[168:171], v[198:201], v[8:11]
	v_mfma_f32_16x16x32_bf16 v[4:7], v[160:163], v[206:209], v[4:7]
	v_mfma_f32_16x16x32_bf16 v[0:3], v[168:171], v[206:209], v[0:3]
	v_mfma_f32_16x16x32_bf16 v[48:51], v[164:167], v[186:189], v[48:51]
	v_mfma_f32_16x16x32_bf16 v[40:43], v[172:175], v[186:189], v[40:43]
	v_mfma_f32_16x16x32_bf16 v[32:35], v[164:167], v[194:197], v[32:35]
	v_mfma_f32_16x16x32_bf16 v[24:27], v[172:175], v[194:197], v[24:27]
	v_mfma_f32_16x16x32_bf16 v[16:19], v[164:167], v[202:205], v[16:19]
	v_mfma_f32_16x16x32_bf16 v[8:11], v[172:175], v[202:205], v[8:11]
	v_mfma_f32_16x16x32_bf16 v[4:7], v[164:167], v[210:213], v[4:7]
	v_mfma_f32_16x16x32_bf16 v[0:3], v[172:175], v[210:213], v[0:3]
	s_setprio 0
	s_barrier
	s_add_i32 s28, 0, 0x18000
	s_add_i32 s38, 0, 0x1c000
	v_add_u32_e32 v156, s28, v142
	v_add_u32_e32 v172, s38, v142
	ds_read_b128 v[144:147], v156
	ds_read_b128 v[148:151], v156 offset:1024
	ds_read_b128 v[152:155], v156 offset:2048
	ds_read_b128 v[156:159], v156 offset:3072
	ds_read_b128 v[160:163], v172
	ds_read_b128 v[164:167], v172 offset:1024
	ds_read_b128 v[168:171], v172 offset:2048
	ds_read_b128 v[172:175], v172 offset:3072
	s_add_u32 s6, s6, 0x100000
	s_addc_u32 s7, s7, 0
	s_mov_b32 m0, s25
	v_lshl_add_u64 v[220:221], s[6:7], 0, v[132:133]
	ds_read_b128 v[182:185], v143 offset:32768
	ds_read_b128 v[186:189], v143 offset:33792
	ds_read_b128 v[190:193], v143 offset:34816
	ds_read_b128 v[194:197], v143 offset:35840
	ds_read_b128 v[198:201], v143 offset:36864
	ds_read_b128 v[202:205], v143 offset:37888
	ds_read_b128 v[206:209], v143 offset:38912
	ds_read_b128 v[210:213], v143 offset:39936
	global_load_lds_dwordx4 v[220:221], off
	v_lshl_add_u64 v[220:221], s[6:7], 0, v[130:131]
	s_mov_b32 m0, s30
	s_nop 0
	global_load_lds_dwordx4 v[220:221], off
	s_waitcnt vmcnt(8)
	s_waitcnt lgkmcnt(0)
	s_barrier
	s_setprio 1
	s_waitcnt lgkmcnt(0)
	v_mfma_f32_16x16x32_bf16 v[124:127], v[144:147], v[182:185], v[124:127]
	v_mfma_f32_16x16x32_bf16 v[120:123], v[152:155], v[182:185], v[120:123]
	v_mfma_f32_16x16x32_bf16 v[116:119], v[144:147], v[190:193], v[116:119]
	v_mfma_f32_16x16x32_bf16 v[108:111], v[152:155], v[190:193], v[108:111]
	v_mfma_f32_16x16x32_bf16 v[100:103], v[144:147], v[198:201], v[100:103]
	v_mfma_f32_16x16x32_bf16 v[92:95], v[152:155], v[198:201], v[92:95]
	v_mfma_f32_16x16x32_bf16 v[84:87], v[144:147], v[206:209], v[84:87]
	v_mfma_f32_16x16x32_bf16 v[76:79], v[152:155], v[206:209], v[76:79]
	v_mfma_f32_16x16x32_bf16 v[124:127], v[148:151], v[186:189], v[124:127]
	v_mfma_f32_16x16x32_bf16 v[120:123], v[156:159], v[186:189], v[120:123]
	v_mfma_f32_16x16x32_bf16 v[116:119], v[148:151], v[194:197], v[116:119]
	v_mfma_f32_16x16x32_bf16 v[108:111], v[156:159], v[194:197], v[108:111]
	v_mfma_f32_16x16x32_bf16 v[100:103], v[148:151], v[202:205], v[100:103]
	v_mfma_f32_16x16x32_bf16 v[92:95], v[156:159], v[202:205], v[92:95]
	v_mfma_f32_16x16x32_bf16 v[84:87], v[148:151], v[210:213], v[84:87]
	v_mfma_f32_16x16x32_bf16 v[76:79], v[156:159], v[210:213], v[76:79]
	s_setprio 0
	s_setprio 1
	v_mfma_f32_16x16x32_bf16 v[112:115], v[160:163], v[182:185], v[112:115]
	v_mfma_f32_16x16x32_bf16 v[104:107], v[168:171], v[182:185], v[104:107]
	v_mfma_f32_16x16x32_bf16 v[96:99], v[160:163], v[190:193], v[96:99]
	v_mfma_f32_16x16x32_bf16 v[88:91], v[168:171], v[190:193], v[88:91]
	v_mfma_f32_16x16x32_bf16 v[80:83], v[160:163], v[198:201], v[80:83]
	v_mfma_f32_16x16x32_bf16 v[72:75], v[168:171], v[198:201], v[72:75]
	v_mfma_f32_16x16x32_bf16 v[68:71], v[160:163], v[206:209], v[68:71]
	v_mfma_f32_16x16x32_bf16 v[64:67], v[168:171], v[206:209], v[64:67]
	v_mfma_f32_16x16x32_bf16 v[112:115], v[164:167], v[186:189], v[112:115]
	v_mfma_f32_16x16x32_bf16 v[104:107], v[172:175], v[186:189], v[104:107]
	v_mfma_f32_16x16x32_bf16 v[96:99], v[164:167], v[194:197], v[96:99]
	v_mfma_f32_16x16x32_bf16 v[88:91], v[172:175], v[194:197], v[88:91]
	v_mfma_f32_16x16x32_bf16 v[80:83], v[164:167], v[202:205], v[80:83]
	v_mfma_f32_16x16x32_bf16 v[72:75], v[172:175], v[202:205], v[72:75]
	v_mfma_f32_16x16x32_bf16 v[68:71], v[164:167], v[210:213], v[68:71]
	v_mfma_f32_16x16x32_bf16 v[64:67], v[172:175], v[210:213], v[64:67]
	s_setprio 0
	s_barrier
; #define PG8_STAGE(bufoff, gbase, voff) do { _Pragma("unroll") for (int _i = 0; _i < 2; ++_i) \
;         __builtin_amdgcn_global_load_lds((const unsigned*)((const char*)(gbase) + (voff)[_i]), (PG8_LAS unsigned*)(lds + (bufoff) + ldsw + _i * 8192), 16, 0, 0); } while (0)
; #define PG8_LDA(dst, b, h) do { _Pragma("unroll") for (int m = 0; m < 4; ++m) _Pragma("unroll") for (int k = 0; k < 2; ++k) dst[m][k] = *(const PG8_LAS bf16x8*)(lds + PG8_SA(b, h) + aoff + m * 2048 + k * 1024); } while (0)
; #define PG8_MMA(ai, bj, At, Bt) do { __builtin_amdgcn_s_setprio(1); _Pragma("unroll") for (int m = 0; m < 4; ++m) _Pragma("unroll") for (int n = 0; n < 2; ++n) _Pragma("unroll") for (int k = 0; k < 2; ++k) \
;         acc[ai][bj][m][n] = __builtin_amdgcn_mfma_f32_16x16x32_bf16(Bt[n][k], At[m][k], acc[ai][bj][m][n], 0, 0, 0); __builtin_amdgcn_s_setprio(0); } while (0)
; #define PG8_WAIT_V(n) asm volatile("s_waitcnt vmcnt(" #n ")" ::: "memory")
; #define PG8_WAIT_L(n) asm volatile("s_waitcnt lgkmcnt(" #n ")" ::: "memory")
; #define PG8_BAR __builtin_amdgcn_s_barrier()
; #define PG8_SCHED __builtin_amdgcn_sched_barrier(0)
; template <class Epi, class Sched, bool ALIGN_EPI = false, bool SP2 = false>
; __device__ __forceinline__ void gemm_phase(PG8_LAS unsigned char* lds, const Gemm g, const Sched& S, const Epi& E) {
;     ...
;             PG8_LDA(At, 1, 1); PG8_STAGE(PG8_SB(1, 0), b3, voffB); PG8_STAGE(PG8_SB(1, 1), b3 + hstep, voffB); PG8_STAGE(PG8_SA(1, 0), a3, voffA);
;             PG8_WAIT_V(8); PG8_WAIT_L(0); PG8_BAR; PG8_MMA(1, 0, At, B0); PG8_MMA(1, 1, At, B1); PG8_BAR; PG8_SCHED;
	s_add_i32 s6, s28, s22
	v_lshl_add_u64 v[138:139], v[138:139], 0, s[44:45]
	s_mov_b32 m0, s6
	ds_read_b128 v[182:185], v143 offset:49152
	ds_read_b128 v[186:189], v143 offset:50176
	ds_read_b128 v[190:193], v143 offset:51200
	ds_read_b128 v[194:197], v143 offset:52224
	ds_read_b128 v[198:201], v143 offset:53248
	ds_read_b128 v[202:205], v143 offset:54272
	ds_read_b128 v[206:209], v143 offset:55296
	ds_read_b128 v[210:213], v143 offset:56320
	global_load_lds_dwordx4 v[138:139], off
	s_add_i32 m0, s6, 0x2000
	s_add_u32 s4, s4, 0x100080
	v_lshl_add_u64 v[138:139], v[214:215], 0, s[44:45]
	s_addc_u32 s5, s5, 0
	s_add_i32 s6, s38, s22
	global_load_lds_dwordx4 v[138:139], off
	v_lshl_add_u64 v[138:139], s[4:5], 0, v[176:177]
	s_mov_b32 m0, s6
	s_nop 0
	global_load_lds_dwordx4 v[138:139], off
	v_lshl_add_u64 v[138:139], s[4:5], 0, v[128:129]
	s_add_i32 m0, s6, 0x2000
	s_nop 0
	global_load_lds_dwordx4 v[138:139], off
	v_lshl_add_u64 v[138:139], v[216:217], 0, s[44:45]
	s_mov_b32 m0, s63
	s_nop 0
	global_load_lds_dwordx4 v[138:139], off
	v_lshl_add_u64 v[138:139], v[218:219], 0, s[44:45]
	s_mov_b32 m0, s68
	s_nop 0
	global_load_lds_dwordx4 v[138:139], off
	s_waitcnt vmcnt(8)
	s_waitcnt lgkmcnt(0)
	s_barrier
	s_setprio 1
	s_waitcnt lgkmcnt(0)
	v_mfma_f32_16x16x32_bf16 v[60:63], v[144:147], v[182:185], v[60:63]
	v_mfma_f32_16x16x32_bf16 v[56:59], v[152:155], v[182:185], v[56:59]
	v_mfma_f32_16x16x32_bf16 v[52:55], v[144:147], v[190:193], v[52:55]
	v_mfma_f32_16x16x32_bf16 v[44:47], v[152:155], v[190:193], v[44:47]
	v_mfma_f32_16x16x32_bf16 v[36:39], v[144:147], v[198:201], v[36:39]
	v_mfma_f32_16x16x32_bf16 v[28:31], v[152:155], v[198:201], v[28:31]
	v_mfma_f32_16x16x32_bf16 v[20:23], v[144:147], v[206:209], v[20:23]
	v_mfma_f32_16x16x32_bf16 v[12:15], v[152:155], v[206:209], v[12:15]
	v_mfma_f32_16x16x32_bf16 v[60:63], v[148:151], v[186:189], v[60:63]
	v_mfma_f32_16x16x32_bf16 v[56:59], v[156:159], v[186:189], v[56:59]
	v_mfma_f32_16x16x32_bf16 v[52:55], v[148:151], v[194:197], v[52:55]
	v_mfma_f32_16x16x32_bf16 v[44:47], v[156:159], v[194:197], v[44:47]
	v_mfma_f32_16x16x32_bf16 v[36:39], v[148:151], v[202:205], v[36:39]
	v_mfma_f32_16x16x32_bf16 v[28:31], v[156:159], v[202:205], v[28:31]
	v_mfma_f32_16x16x32_bf16 v[20:23], v[148:151], v[210:213], v[20:23]
	v_mfma_f32_16x16x32_bf16 v[12:15], v[156:159], v[210:213], v[12:15]
	s_setprio 0
	s_setprio 1
	v_mfma_f32_16x16x32_bf16 v[48:51], v[160:163], v[182:185], v[48:51]
	v_mfma_f32_16x16x32_bf16 v[40:43], v[168:171], v[182:185], v[40:43]
	v_mfma_f32_16x16x32_bf16 v[32:35], v[160:163], v[190:193], v[32:35]
	v_mfma_f32_16x16x32_bf16 v[24:27], v[168:171], v[190:193], v[24:27]
	v_mfma_f32_16x16x32_bf16 v[16:19], v[160:163], v[198:201], v[16:19]
	v_mfma_f32_16x16x32_bf16 v[8:11], v[168:171], v[198:201], v[8:11]
	v_mfma_f32_16x16x32_bf16 v[4:7], v[160:163], v[206:209], v[4:7]
	v_mfma_f32_16x16x32_bf16 v[0:3], v[168:171], v[206:209], v[0:3]
	v_mfma_f32_16x16x32_bf16 v[48:51], v[164:167], v[186:189], v[48:51]
	v_mfma_f32_16x16x32_bf16 v[40:43], v[172:175], v[186:189], v[40:43]
	s_add_i32 s74, s74, 2
	v_mfma_f32_16x16x32_bf16 v[32:35], v[164:167], v[194:197], v[32:35]
	s_add_u32 s64, s64, 0x100
	v_mfma_f32_16x16x32_bf16 v[24:27], v[172:175], v[194:197], v[24:27]
	s_addc_u32 s65, s65, 0
	v_mfma_f32_16x16x32_bf16 v[16:19], v[164:167], v[202:205], v[16:19]
	s_add_u32 s66, s66, 0x100
	v_mfma_f32_16x16x32_bf16 v[8:11], v[172:175], v[202:205], v[8:11]
	s_addc_u32 s67, s67, 0
	v_mfma_f32_16x16x32_bf16 v[4:7], v[164:167], v[210:213], v[4:7]
	s_cmp_gt_u32 s74, 61
	v_mfma_f32_16x16x32_bf16 v[0:3], v[172:175], v[210:213], v[0:3]
	s_setprio 0
	s_barrier
	s_cbranch_scc0 .LBB0_790

; #define PG8_STAGE(bufoff, gbase, voff) do { _Pragma("unroll") for (int _i = 0; _i < 2; ++_i) \
;         __builtin_amdgcn_global_load_lds((const unsigned*)((const char*)(gbase) + (voff)[_i]), (PG8_LAS unsigned*)(lds + (bufoff) + ldsw + _i * 8192), 16, 0, 0); } while (0)
; #define PG8_LDA(dst, b, h) do { _Pragma("unroll") for (int m = 0; m < 4; ++m) _Pragma("unroll") for (int k = 0; k < 2; ++k) dst[m][k] = *(const PG8_LAS bf16x8*)(lds + PG8_SA(b, h) + aoff + m * 2048 + k * 1024); } while (0)
; #define PG8_LDB(dst, b, h) do { _Pragma("unroll") for (int n = 0; n < 2; ++n) _Pragma("unroll") for (int k = 0; k < 2; ++k) dst[n][k] = *(const PG8_LAS bf16x8*)(lds + PG8_SB(b, h) + boff + n * 2048 + k * 1024); } while (0)
; #define PG8_MMA(ai, bj, At, Bt) do { __builtin_amdgcn_s_setprio(1); _Pragma("unroll") for (int m = 0; m < 4; ++m) _Pragma("unroll") for (int n = 0; n < 2; ++n) _Pragma("unroll") for (int k = 0; k < 2; ++k) \
;         acc[ai][bj][m][n] = __builtin_amdgcn_mfma_f32_16x16x32_bf16(Bt[n][k], At[m][k], acc[ai][bj][m][n], 0, 0, 0); __builtin_amdgcn_s_setprio(0); } while (0)
; #define PG8_WAIT_V(n) asm volatile("s_waitcnt vmcnt(" #n ")" ::: "memory")
; #define PG8_WAIT_L(n) asm volatile("s_waitcnt lgkmcnt(" #n ")" ::: "memory")
; #define PG8_BAR __builtin_amdgcn_s_barrier()
; #define PG8_SCHED __builtin_amdgcn_sched_barrier(0)
; template <class Epi, class Sched, bool ALIGN_EPI = false, bool SP2 = false>
; __device__ __forceinline__ void gemm_phase(PG8_LAS unsigned char* lds, const Gemm g, const Sched& S, const Epi& E) {
;     ...
;             const bool last = (t == nt - 2);
;             const char* a1 = cA + (size_t)(t + 1) * kstep;
;             const char* a2 = last ? nA : cA + (size_t)(t + 2) * kstep; const char* b2 = last ? nB : cB + (size_t)(t + 2) * kstep;
;             const char* a3 = a2 + kstep; const char* b3 = b2 + kstep;
;             if (last && has_next) S.a_ready(nxt);
;             if constexpr (SP2) {
;             PG8_LDB(B0, 0, 0); PG8_LDB(B1, 0, 1); PG8_SCHED; PG8_LDA(At, 0, 0); PG8_STAGE(PG8_SA(1, 1), a1 + hstep, voffA);
;             PG8_WAIT_V(8); PG8_WAIT_L(0); PG8_BAR; PG8_MMA(0, 0, At, B0); PG8_MMA(0, 1, At, B1); PG8_BAR; PG8_SCHED;
;             PG8_LDA(At, 0, 1); PG8_STAGE(PG8_SB(0, 0), b2, voffB); PG8_STAGE(PG8_SB(0, 1), b2 + hstep, voffB); PG8_STAGE(PG8_SA(0, 0), a2, voffA);
.Lg4_peel:
	s_add_u32 s4, s64, 0xfff00080
	s_addc_u32 s5, s65, -1
	s_add_i32 s28, 0, 0x10000
	s_cmp_eq_u32 s74, 60
	s_cselect_b32 s7, s35, s5
	s_cselect_b32 s6, s72, s4
	v_add_u32_e32 v138, s28, v142
	s_cselect_b32 s5, s27, s67
	s_cselect_b32 s4, s73, s66
	s_add_i32 s48, 0, 0x14000
	ds_read_b128 v[144:147], v138
	ds_read_b128 v[148:151], v138 offset:1024
	ds_read_b128 v[152:155], v138 offset:2048
	ds_read_b128 v[156:159], v138 offset:3072
	v_add_u32_e32 v138, s48, v142
	ds_read_b128 v[160:163], v138
	ds_read_b128 v[164:167], v138 offset:1024
	ds_read_b128 v[168:171], v138 offset:2048
	ds_read_b128 v[172:175], v138 offset:3072
	v_lshl_add_u64 v[138:139], s[64:65], 0, v[134:135]
	s_add_i32 m0, s23, 0xc000
	ds_read_b128 v[182:185], v143
	ds_read_b128 v[186:189], v143 offset:1024
	ds_read_b128 v[190:193], v143 offset:2048
	ds_read_b128 v[194:197], v143 offset:3072
	ds_read_b128 v[198:201], v143 offset:4096
	ds_read_b128 v[202:205], v143 offset:5120
	ds_read_b128 v[206:209], v143 offset:6144
	ds_read_b128 v[210:213], v143 offset:7168
	global_load_lds_dwordx4 v[138:139], off
	v_lshl_add_u64 v[138:139], s[64:65], 0, v[136:137]
	s_add_i32 m0, s23, 0xe000
	s_nop 0
	global_load_lds_dwordx4 v[138:139], off
	s_waitcnt vmcnt(24)
	s_waitcnt lgkmcnt(0)
	s_barrier
	s_setprio 1
	s_waitcnt lgkmcnt(0)
	v_mfma_f32_16x16x32_bf16 v[124:127], v[144:147], v[182:185], 0
	v_mfma_f32_16x16x32_bf16 v[120:123], v[152:155], v[182:185], 0
	v_mfma_f32_16x16x32_bf16 v[116:119], v[144:147], v[190:193], 0
	v_mfma_f32_16x16x32_bf16 v[108:111], v[152:155], v[190:193], 0
	v_mfma_f32_16x16x32_bf16 v[100:103], v[144:147], v[198:201], 0
	v_mfma_f32_16x16x32_bf16 v[92:95], v[152:155], v[198:201], 0
	v_mfma_f32_16x16x32_bf16 v[84:87], v[144:147], v[206:209], 0
	v_mfma_f32_16x16x32_bf16 v[76:79], v[152:155], v[206:209], 0
	v_mfma_f32_16x16x32_bf16 v[124:127], v[148:151], v[186:189], v[124:127]
	v_mfma_f32_16x16x32_bf16 v[120:123], v[156:159], v[186:189], v[120:123]
	v_mfma_f32_16x16x32_bf16 v[116:119], v[148:151], v[194:197], v[116:119]
	v_mfma_f32_16x16x32_bf16 v[108:111], v[156:159], v[194:197], v[108:111]
	v_mfma_f32_16x16x32_bf16 v[100:103], v[148:151], v[202:205], v[100:103]
	v_mfma_f32_16x16x32_bf16 v[92:95], v[156:159], v[202:205], v[92:95]
	v_mfma_f32_16x16x32_bf16 v[84:87], v[148:151], v[210:213], v[84:87]
	v_mfma_f32_16x16x32_bf16 v[76:79], v[156:159], v[210:213], v[76:79]
	s_setprio 0
	s_setprio 1
	v_mfma_f32_16x16x32_bf16 v[112:115], v[160:163], v[182:185], 0
	v_mfma_f32_16x16x32_bf16 v[104:107], v[168:171], v[182:185], 0
	v_mfma_f32_16x16x32_bf16 v[96:99], v[160:163], v[190:193], 0
	v_mfma_f32_16x16x32_bf16 v[88:91], v[168:171], v[190:193], 0
	v_mfma_f32_16x16x32_bf16 v[80:83], v[160:163], v[198:201], 0
	v_mfma_f32_16x16x32_bf16 v[72:75], v[168:171], v[198:201], 0
	v_mfma_f32_16x16x32_bf16 v[68:71], v[160:163], v[206:209], 0
	v_mfma_f32_16x16x32_bf16 v[64:67], v[168:171], v[206:209], 0
	v_mfma_f32_16x16x32_bf16 v[112:115], v[164:167], v[186:189], v[112:115]
	v_mfma_f32_16x16x32_bf16 v[104:107], v[172:175], v[186:189], v[104:107]
	v_mfma_f32_16x16x32_bf16 v[96:99], v[164:167], v[194:197], v[96:99]
	v_mfma_f32_16x16x32_bf16 v[88:91], v[172:175], v[194:197], v[88:91]
	v_mfma_f32_16x16x32_bf16 v[80:83], v[164:167], v[202:205], v[80:83]
	v_mfma_f32_16x16x32_bf16 v[72:75], v[172:175], v[202:205], v[72:75]
	v_mfma_f32_16x16x32_bf16 v[68:71], v[164:167], v[210:213], v[68:71]
	v_mfma_f32_16x16x32_bf16 v[64:67], v[172:175], v[210:213], v[64:67]
	s_setprio 0
	s_barrier
	s_add_i32 s28, s28, s22
	v_lshl_add_u64 v[138:139], s[4:5], 0, v[176:177]
	s_mov_b32 m0, s28
	ds_read_b128 v[182:185], v143 offset:16384
	ds_read_b128 v[186:189], v143 offset:17408
	ds_read_b128 v[190:193], v143 offset:18432
	ds_read_b128 v[194:197], v143 offset:19456
	ds_read_b128 v[198:201], v143 offset:20480
	ds_read_b128 v[202:205], v143 offset:21504
	ds_read_b128 v[206:209], v143 offset:22528
	ds_read_b128 v[210:213], v143 offset:23552
	global_load_lds_dwordx4 v[138:139], off
	s_add_i32 m0, s28, 0x2000
	s_add_u32 s38, s4, 0x100000
	v_lshl_add_u64 v[214:215], s[4:5], 0, v[128:129]
	s_addc_u32 s39, s5, 0
	s_add_i32 s28, s48, s22
	global_load_lds_dwordx4 v[214:215], off
	v_lshl_add_u64 v[216:217], s[38:39], 0, v[176:177]
	s_mov_b32 m0, s28
	v_lshl_add_u64 v[218:219], s[6:7], 0, v[130:131]
	global_load_lds_dwordx4 v[216:217], off
	v_lshl_add_u64 v[216:217], s[38:39], 0, v[128:129]
	s_add_i32 m0, s28, 0x2000
	s_nop 0
	global_load_lds_dwordx4 v[216:217], off
	v_lshl_add_u64 v[216:217], s[6:7], 0, v[132:133]
	s_mov_b32 m0, s23
	s_nop 0
	global_load_lds_dwordx4 v[216:217], off
	s_mov_b32 m0, s24
	s_nop 0
	global_load_lds_dwordx4 v[218:219], off
	s_waitcnt vmcnt(24)
	s_waitcnt lgkmcnt(0)
	s_barrier
; #define PG8_STAGE(bufoff, gbase, voff) do { _Pragma("unroll") for (int _i = 0; _i < 2; ++_i) \
;         __builtin_amdgcn_global_load_lds((const unsigned*)((const char*)(gbase) + (voff)[_i]), (PG8_LAS unsigned*)(lds + (bufoff) + ldsw + _i * 8192), 16, 0, 0); } while (0)
; #define PG8_LDA(dst, b, h) do { _Pragma("unroll") for (int m = 0; m < 4; ++m) _Pragma("unroll") for (int k = 0; k < 2; ++k) dst[m][k] = *(const PG8_LAS bf16x8*)(lds + PG8_SA(b, h) + aoff + m * 2048 + k * 1024); } while (0)
; #define PG8_LDB(dst, b, h) do { _Pragma("unroll") for (int n = 0; n < 2; ++n) _Pragma("unroll") for (int k = 0; k < 2; ++k) dst[n][k] = *(const PG8_LAS bf16x8*)(lds + PG8_SB(b, h) + boff + n * 2048 + k * 1024); } while (0)
; #define PG8_MMA(ai, bj, At, Bt) do { __builtin_amdgcn_s_setprio(1); _Pragma("unroll") for (int m = 0; m < 4; ++m) _Pragma("unroll") for (int n = 0; n < 2; ++n) _Pragma("unroll") for (int k = 0; k < 2; ++k) \
;         acc[ai][bj][m][n] = __builtin_amdgcn_mfma_f32_16x16x32_bf16(Bt[n][k], At[m][k], acc[ai][bj][m][n], 0, 0, 0); __builtin_amdgcn_s_setprio(0); } while (0)
; #define PG8_WAIT_V(n) asm volatile("s_waitcnt vmcnt(" #n ")" ::: "memory")
; #define PG8_WAIT_L(n) asm volatile("s_waitcnt lgkmcnt(" #n ")" ::: "memory")
; #define PG8_BAR __builtin_amdgcn_s_barrier()
; #define PG8_SCHED __builtin_amdgcn_sched_barrier(0)
; template <class Epi, class Sched, bool ALIGN_EPI = false, bool SP2 = false>
; __device__ __forceinline__ void gemm_phase(PG8_LAS unsigned char* lds, const Gemm g, const Sched& S, const Epi& E) {
;     ...
;             PG8_WAIT_V(8); PG8_WAIT_L(0); PG8_BAR; PG8_MMA(1, 0, At, B0); PG8_MMA(1, 1, At, B1); PG8_BAR; PG8_SCHED;
;             PG8_LDB(B0, 1, 0); PG8_LDB(B1, 1, 1); PG8_SCHED; PG8_LDA(At, 1, 0); PG8_STAGE(PG8_SA(0, 1), a2 + hstep, voffA);
;             PG8_WAIT_V(8); PG8_WAIT_L(0); PG8_BAR; PG8_MMA(0, 0, At, B0); PG8_MMA(0, 1, At, B1); PG8_BAR; PG8_SCHED;
	s_setprio 1
	s_waitcnt lgkmcnt(0)
	v_mfma_f32_16x16x32_bf16 v[60:63], v[144:147], v[182:185], 0
	v_mfma_f32_16x16x32_bf16 v[56:59], v[152:155], v[182:185], 0
	v_mfma_f32_16x16x32_bf16 v[52:55], v[144:147], v[190:193], 0
	v_mfma_f32_16x16x32_bf16 v[44:47], v[152:155], v[190:193], 0
	v_mfma_f32_16x16x32_bf16 v[36:39], v[144:147], v[198:201], 0
	v_mfma_f32_16x16x32_bf16 v[28:31], v[152:155], v[198:201], 0
	v_mfma_f32_16x16x32_bf16 v[20:23], v[144:147], v[206:209], 0
	v_mfma_f32_16x16x32_bf16 v[12:15], v[152:155], v[206:209], 0
	v_mfma_f32_16x16x32_bf16 v[60:63], v[148:151], v[186:189], v[60:63]
	v_mfma_f32_16x16x32_bf16 v[56:59], v[156:159], v[186:189], v[56:59]
	v_mfma_f32_16x16x32_bf16 v[52:55], v[148:151], v[194:197], v[52:55]
	v_mfma_f32_16x16x32_bf16 v[44:47], v[156:159], v[194:197], v[44:47]
	v_mfma_f32_16x16x32_bf16 v[36:39], v[148:151], v[202:205], v[36:39]
	v_mfma_f32_16x16x32_bf16 v[28:31], v[156:159], v[202:205], v[28:31]
	v_mfma_f32_16x16x32_bf16 v[20:23], v[148:151], v[210:213], v[20:23]
	v_mfma_f32_16x16x32_bf16 v[12:15], v[156:159], v[210:213], v[12:15]
	s_setprio 0
	s_setprio 1
	v_mfma_f32_16x16x32_bf16 v[48:51], v[160:163], v[182:185], 0
	v_mfma_f32_16x16x32_bf16 v[40:43], v[168:171], v[182:185], 0
	v_mfma_f32_16x16x32_bf16 v[32:35], v[160:163], v[190:193], 0
	v_mfma_f32_16x16x32_bf16 v[24:27], v[168:171], v[190:193], 0
	v_mfma_f32_16x16x32_bf16 v[16:19], v[160:163], v[198:201], 0
	v_mfma_f32_16x16x32_bf16 v[8:11], v[168:171], v[198:201], 0
	v_mfma_f32_16x16x32_bf16 v[4:7], v[160:163], v[206:209], 0
	v_mfma_f32_16x16x32_bf16 v[0:3], v[168:171], v[206:209], 0
	v_mfma_f32_16x16x32_bf16 v[48:51], v[164:167], v[186:189], v[48:51]
	v_mfma_f32_16x16x32_bf16 v[40:43], v[172:175], v[186:189], v[40:43]
	v_mfma_f32_16x16x32_bf16 v[32:35], v[164:167], v[194:197], v[32:35]
	v_mfma_f32_16x16x32_bf16 v[24:27], v[172:175], v[194:197], v[24:27]
	v_mfma_f32_16x16x32_bf16 v[16:19], v[164:167], v[202:205], v[16:19]
	v_mfma_f32_16x16x32_bf16 v[8:11], v[172:175], v[202:205], v[8:11]
	v_mfma_f32_16x16x32_bf16 v[4:7], v[164:167], v[210:213], v[4:7]
	v_mfma_f32_16x16x32_bf16 v[0:3], v[172:175], v[210:213], v[0:3]
	s_setprio 0
	s_barrier
	s_add_i32 s28, 0, 0x18000
	s_add_i32 s38, 0, 0x1c000
	v_add_u32_e32 v156, s28, v142
	v_add_u32_e32 v172, s38, v142
	ds_read_b128 v[144:147], v156
	ds_read_b128 v[148:151], v156 offset:1024
	ds_read_b128 v[152:155], v156 offset:2048
	ds_read_b128 v[156:159], v156 offset:3072
	ds_read_b128 v[160:163], v172
	ds_read_b128 v[164:167], v172 offset:1024
	ds_read_b128 v[168:171], v172 offset:2048
	ds_read_b128 v[172:175], v172 offset:3072
	s_add_u32 s6, s6, 0x100000
	s_addc_u32 s7, s7, 0
	s_mov_b32 m0, s25
	v_lshl_add_u64 v[220:221], s[6:7], 0, v[132:133]
	ds_read_b128 v[182:185], v143 offset:32768
	ds_read_b128 v[186:189], v143 offset:33792
	ds_read_b128 v[190:193], v143 offset:34816
	ds_read_b128 v[194:197], v143 offset:35840
	ds_read_b128 v[198:201], v143 offset:36864
	ds_read_b128 v[202:205], v143 offset:37888
	ds_read_b128 v[206:209], v143 offset:38912
	ds_read_b128 v[210:213], v143 offset:39936
	global_load_lds_dwordx4 v[220:221], off
	v_lshl_add_u64 v[220:221], s[6:7], 0, v[130:131]
	s_mov_b32 m0, s30
	s_nop 0
	global_load_lds_dwordx4 v[220:221], off
	s_waitcnt vmcnt(8)
	s_waitcnt lgkmcnt(0)
	s_barrier
	s_setprio 1
	s_waitcnt lgkmcnt(0)
	v_mfma_f32_16x16x32_bf16 v[124:127], v[144:147], v[182:185], v[124:127]
	v_mfma_f32_16x16x32_bf16 v[120:123], v[152:155], v[182:185], v[120:123]
	v_mfma_f32_16x16x32_bf16 v[116:119], v[144:147], v[190:193], v[116:119]
	v_mfma_f32_16x16x32_bf16 v[108:111], v[152:155], v[190:193], v[108:111]
	v_mfma_f32_16x16x32_bf16 v[100:103], v[144:147], v[198:201], v[100:103]
	v_mfma_f32_16x16x32_bf16 v[92:95], v[152:155], v[198:201], v[92:95]
	v_mfma_f32_16x16x32_bf16 v[84:87], v[144:147], v[206:209], v[84:87]
	v_mfma_f32_16x16x32_bf16 v[76:79], v[152:155], v[206:209], v[76:79]
	v_mfma_f32_16x16x32_bf16 v[124:127], v[148:151], v[186:189], v[124:127]
	v_mfma_f32_16x16x32_bf16 v[120:123], v[156:159], v[186:189], v[120:123]
	v_mfma_f32_16x16x32_bf16 v[116:119], v[148:151], v[194:197], v[116:119]
	v_mfma_f32_16x16x32_bf16 v[108:111], v[156:159], v[194:197], v[108:111]
	v_mfma_f32_16x16x32_bf16 v[100:103], v[148:151], v[202:205], v[100:103]
	v_mfma_f32_16x16x32_bf16 v[92:95], v[156:159], v[202:205], v[92:95]
	v_mfma_f32_16x16x32_bf16 v[84:87], v[148:151], v[210:213], v[84:87]
	v_mfma_f32_16x16x32_bf16 v[76:79], v[156:159], v[210:213], v[76:79]
	s_setprio 0
	s_setprio 1
	v_mfma_f32_16x16x32_bf16 v[112:115], v[160:163], v[182:185], v[112:115]
	v_mfma_f32_16x16x32_bf16 v[104:107], v[168:171], v[182:185], v[104:107]
	v_mfma_f32_16x16x32_bf16 v[96:99], v[160:163], v[190:193], v[96:99]
	v_mfma_f32_16x16x32_bf16 v[88:91], v[168:171], v[190:193], v[88:91]
	v_mfma_f32_16x16x32_bf16 v[80:83], v[160:163], v[198:201], v[80:83]
	v_mfma_f32_16x16x32_bf16 v[72:75], v[168:171], v[198:201], v[72:75]
	v_mfma_f32_16x16x32_bf16 v[68:71], v[160:163], v[206:209], v[68:71]
	v_mfma_f32_16x16x32_bf16 v[64:67], v[168:171], v[206:209], v[64:67]
	v_mfma_f32_16x16x32_bf16 v[112:115], v[164:167], v[186:189], v[112:115]
	v_mfma_f32_16x16x32_bf16 v[104:107], v[172:175], v[186:189], v[104:107]
	v_mfma_f32_16x16x32_bf16 v[96:99], v[164:167], v[194:197], v[96:99]
	v_mfma_f32_16x16x32_bf16 v[88:91], v[172:175], v[194:197], v[88:91]
	v_mfma_f32_16x16x32_bf16 v[80:83], v[164:167], v[202:205], v[80:83]
	v_mfma_f32_16x16x32_bf16 v[72:75], v[172:175], v[202:205], v[72:75]
	v_mfma_f32_16x16x32_bf16 v[68:71], v[164:167], v[210:213], v[68:71]
	v_mfma_f32_16x16x32_bf16 v[64:67], v[172:175], v[210:213], v[64:67]
	s_setprio 0
	s_barrier
; #define PG8_STAGE(bufoff, gbase, voff) do { _Pragma("unroll") for (int _i = 0; _i < 2; ++_i) \
;         __builtin_amdgcn_global_load_lds((const unsigned*)((const char*)(gbase) + (voff)[_i]), (PG8_LAS unsigned*)(lds + (bufoff) + ldsw + _i * 8192), 16, 0, 0); } while (0)
; #define PG8_LDA(dst, b, h) do { _Pragma("unroll") for (int m = 0; m < 4; ++m) _Pragma("unroll") for (int k = 0; k < 2; ++k) dst[m][k] = *(const PG8_LAS bf16x8*)(lds + PG8_SA(b, h) + aoff + m * 2048 + k * 1024); } while (0)
; #define PG8_MMA(ai, bj, At, Bt) do { __builtin_amdgcn_s_setprio(1); _Pragma("unroll") for (int m = 0; m < 4; ++m) _Pragma("unroll") for (int n = 0; n < 2; ++n) _Pragma("unroll") for (int k = 0; k < 2; ++k) \
;         acc[ai][bj][m][n] = __builtin_amdgcn_mfma_f32_16x16x32_bf16(Bt[n][k], At[m][k], acc[ai][bj][m][n], 0, 0, 0); __builtin_amdgcn_s_setprio(0); } while (0)
; #define PG8_WAIT_V(n) asm volatile("s_waitcnt vmcnt(" #n ")" ::: "memory")
; #define PG8_WAIT_L(n) asm volatile("s_waitcnt lgkmcnt(" #n ")" ::: "memory")
; #define PG8_BAR __builtin_amdgcn_s_barrier()
; #define PG8_SCHED __builtin_amdgcn_sched_barrier(0)
; template <class Epi, class Sched, bool ALIGN_EPI = false, bool SP2 = false>
; __device__ __forceinline__ void gemm_phase(PG8_LAS unsigned char* lds, const Gemm g, const Sched& S, const Epi& E) {
;     ...
;             PG8_LDA(At, 1, 1); PG8_STAGE(PG8_SB(1, 0), b3, voffB); PG8_STAGE(PG8_SB(1, 1), b3 + hstep, voffB); PG8_STAGE(PG8_SA(1, 0), a3, voffA);
;             PG8_WAIT_V(8); PG8_WAIT_L(0); PG8_BAR; PG8_MMA(1, 0, At, B0); PG8_MMA(1, 1, At, B1); PG8_BAR; PG8_SCHED;
	s_add_i32 s6, s28, s22
	v_lshl_add_u64 v[138:139], v[138:139], 0, s[44:45]
	s_mov_b32 m0, s6
	ds_read_b128 v[182:185], v143 offset:49152
	ds_read_b128 v[186:189], v143 offset:50176
	ds_read_b128 v[190:193], v143 offset:51200
	ds_read_b128 v[194:197], v143 offset:52224
	ds_read_b128 v[198:201], v143 offset:53248
	ds_read_b128 v[202:205], v143 offset:54272
	ds_read_b128 v[206:209], v143 offset:55296
	ds_read_b128 v[210:213], v143 offset:56320
	global_load_lds_dwordx4 v[138:139], off
	s_add_i32 m0, s6, 0x2000
	s_add_u32 s4, s4, 0x100080
	v_lshl_add_u64 v[138:139], v[214:215], 0, s[44:45]
	s_addc_u32 s5, s5, 0
	s_add_i32 s6, s38, s22
	global_load_lds_dwordx4 v[138:139], off
	v_lshl_add_u64 v[138:139], s[4:5], 0, v[176:177]
	s_mov_b32 m0, s6
	s_nop 0
	global_load_lds_dwordx4 v[138:139], off
	v_lshl_add_u64 v[138:139], s[4:5], 0, v[128:129]
	s_add_i32 m0, s6, 0x2000
	s_nop 0
	global_load_lds_dwordx4 v[138:139], off
	v_lshl_add_u64 v[138:139], v[216:217], 0, s[44:45]
	s_mov_b32 m0, s63
	s_nop 0
	global_load_lds_dwordx4 v[138:139], off
	v_lshl_add_u64 v[138:139], v[218:219], 0, s[44:45]
	s_mov_b32 m0, s68
	s_nop 0
	global_load_lds_dwordx4 v[138:139], off
	s_waitcnt vmcnt(8)
	s_waitcnt lgkmcnt(0)
	s_barrier
	s_setprio 1
	s_waitcnt lgkmcnt(0)
	v_mfma_f32_16x16x32_bf16 v[60:63], v[144:147], v[182:185], v[60:63]
	v_mfma_f32_16x16x32_bf16 v[56:59], v[152:155], v[182:185], v[56:59]
	v_mfma_f32_16x16x32_bf16 v[52:55], v[144:147], v[190:193], v[52:55]
	v_mfma_f32_16x16x32_bf16 v[44:47], v[152:155], v[190:193], v[44:47]
	v_mfma_f32_16x16x32_bf16 v[36:39], v[144:147], v[198:201], v[36:39]
	v_mfma_f32_16x16x32_bf16 v[28:31], v[152:155], v[198:201], v[28:31]
	v_mfma_f32_16x16x32_bf16 v[20:23], v[144:147], v[206:209], v[20:23]
	v_mfma_f32_16x16x32_bf16 v[12:15], v[152:155], v[206:209], v[12:15]
	v_mfma_f32_16x16x32_bf16 v[60:63], v[148:151], v[186:189], v[60:63]
	v_mfma_f32_16x16x32_bf16 v[56:59], v[156:159], v[186:189], v[56:59]
	v_mfma_f32_16x16x32_bf16 v[52:55], v[148:151], v[194:197], v[52:55]
	v_mfma_f32_16x16x32_bf16 v[44:47], v[156:159], v[194:197], v[44:47]
	v_mfma_f32_16x16x32_bf16 v[36:39], v[148:151], v[202:205], v[36:39]
	v_mfma_f32_16x16x32_bf16 v[28:31], v[156:159], v[202:205], v[28:31]
	v_mfma_f32_16x16x32_bf16 v[20:23], v[148:151], v[210:213], v[20:23]
	v_mfma_f32_16x16x32_bf16 v[12:15], v[156:159], v[210:213], v[12:15]
	s_setprio 0
	s_setprio 1
	v_mfma_f32_16x16x32_bf16 v[48:51], v[160:163], v[182:185], v[48:51]
	v_mfma_f32_16x16x32_bf16 v[40:43], v[168:171], v[182:185], v[40:43]
	v_mfma_f32_16x16x32_bf16 v[32:35], v[160:163], v[190:193], v[32:35]
	v_mfma_f32_16x16x32_bf16 v[24:27], v[168:171], v[190:193], v[24:27]
	v_mfma_f32_16x16x32_bf16 v[16:19], v[160:163], v[198:201], v[16:19]
	v_mfma_f32_16x16x32_bf16 v[8:11], v[168:171], v[198:201], v[8:11]
	v_mfma_f32_16x16x32_bf16 v[4:7], v[160:163], v[206:209], v[4:7]
	v_mfma_f32_16x16x32_bf16 v[0:3], v[168:171], v[206:209], v[0:3]
	v_mfma_f32_16x16x32_bf16 v[48:51], v[164:167], v[186:189], v[48:51]
	v_mfma_f32_16x16x32_bf16 v[40:43], v[172:175], v[186:189], v[40:43]
	s_add_i32 s74, s74, 2
	v_mfma_f32_16x16x32_bf16 v[32:35], v[164:167], v[194:197], v[32:35]
	s_add_u32 s64, s64, 0x100
	v_mfma_f32_16x16x32_bf16 v[24:27], v[172:175], v[194:197], v[24:27]
	s_addc_u32 s65, s65, 0
	v_mfma_f32_16x16x32_bf16 v[16:19], v[164:167], v[202:205], v[16:19]
	s_add_u32 s66, s66, 0x100
	v_mfma_f32_16x16x32_bf16 v[8:11], v[172:175], v[202:205], v[8:11]
	s_addc_u32 s67, s67, 0
	v_mfma_f32_16x16x32_bf16 v[4:7], v[164:167], v[210:213], v[4:7]
	s_cmp_gt_u32 s74, 61
	v_mfma_f32_16x16x32_bf16 v[0:3], v[172:175], v[210:213], v[0:3]
	s_setprio 0
	s_barrier
	s_cbranch_scc0 .LBB0_790
	s_branch .Lg4_post

; #define PG8_STAGE(bufoff, gbase, voff) do { _Pragma("unroll") for (int _i = 0; _i < 2; ++_i) \
;         __builtin_amdgcn_global_load_lds((const unsigned*)((const char*)(gbase) + (voff)[_i]), (PG8_LAS unsigned*)(lds + (bufoff) + ldsw + _i * 8192), 16, 0, 0); } while (0)
; #define PG8_LDA(dst, b, h) do { _Pragma("unroll") for (int m = 0; m < 4; ++m) _Pragma("unroll") for (int k = 0; k < 2; ++k) dst[m][k] = *(const PG8_LAS bf16x8*)(lds + PG8_SA(b, h) + aoff + m * 2048 + k * 1024); } while (0)
; #define PG8_LDB(dst, b, h) do { _Pragma("unroll") for (int n = 0; n < 2; ++n) _Pragma("unroll") for (int k = 0; k < 2; ++k) dst[n][k] = *(const PG8_LAS bf16x8*)(lds + PG8_SB(b, h) + boff + n * 2048 + k * 1024); } while (0)
; #define PG8_MMA(ai, bj, At, Bt) do { __builtin_amdgcn_s_setprio(1); _Pragma("unroll") for (int m = 0; m < 4; ++m) _Pragma("unroll") for (int n = 0; n < 2; ++n) _Pragma("unroll") for (int k = 0; k < 2; ++k) \
;         acc[ai][bj][m][n] = __builtin_amdgcn_mfma_f32_16x16x32_bf16(Bt[n][k], At[m][k], acc[ai][bj][m][n], 0, 0, 0); __builtin_amdgcn_s_setprio(0); } while (0)
; #define PG8_WAIT_V(n) asm volatile("s_waitcnt vmcnt(" #n ")" ::: "memory")
; #define PG8_WAIT_L(n) asm volatile("s_waitcnt lgkmcnt(" #n ")" ::: "memory")
; #define PG8_BAR __builtin_amdgcn_s_barrier()
; #define PG8_SCHED __builtin_amdgcn_sched_barrier(0)
; template <class Epi, class Sched, bool ALIGN_EPI = false, bool SP2 = false>
; __device__ __forceinline__ void gemm_phase(PG8_LAS unsigned char* lds, const Gemm g, const Sched& S, const Epi& E) {
;     ...
;             const bool last = (t == nt - 2);
;             const char* a1 = cA + (size_t)(t + 1) * kstep;
;             const char* a2 = last ? nA : cA + (size_t)(t + 2) * kstep; const char* b2 = last ? nB : cB + (size_t)(t + 2) * kstep;
;             const char* a3 = a2 + kstep; const char* b3 = b2 + kstep;
;             if (last && has_next) S.a_ready(nxt);
;             if constexpr (SP2) {
;             PG8_LDB(B0, 0, 0); PG8_LDB(B1, 0, 1); PG8_SCHED; PG8_LDA(At, 0, 0); PG8_STAGE(PG8_SA(1, 1), a1 + hstep, voffA);
;             PG8_WAIT_V(8); PG8_WAIT_L(0); PG8_BAR; PG8_MMA(0, 0, At, B0); PG8_MMA(0, 1, At, B1); PG8_BAR; PG8_SCHED;
;             PG8_LDA(At, 0, 1); PG8_STAGE(PG8_SB(0, 0), b2, voffB); PG8_STAGE(PG8_SB(0, 1), b2 + hstep, voffB); PG8_STAGE(PG8_SA(0, 0), a2, voffA);
.LBB0_812:
	s_add_i32 s83, s4, 2
	s_add_u32 s28, s64, 0x80
	s_addc_u32 s5, s65, 0
	s_add_i32 s48, 0, 0x10000
	s_cmp_eq_u32 s72, s4
	s_cselect_b32 s5, s37, s5
	s_cselect_b32 s4, s36, s28
	s_cselect_b32 s39, s41, s67
	s_cselect_b32 s38, s40, s66
	s_add_i32 s28, 0, 0x14000
	v_add_u32_e32 v154, s48, v140
	v_add_u32_e32 v170, s28, v140
	ds_read_b128 v[142:145], v154
	ds_read_b128 v[146:149], v154 offset:1024
	ds_read_b128 v[150:153], v154 offset:2048
	ds_read_b128 v[154:157], v154 offset:3072
	ds_read_b128 v[158:161], v170
	ds_read_b128 v[162:165], v170 offset:1024
	ds_read_b128 v[166:169], v170 offset:2048
	ds_read_b128 v[170:173], v170 offset:3072
	v_lshl_add_u64 v[174:175], s[64:65], 0, v[134:135]
	s_add_i32 m0, s25, 0xc000
	ds_read_b128 v[182:185], v141
	ds_read_b128 v[186:189], v141 offset:1024
	ds_read_b128 v[190:193], v141 offset:2048
	ds_read_b128 v[194:197], v141 offset:3072
	ds_read_b128 v[198:201], v141 offset:4096
	ds_read_b128 v[202:205], v141 offset:5120
	ds_read_b128 v[206:209], v141 offset:6144
	ds_read_b128 v[210:213], v141 offset:7168
	global_load_lds_dwordx4 v[174:175], off
	v_lshl_add_u64 v[174:175], s[64:65], 0, v[136:137]
	s_add_i32 m0, s25, 0xe000
	s_nop 0
	global_load_lds_dwordx4 v[174:175], off
	s_waitcnt vmcnt(8)
	s_waitcnt lgkmcnt(0)
	s_barrier
	s_setprio 1
	s_waitcnt lgkmcnt(0)
	v_mfma_f32_16x16x32_bf16 v[124:127], v[142:145], v[182:185], v[124:127]
	v_mfma_f32_16x16x32_bf16 v[120:123], v[150:153], v[182:185], v[120:123]
	v_mfma_f32_16x16x32_bf16 v[108:111], v[142:145], v[190:193], v[108:111]
	v_mfma_f32_16x16x32_bf16 v[104:107], v[150:153], v[190:193], v[104:107]
	v_mfma_f32_16x16x32_bf16 v[92:95], v[142:145], v[198:201], v[92:95]
	v_mfma_f32_16x16x32_bf16 v[88:91], v[150:153], v[198:201], v[88:91]
	v_mfma_f32_16x16x32_bf16 v[76:79], v[142:145], v[206:209], v[76:79]
	v_mfma_f32_16x16x32_bf16 v[72:75], v[150:153], v[206:209], v[72:75]
	v_mfma_f32_16x16x32_bf16 v[124:127], v[146:149], v[186:189], v[124:127]
	v_mfma_f32_16x16x32_bf16 v[120:123], v[154:157], v[186:189], v[120:123]
	v_mfma_f32_16x16x32_bf16 v[108:111], v[146:149], v[194:197], v[108:111]
	v_mfma_f32_16x16x32_bf16 v[104:107], v[154:157], v[194:197], v[104:107]
	v_mfma_f32_16x16x32_bf16 v[92:95], v[146:149], v[202:205], v[92:95]
	v_mfma_f32_16x16x32_bf16 v[88:91], v[154:157], v[202:205], v[88:91]
	v_mfma_f32_16x16x32_bf16 v[76:79], v[146:149], v[210:213], v[76:79]
	v_mfma_f32_16x16x32_bf16 v[72:75], v[154:157], v[210:213], v[72:75]
	s_setprio 0
	s_setprio 1
	v_mfma_f32_16x16x32_bf16 v[116:119], v[158:161], v[182:185], v[116:119]
	v_mfma_f32_16x16x32_bf16 v[112:115], v[166:169], v[182:185], v[112:115]
	v_mfma_f32_16x16x32_bf16 v[100:103], v[158:161], v[190:193], v[100:103]
	v_mfma_f32_16x16x32_bf16 v[96:99], v[166:169], v[190:193], v[96:99]
	v_mfma_f32_16x16x32_bf16 v[84:87], v[158:161], v[198:201], v[84:87]
	v_mfma_f32_16x16x32_bf16 v[80:83], v[166:169], v[198:201], v[80:83]
	v_mfma_f32_16x16x32_bf16 v[68:71], v[158:161], v[206:209], v[68:71]
	v_mfma_f32_16x16x32_bf16 v[64:67], v[166:169], v[206:209], v[64:67]
	v_mfma_f32_16x16x32_bf16 v[116:119], v[162:165], v[186:189], v[116:119]
	v_mfma_f32_16x16x32_bf16 v[112:115], v[170:173], v[186:189], v[112:115]
	v_mfma_f32_16x16x32_bf16 v[100:103], v[162:165], v[194:197], v[100:103]
	v_mfma_f32_16x16x32_bf16 v[96:99], v[170:173], v[194:197], v[96:99]
	v_mfma_f32_16x16x32_bf16 v[84:87], v[162:165], v[202:205], v[84:87]
	v_mfma_f32_16x16x32_bf16 v[80:83], v[170:173], v[202:205], v[80:83]
	v_mfma_f32_16x16x32_bf16 v[68:71], v[162:165], v[210:213], v[68:71]
	v_mfma_f32_16x16x32_bf16 v[64:67], v[170:173], v[210:213], v[64:67]
	s_setprio 0
	s_barrier
	s_add_i32 s48, s48, s24
	v_lshl_add_u64 v[174:175], s[38:39], 0, v[176:177]
	s_mov_b32 m0, s48
	ds_read_b128 v[182:185], v141 offset:16384
	ds_read_b128 v[186:189], v141 offset:17408
	ds_read_b128 v[190:193], v141 offset:18432
	ds_read_b128 v[194:197], v141 offset:19456
	ds_read_b128 v[198:201], v141 offset:20480
	ds_read_b128 v[202:205], v141 offset:21504
	ds_read_b128 v[206:209], v141 offset:22528
	ds_read_b128 v[210:213], v141 offset:23552
	global_load_lds_dwordx4 v[174:175], off
	s_add_i32 m0, s48, 0x2000
	v_lshl_add_u64 v[214:215], s[38:39], 0, v[128:129]
	s_add_u32 s38, s38, s0
	s_addc_u32 s39, s39, s1
	s_add_i32 s28, s28, s24
	global_load_lds_dwordx4 v[214:215], off
	v_lshl_add_u64 v[216:217], s[38:39], 0, v[176:177]
	s_mov_b32 m0, s28
	v_lshl_add_u64 v[218:219], s[38:39], 0, v[128:129]
	global_load_lds_dwordx4 v[216:217], off
	s_add_i32 m0, s28, 0x2000
	v_lshl_add_u64 v[220:221], s[4:5], 0, v[132:133]
	global_load_lds_dwordx4 v[218:219], off
	s_mov_b32 m0, s25
	v_lshl_add_u64 v[222:223], s[4:5], 0, v[130:131]
	global_load_lds_dwordx4 v[220:221], off
	s_mov_b32 m0, s30
	s_nop 0
	global_load_lds_dwordx4 v[222:223], off
	s_waitcnt vmcnt(8)
	s_waitcnt lgkmcnt(0)
	s_barrier
; #define PG8_STAGE(bufoff, gbase, voff) do { _Pragma("unroll") for (int _i = 0; _i < 2; ++_i) \
;         __builtin_amdgcn_global_load_lds((const unsigned*)((const char*)(gbase) + (voff)[_i]), (PG8_LAS unsigned*)(lds + (bufoff) + ldsw + _i * 8192), 16, 0, 0); } while (0)
; #define PG8_LDA(dst, b, h) do { _Pragma("unroll") for (int m = 0; m < 4; ++m) _Pragma("unroll") for (int k = 0; k < 2; ++k) dst[m][k] = *(const PG8_LAS bf16x8*)(lds + PG8_SA(b, h) + aoff + m * 2048 + k * 1024); } while (0)
; #define PG8_LDB(dst, b, h) do { _Pragma("unroll") for (int n = 0; n < 2; ++n) _Pragma("unroll") for (int k = 0; k < 2; ++k) dst[n][k] = *(const PG8_LAS bf16x8*)(lds + PG8_SB(b, h) + boff + n * 2048 + k * 1024); } while (0)
; #define PG8_MMA(ai, bj, At, Bt) do { __builtin_amdgcn_s_setprio(1); _Pragma("unroll") for (int m = 0; m < 4; ++m) _Pragma("unroll") for (int n = 0; n < 2; ++n) _Pragma("unroll") for (int k = 0; k < 2; ++k) \
;         acc[ai][bj][m][n] = __builtin_amdgcn_mfma_f32_16x16x32_bf16(Bt[n][k], At[m][k], acc[ai][bj][m][n], 0, 0, 0); __builtin_amdgcn_s_setprio(0); } while (0)
; #define PG8_WAIT_V(n) asm volatile("s_waitcnt vmcnt(" #n ")" ::: "memory")
; #define PG8_WAIT_L(n) asm volatile("s_waitcnt lgkmcnt(" #n ")" ::: "memory")
; #define PG8_BAR __builtin_amdgcn_s_barrier()
; #define PG8_SCHED __builtin_amdgcn_sched_barrier(0)
; template <class Epi, class Sched, bool ALIGN_EPI = false, bool SP2 = false>
; __device__ __forceinline__ void gemm_phase(PG8_LAS unsigned char* lds, const Gemm g, const Sched& S, const Epi& E) {
;     ...
;             PG8_WAIT_V(8); PG8_WAIT_L(0); PG8_BAR; PG8_MMA(1, 0, At, B0); PG8_MMA(1, 1, At, B1); PG8_BAR; PG8_SCHED;
;             PG8_LDB(B0, 1, 0); PG8_LDB(B1, 1, 1); PG8_SCHED; PG8_LDA(At, 1, 0); PG8_STAGE(PG8_SA(0, 1), a2 + hstep, voffA);
;             PG8_WAIT_V(8); PG8_WAIT_L(0); PG8_BAR; PG8_MMA(0, 0, At, B0); PG8_MMA(0, 1, At, B1); PG8_BAR; PG8_SCHED;
	s_setprio 1
	s_waitcnt lgkmcnt(0)
	v_mfma_f32_16x16x32_bf16 v[60:63], v[142:145], v[182:185], v[60:63]
	v_mfma_f32_16x16x32_bf16 v[56:59], v[150:153], v[182:185], v[56:59]
	v_mfma_f32_16x16x32_bf16 v[44:47], v[142:145], v[190:193], v[44:47]
	v_mfma_f32_16x16x32_bf16 v[40:43], v[150:153], v[190:193], v[40:43]
	v_mfma_f32_16x16x32_bf16 v[28:31], v[142:145], v[198:201], v[28:31]
	v_mfma_f32_16x16x32_bf16 v[24:27], v[150:153], v[198:201], v[24:27]
	v_mfma_f32_16x16x32_bf16 v[12:15], v[142:145], v[206:209], v[12:15]
	v_mfma_f32_16x16x32_bf16 v[8:11], v[150:153], v[206:209], v[8:11]
	v_mfma_f32_16x16x32_bf16 v[60:63], v[146:149], v[186:189], v[60:63]
	v_mfma_f32_16x16x32_bf16 v[56:59], v[154:157], v[186:189], v[56:59]
	v_mfma_f32_16x16x32_bf16 v[44:47], v[146:149], v[194:197], v[44:47]
	v_mfma_f32_16x16x32_bf16 v[40:43], v[154:157], v[194:197], v[40:43]
	v_mfma_f32_16x16x32_bf16 v[28:31], v[146:149], v[202:205], v[28:31]
	v_mfma_f32_16x16x32_bf16 v[24:27], v[154:157], v[202:205], v[24:27]
	v_mfma_f32_16x16x32_bf16 v[12:15], v[146:149], v[210:213], v[12:15]
	v_mfma_f32_16x16x32_bf16 v[8:11], v[154:157], v[210:213], v[8:11]
	s_setprio 0
	s_setprio 1
	v_mfma_f32_16x16x32_bf16 v[52:55], v[158:161], v[182:185], v[52:55]
	v_mfma_f32_16x16x32_bf16 v[48:51], v[166:169], v[182:185], v[48:51]
	v_mfma_f32_16x16x32_bf16 v[36:39], v[158:161], v[190:193], v[36:39]
	v_mfma_f32_16x16x32_bf16 v[32:35], v[166:169], v[190:193], v[32:35]
	v_mfma_f32_16x16x32_bf16 v[20:23], v[158:161], v[198:201], v[20:23]
	v_mfma_f32_16x16x32_bf16 v[16:19], v[166:169], v[198:201], v[16:19]
	v_mfma_f32_16x16x32_bf16 v[4:7], v[158:161], v[206:209], v[4:7]
	v_mfma_f32_16x16x32_bf16 v[0:3], v[166:169], v[206:209], v[0:3]
	v_mfma_f32_16x16x32_bf16 v[52:55], v[162:165], v[186:189], v[52:55]
	v_mfma_f32_16x16x32_bf16 v[48:51], v[170:173], v[186:189], v[48:51]
	v_mfma_f32_16x16x32_bf16 v[36:39], v[162:165], v[194:197], v[36:39]
	v_mfma_f32_16x16x32_bf16 v[32:35], v[170:173], v[194:197], v[32:35]
	v_mfma_f32_16x16x32_bf16 v[20:23], v[162:165], v[202:205], v[20:23]
	v_mfma_f32_16x16x32_bf16 v[16:19], v[170:173], v[202:205], v[16:19]
	v_mfma_f32_16x16x32_bf16 v[4:7], v[162:165], v[210:213], v[4:7]
	v_mfma_f32_16x16x32_bf16 v[0:3], v[170:173], v[210:213], v[0:3]
	s_setprio 0
	s_barrier
	s_add_i32 s28, 0, 0x18000
	s_add_i32 s38, 0, 0x1c000
	v_add_u32_e32 v154, s28, v140
	v_add_u32_e32 v170, s38, v140
	ds_read_b128 v[142:145], v154
	ds_read_b128 v[146:149], v154 offset:1024
	ds_read_b128 v[150:153], v154 offset:2048
	ds_read_b128 v[154:157], v154 offset:3072
	ds_read_b128 v[158:161], v170
	ds_read_b128 v[162:165], v170 offset:1024
	ds_read_b128 v[166:169], v170 offset:2048
	ds_read_b128 v[170:173], v170 offset:3072
	s_add_u32 s4, s4, s0
	s_addc_u32 s5, s5, s1
	s_mov_b32 m0, s31
	v_lshl_add_u64 v[224:225], s[4:5], 0, v[132:133]
	ds_read_b128 v[182:185], v141 offset:32768
	ds_read_b128 v[186:189], v141 offset:33792
	ds_read_b128 v[190:193], v141 offset:34816
	ds_read_b128 v[194:197], v141 offset:35840
	ds_read_b128 v[198:201], v141 offset:36864
	ds_read_b128 v[202:205], v141 offset:37888
	ds_read_b128 v[206:209], v141 offset:38912
	ds_read_b128 v[210:213], v141 offset:39936
	global_load_lds_dwordx4 v[224:225], off
	v_lshl_add_u64 v[224:225], s[4:5], 0, v[130:131]
	s_mov_b32 m0, s46
	s_nop 0
	global_load_lds_dwordx4 v[224:225], off
	s_waitcnt vmcnt(8)
	s_waitcnt lgkmcnt(0)
	s_barrier
	s_setprio 1
	s_waitcnt lgkmcnt(0)
	v_mfma_f32_16x16x32_bf16 v[124:127], v[142:145], v[182:185], v[124:127]
	v_mfma_f32_16x16x32_bf16 v[120:123], v[150:153], v[182:185], v[120:123]
	v_mfma_f32_16x16x32_bf16 v[108:111], v[142:145], v[190:193], v[108:111]
	v_mfma_f32_16x16x32_bf16 v[104:107], v[150:153], v[190:193], v[104:107]
	v_mfma_f32_16x16x32_bf16 v[92:95], v[142:145], v[198:201], v[92:95]
	v_mfma_f32_16x16x32_bf16 v[88:91], v[150:153], v[198:201], v[88:91]
	v_mfma_f32_16x16x32_bf16 v[76:79], v[142:145], v[206:209], v[76:79]
	v_mfma_f32_16x16x32_bf16 v[72:75], v[150:153], v[206:209], v[72:75]
	v_mfma_f32_16x16x32_bf16 v[124:127], v[146:149], v[186:189], v[124:127]
	v_mfma_f32_16x16x32_bf16 v[120:123], v[154:157], v[186:189], v[120:123]
	v_mfma_f32_16x16x32_bf16 v[108:111], v[146:149], v[194:197], v[108:111]
	v_mfma_f32_16x16x32_bf16 v[104:107], v[154:157], v[194:197], v[104:107]
	v_mfma_f32_16x16x32_bf16 v[92:95], v[146:149], v[202:205], v[92:95]
	v_mfma_f32_16x16x32_bf16 v[88:91], v[154:157], v[202:205], v[88:91]
	v_mfma_f32_16x16x32_bf16 v[76:79], v[146:149], v[210:213], v[76:79]
	v_mfma_f32_16x16x32_bf16 v[72:75], v[154:157], v[210:213], v[72:75]
	s_setprio 0
	s_setprio 1
	v_mfma_f32_16x16x32_bf16 v[116:119], v[158:161], v[182:185], v[116:119]
	v_mfma_f32_16x16x32_bf16 v[112:115], v[166:169], v[182:185], v[112:115]
	v_mfma_f32_16x16x32_bf16 v[100:103], v[158:161], v[190:193], v[100:103]
	v_mfma_f32_16x16x32_bf16 v[96:99], v[166:169], v[190:193], v[96:99]
	v_mfma_f32_16x16x32_bf16 v[84:87], v[158:161], v[198:201], v[84:87]
	v_mfma_f32_16x16x32_bf16 v[80:83], v[166:169], v[198:201], v[80:83]
	v_mfma_f32_16x16x32_bf16 v[68:71], v[158:161], v[206:209], v[68:71]
	v_mfma_f32_16x16x32_bf16 v[64:67], v[166:169], v[206:209], v[64:67]
	v_mfma_f32_16x16x32_bf16 v[116:119], v[162:165], v[186:189], v[116:119]
	v_mfma_f32_16x16x32_bf16 v[112:115], v[170:173], v[186:189], v[112:115]
	v_mfma_f32_16x16x32_bf16 v[100:103], v[162:165], v[194:197], v[100:103]
	v_mfma_f32_16x16x32_bf16 v[96:99], v[170:173], v[194:197], v[96:99]
	v_mfma_f32_16x16x32_bf16 v[84:87], v[162:165], v[202:205], v[84:87]
	v_mfma_f32_16x16x32_bf16 v[80:83], v[170:173], v[202:205], v[80:83]
	v_mfma_f32_16x16x32_bf16 v[68:71], v[162:165], v[210:213], v[68:71]
	v_mfma_f32_16x16x32_bf16 v[64:67], v[170:173], v[210:213], v[64:67]
	s_setprio 0
	s_barrier
; #define PG8_STAGE(bufoff, gbase, voff) do { _Pragma("unroll") for (int _i = 0; _i < 2; ++_i) \
;         __builtin_amdgcn_global_load_lds((const unsigned*)((const char*)(gbase) + (voff)[_i]), (PG8_LAS unsigned*)(lds + (bufoff) + ldsw + _i * 8192), 16, 0, 0); } while (0)
; #define PG8_LDA(dst, b, h) do { _Pragma("unroll") for (int m = 0; m < 4; ++m) _Pragma("unroll") for (int k = 0; k < 2; ++k) dst[m][k] = *(const PG8_LAS bf16x8*)(lds + PG8_SA(b, h) + aoff + m * 2048 + k * 1024); } while (0)
; #define PG8_MMA(ai, bj, At, Bt) do { __builtin_amdgcn_s_setprio(1); _Pragma("unroll") for (int m = 0; m < 4; ++m) _Pragma("unroll") for (int n = 0; n < 2; ++n) _Pragma("unroll") for (int k = 0; k < 2; ++k) \
;         acc[ai][bj][m][n] = __builtin_amdgcn_mfma_f32_16x16x32_bf16(Bt[n][k], At[m][k], acc[ai][bj][m][n], 0, 0, 0); __builtin_amdgcn_s_setprio(0); } while (0)
; #define PG8_WAIT_V(n) asm volatile("s_waitcnt vmcnt(" #n ")" ::: "memory")
; #define PG8_WAIT_L(n) asm volatile("s_waitcnt lgkmcnt(" #n ")" ::: "memory")
; #define PG8_BAR __builtin_amdgcn_s_barrier()
; #define PG8_SCHED __builtin_amdgcn_sched_barrier(0)
; template <class Epi, class Sched, bool ALIGN_EPI = false, bool SP2 = false>
; __device__ __forceinline__ void gemm_phase(PG8_LAS unsigned char* lds, const Gemm g, const Sched& S, const Epi& E) {
;     ...
;             PG8_LDA(At, 1, 1); PG8_STAGE(PG8_SB(1, 0), b3, voffB); PG8_STAGE(PG8_SB(1, 1), b3 + hstep, voffB); PG8_STAGE(PG8_SA(1, 0), a3, voffA);
;             PG8_WAIT_V(8); PG8_WAIT_L(0); PG8_BAR; PG8_MMA(1, 0, At, B0); PG8_MMA(1, 1, At, B1); PG8_BAR; PG8_SCHED;
	s_add_i32 s4, s28, s24
	v_lshl_add_u64 v[174:175], v[174:175], 0, s[44:45]
	s_mov_b32 m0, s4
	ds_read_b128 v[182:185], v141 offset:49152
	ds_read_b128 v[186:189], v141 offset:50176
	ds_read_b128 v[190:193], v141 offset:51200
	ds_read_b128 v[194:197], v141 offset:52224
	ds_read_b128 v[198:201], v141 offset:53248
	ds_read_b128 v[202:205], v141 offset:54272
	ds_read_b128 v[206:209], v141 offset:55296
	ds_read_b128 v[210:213], v141 offset:56320
	global_load_lds_dwordx4 v[174:175], off
	v_lshl_add_u64 v[174:175], v[214:215], 0, s[44:45]
	s_add_i32 m0, s4, 0x2000
	s_add_i32 s4, s38, s24
	global_load_lds_dwordx4 v[174:175], off
	v_lshl_add_u64 v[174:175], v[216:217], 0, s[44:45]
	s_mov_b32 m0, s4
	s_nop 0
	global_load_lds_dwordx4 v[174:175], off
	v_lshl_add_u64 v[174:175], v[218:219], 0, s[44:45]
	s_add_i32 m0, s4, 0x2000
	s_nop 0
	global_load_lds_dwordx4 v[174:175], off
	v_lshl_add_u64 v[174:175], v[220:221], 0, s[44:45]
	s_mov_b32 m0, s69
	s_nop 0
	global_load_lds_dwordx4 v[174:175], off
	v_lshl_add_u64 v[174:175], v[222:223], 0, s[44:45]
	s_mov_b32 m0, s70
	s_nop 0
	global_load_lds_dwordx4 v[174:175], off
	s_waitcnt vmcnt(8)
	s_waitcnt lgkmcnt(0)
	s_barrier
	s_setprio 1
	s_waitcnt lgkmcnt(0)
	v_mfma_f32_16x16x32_bf16 v[60:63], v[142:145], v[182:185], v[60:63]
	v_mfma_f32_16x16x32_bf16 v[56:59], v[150:153], v[182:185], v[56:59]
	v_mfma_f32_16x16x32_bf16 v[44:47], v[142:145], v[190:193], v[44:47]
	v_mfma_f32_16x16x32_bf16 v[40:43], v[150:153], v[190:193], v[40:43]
	v_mfma_f32_16x16x32_bf16 v[28:31], v[142:145], v[198:201], v[28:31]
	v_mfma_f32_16x16x32_bf16 v[24:27], v[150:153], v[198:201], v[24:27]
	v_mfma_f32_16x16x32_bf16 v[12:15], v[142:145], v[206:209], v[12:15]
	v_mfma_f32_16x16x32_bf16 v[8:11], v[150:153], v[206:209], v[8:11]
	v_mfma_f32_16x16x32_bf16 v[60:63], v[146:149], v[186:189], v[60:63]
	v_mfma_f32_16x16x32_bf16 v[56:59], v[154:157], v[186:189], v[56:59]
	v_mfma_f32_16x16x32_bf16 v[44:47], v[146:149], v[194:197], v[44:47]
	v_mfma_f32_16x16x32_bf16 v[40:43], v[154:157], v[194:197], v[40:43]
	v_mfma_f32_16x16x32_bf16 v[28:31], v[146:149], v[202:205], v[28:31]
	v_mfma_f32_16x16x32_bf16 v[24:27], v[154:157], v[202:205], v[24:27]
	v_mfma_f32_16x16x32_bf16 v[12:15], v[146:149], v[210:213], v[12:15]
	v_mfma_f32_16x16x32_bf16 v[8:11], v[154:157], v[210:213], v[8:11]
	s_setprio 0
	s_setprio 1
	v_mfma_f32_16x16x32_bf16 v[52:55], v[158:161], v[182:185], v[52:55]
	v_mfma_f32_16x16x32_bf16 v[48:51], v[166:169], v[182:185], v[48:51]
	v_mfma_f32_16x16x32_bf16 v[36:39], v[158:161], v[190:193], v[36:39]
	v_mfma_f32_16x16x32_bf16 v[32:35], v[166:169], v[190:193], v[32:35]
	v_mfma_f32_16x16x32_bf16 v[20:23], v[158:161], v[198:201], v[20:23]
	v_mfma_f32_16x16x32_bf16 v[16:19], v[166:169], v[198:201], v[16:19]
	v_mfma_f32_16x16x32_bf16 v[4:7], v[158:161], v[206:209], v[4:7]
	v_mfma_f32_16x16x32_bf16 v[0:3], v[166:169], v[206:209], v[0:3]
	v_mfma_f32_16x16x32_bf16 v[52:55], v[162:165], v[186:189], v[52:55]
	v_mfma_f32_16x16x32_bf16 v[48:51], v[170:173], v[186:189], v[48:51]
	s_add_u32 s64, s64, 0x100
	v_mfma_f32_16x16x32_bf16 v[36:39], v[162:165], v[194:197], v[36:39]
	s_addc_u32 s65, s65, 0
	v_mfma_f32_16x16x32_bf16 v[32:35], v[170:173], v[194:197], v[32:35]
	s_add_u32 s66, s66, 0x100
	v_mfma_f32_16x16x32_bf16 v[20:23], v[162:165], v[202:205], v[20:23]
	s_addc_u32 s67, s67, 0
	v_mfma_f32_16x16x32_bf16 v[16:19], v[170:173], v[202:205], v[16:19]
	s_cmp_ge_i32 s83, s63
	v_mfma_f32_16x16x32_bf16 v[4:7], v[162:165], v[210:213], v[4:7]
	s_mov_b32 s4, s83
	v_mfma_f32_16x16x32_bf16 v[0:3], v[170:173], v[210:213], v[0:3]
	s_setprio 0
	s_barrier
	s_cbranch_scc0 .LBB0_812

; #define LAS __attribute__((address_space(3)))
; __global__ void __launch_bounds__(512, 2) fwd_megakernel(Args a) {
;     extern __shared__ __attribute__((aligned(16))) unsigned char lds_raw[];
;     LAS unsigned char* lds = (LAS unsigned char*)lds_raw;
;     cg::grid_group grid = cg::this_grid();
;     ...
;     const int tid = threadIdx.x, lane = tid & 63, wave = __builtin_amdgcn_readfirstlane(tid >> 6);
	.amdhsa_kernel _Z14fwd_megakernel4Args
		.amdhsa_group_segment_fixed_size 0
		.amdhsa_private_segment_fixed_size 0
		.amdhsa_kernarg_size 424
		.amdhsa_user_sgpr_count 2
		.amdhsa_user_sgpr_dispatch_ptr 0
		.amdhsa_user_sgpr_queue_ptr 0
		.amdhsa_user_sgpr_kernarg_segment_ptr 1
		.amdhsa_user_sgpr_dispatch_id 0
		.amdhsa_user_sgpr_kernarg_preload_length 0
		.amdhsa_user_sgpr_kernarg_preload_offset 0
		.amdhsa_user_sgpr_private_segment_size 0
		.amdhsa_uses_dynamic_stack 0
		.amdhsa_enable_private_segment 0
		.amdhsa_system_sgpr_workgroup_id_x 1
		.amdhsa_system_sgpr_workgroup_id_y 0
		.amdhsa_system_sgpr_workgroup_id_z 0
		.amdhsa_system_sgpr_workgroup_info 0
		.amdhsa_system_vgpr_workitem_id 2
		.amdhsa_next_free_vgpr 256
		.amdhsa_next_free_sgpr 101
		.amdhsa_accum_offset 256
		.amdhsa_reserve_vcc 1
		.amdhsa_float_round_mode_32 0
		.amdhsa_float_round_mode_16_64 0
		.amdhsa_float_denorm_mode_32 3
		.amdhsa_float_denorm_mode_16_64 3
		.amdhsa_dx10_clamp 1
		.amdhsa_ieee_mode 1
		.amdhsa_fp16_overflow 0
		.amdhsa_tg_split 0
		.amdhsa_exception_fp_ieee_invalid_op 0
		.amdhsa_exception_fp_denorm_src 0
		.amdhsa_exception_fp_ieee_div_zero 0
		.amdhsa_exception_fp_ieee_overflow 0
		.amdhsa_exception_fp_ieee_underflow 0
		.amdhsa_exception_fp_ieee_inexact 0
		.amdhsa_exception_int_div_zero 0
	.end_amdhsa_kernel

; #define LAS __attribute__((address_space(3)))
; __global__ void __launch_bounds__(512, 2) fwd_megakernel(Args a) {
;     extern __shared__ __attribute__((aligned(16))) unsigned char lds_raw[];
;     LAS unsigned char* lds = (LAS unsigned char*)lds_raw;
;     cg::grid_group grid = cg::this_grid();
;     ...
;     const int tid = threadIdx.x, lane = tid & 63, wave = __builtin_amdgcn_readfirstlane(tid >> 6);
amdhsa.kernels:
  - .agpr_count:     0
    .args:
      - .offset:         0
        .size:           168
        .value_kind:     by_value
      - .offset:         168
        .size:           4
        .value_kind:     hidden_block_count_x
      - .offset:         172
        .size:           4
        .value_kind:     hidden_block_count_y
      - .offset:         176
        .size:           4
        .value_kind:     hidden_block_count_z
      - .offset:         180
        .size:           2
        .value_kind:     hidden_group_size_x
      - .offset:         182
        .size:           2
        .value_kind:     hidden_group_size_y
      - .offset:         184
        .size:           2
        .value_kind:     hidden_group_size_z
      - .offset:         186
        .size:           2
        .value_kind:     hidden_remainder_x
      - .offset:         188
        .size:           2
        .value_kind:     hidden_remainder_y
      - .offset:         190
        .size:           2
        .value_kind:     hidden_remainder_z
      - .offset:         208
        .size:           8
        .value_kind:     hidden_global_offset_x
      - .offset:         216
        .size:           8
        .value_kind:     hidden_global_offset_y
      - .offset:         224
        .size:           8
        .value_kind:     hidden_global_offset_z
      - .offset:         232
        .size:           2
        .value_kind:     hidden_grid_dims
      - .offset:         256
        .size:           8
        .value_kind:     hidden_multigrid_sync_arg
      - .offset:         288
        .size:           4
        .value_kind:     hidden_dynamic_lds_size
    .group_segment_fixed_size: 0
    .kernarg_segment_align: 8
    .kernarg_segment_size: 424
    .language:       OpenCL C
    .language_version:
      - 2
      - 0
    .max_flat_workgroup_size: 512
    .name:           _Z14fwd_megakernel4Args
    .private_segment_fixed_size: 0
    .sgpr_count:     107
    .sgpr_spill_count: 205
    .symbol:         _Z14fwd_megakernel4Args.kd
    .uniform_work_group_size: 1
    .uses_dynamic_stack: false
    .vgpr_count:     256
    .vgpr_spill_count: 0
    .wavefront_size: 64
